# GEMM loops of in-proj, FF1, FF2: one s_barrier per superphase (wave halves place it at different points), MFMA prio 2 for waves 4-7, balanced saddr LDS-DMA staging
# speedup vs baseline: 1.0125x; 1.0006x over previous
; #define PG8_STAGE(bufoff, gbase, voff) do { _Pragma("unroll") for (int _i = 0; _i < 2; ++_i) \
;         __builtin_amdgcn_global_load_lds((const unsigned*)((const char*)(gbase) + (voff)[_i]), (PG8_LAS unsigned*)(lds + (bufoff) + ldsw + _i * 8192), 16, 0, 0); } while (0)
; #define PG8_WAIT_V(n) asm volatile("s_waitcnt vmcnt(" #n ")" ::: "memory")
; #define PG8_BAR __builtin_amdgcn_s_barrier()
; template <class Epi, class Sched, bool ALIGN_EPI = false, bool SP2 = false>
; __device__ __forceinline__ void gemm_phase(PG8_LAS unsigned char* lds, const Gemm g, const Sched& S, const Epi& E) {
;     const int tid = threadIdx.x, wid = __builtin_amdgcn_readfirstlane(tid >> 6), lane = tid & 63, wr = wid >> 2, wc = wid & 3, fr = lane & 15, fq = lane >> 4;
;     const int K = g.K, nt = K / BK;
;     unsigned voffA[2], voffB[2];
; #pragma unroll
;     for (int i = 0; i < 2; ++i) { int R, C; stage_rc(tid * 16 + i * 8192, R, C); const int Rb = Epi::PERM ? ((R & ~31) + perm32(R & 31)) : R;
;         voffA[i] = (unsigned)(R * g.ld + C) * 2u; voffB[i] = (unsigned)(Rb * g.ld + C) * 2u; }
;     const size_t kstep = (size_t)(BK * 2);
;     const size_t hstep = (size_t)HALF * g.ld * 2;
;     const size_t tstep = 2 * hstep;
;     const unsigned ldsw = (unsigned)wid * 1024u;
;     const int aoff = lds_byte(wr * 64 + fr, fq * 8), boff = lds_byte(wc * 32 + fr, fq * 8);
;     ...
;     if constexpr (SP2) {
;         PG8_STAGE(PG8_SB(0, 0), cB, voffB); PG8_STAGE(PG8_SB(0, 1), cB + hstep, voffB); PG8_STAGE(PG8_SA(0, 0), cA, voffA); PG8_STAGE(PG8_SA(0, 1), cA + hstep, voffA);
;         if (wr == 1) PG8_BAR;
;         PG8_WAIT_V(2); PG8_BAR;
;         PG8_STAGE(PG8_SB(1, 0), cB + kstep, voffB); PG8_STAGE(PG8_SA(1, 0), cA + kstep, voffA); PG8_STAGE(PG8_SB(1, 1), cB + hstep + kstep, voffB);
;         PG8_WAIT_V(6); PG8_BAR;
.LBB0_338:
	s_lshl_b32 s1, s4, 5
	s_mov_b64 s[16:17], 0x80
	s_and_b32 s1, s1, 0x60
	s_add_i32 m0, s94, 0x18000
	v_lshl_add_u64 v[10:11], v[10:11], 0, s[16:17]
	s_lshl_b32 s0, s6, 13
	s_lshl_b32 s7, s1, 7
	s_ashr_i32 s24, s85, 31
	s_waitcnt vmcnt(2)
	s_barrier
	global_load_lds_dwordx4 v[10:11], off
	v_lshl_add_u64 v[8:9], v[8:9], 0, s[16:17]
	s_add_i32 m0, s94, 0x1a000
	s_add_i32 s25, s94, 0x8000
	s_add_i32 s82, s94, 0xa000
	global_load_lds_dwordx4 v[8:9], off
	v_lshl_add_u64 v[4:5], v[4:5], 0, s[16:17]
	s_mov_b32 m0, s25
	s_add_u32 s4, s90, 0x100080
	global_load_lds_dwordx4 v[4:5], off
	v_lshl_add_u64 v[4:5], v[6:7], 0, s[16:17]
	s_mov_b32 m0, s82
	s_addc_u32 s5, s91, 0
	global_load_lds_dwordx4 v[4:5], off
	s_add_i32 m0, s94, 0x1c000
	v_lshl_add_u64 v[4:5], s[4:5], 0, v[136:137]
	global_load_lds_dwordx4 v[4:5], off
	v_lshl_add_u64 v[4:5], s[4:5], 0, v[140:141]
	s_add_i32 m0, s94, 0x1e000
	v_lshlrev_b32_e32 v7, 2, v1
	global_load_lds_dwordx4 v[4:5], off
	s_add_u32 vcc_lo, s88, 0x100080
	s_addc_u32 vcc_hi, s89, 0
	s_add_i32 m0, s27, 0xc000
	s_nop 0
	global_load_lds_dwordx4 v134, vcc
	s_add_i32 m0, s27, 0xe000
	s_nop 0
	global_load_lds_dwordx4 v138, vcc
	v_lshrrev_b32_e32 v4, 1, v0
	v_and_b32_e32 v4, 24, v4
	v_lshlrev_b32_e32 v5, 1, v4
	v_lshl_or_b32 v6, v1, 6, v5
	v_and_b32_e32 v7, 32, v7
	v_bitop3_b32 v6, v6, s0, v7 bitop3:0xde
	v_lshlrev_b32_e32 v7, 6, v0
	s_movk_i32 s0, 0x3c0
	v_and_or_b32 v5, v7, s0, v5
	v_lshlrev_b32_e32 v7, 2, v0
	v_and_b32_e32 v7, 32, v7
	v_or_b32_e32 v168, s1, v4
	v_lshlrev_b32_e32 v4, 10, v0
	v_bitop3_b32 v167, s7, v5, v7 bitop3:0xf6
	v_and_b32_e32 v4, 0x60000, v4
	v_lshlrev_b32_e32 v5, 13, v13
	v_or3_b32 v4, v3, v4, v5
	s_ashr_i32 s83, s3, 31
	v_add_u32_e32 v142, v4, v12
	v_lshlrev_b32_e32 v4, 6, v14
	s_waitcnt vmcnt(8)
	s_cmpk_lt_u32 s2, 0x100
	v_and_b32_e32 v4, 0xe0000, v4
	s_cselect_b64 s[18:19], -1, 0
	v_or3_b32 v3, v3, v4, v5
	s_add_i32 s26, 0, 0x10000
	s_add_i32 s2, 0, 0x14000
	v_lshl_or_b32 v166, s6, 6, v1
	v_cmp_eq_u32_e64 s[4:5], 0, v1
	v_mov_b32_e32 v143, v2
	v_add_u32_e32 v144, v3, v12
	v_mov_b32_e32 v145, v2
	v_mov_b64_e32 v[146:147], 0x9ff
	v_add_u32_e32 v169, s26, v167
	v_add_u32_e32 v170, s2, v167
	v_add_u32_e32 v171, 0, v6
	s_lshl_b32 s20, s6, 2
	v_mov_b64_e32 v[148:149], 0xa3f
	v_mov_b32_e32 v172, 0x3e0293ee
	s_mov_b32 s46, 0
	s_barrier
	s_waitcnt vmcnt(0)
	s_branch .LBB0_341

; #define PG8_STAGE(bufoff, gbase, voff) do { _Pragma("unroll") for (int _i = 0; _i < 2; ++_i) \
;         __builtin_amdgcn_global_load_lds((const unsigned*)((const char*)(gbase) + (voff)[_i]), (PG8_LAS unsigned*)(lds + (bufoff) + ldsw + _i * 8192), 16, 0, 0); } while (0)
; #define PG8_WAIT_V(n) asm volatile("s_waitcnt vmcnt(" #n ")" ::: "memory")
; #define PG8_BAR __builtin_amdgcn_s_barrier()
; template <class Epi, class Sched, bool ALIGN_EPI = false, bool SP2 = false>
; __device__ __forceinline__ void gemm_phase(PG8_LAS unsigned char* lds, const Gemm g, const Sched& S, const Epi& E) {
;     const int tid = threadIdx.x, wid = __builtin_amdgcn_readfirstlane(tid >> 6), lane = tid & 63, wr = wid >> 2, wc = wid & 3, fr = lane & 15, fq = lane >> 4;
;     const int K = g.K, nt = K / BK;
;     unsigned voffA[2], voffB[2];
; #pragma unroll
;     for (int i = 0; i < 2; ++i) { int R, C; stage_rc(tid * 16 + i * 8192, R, C); const int Rb = Epi::PERM ? ((R & ~31) + perm32(R & 31)) : R;
;         voffA[i] = (unsigned)(R * g.ld + C) * 2u; voffB[i] = (unsigned)(Rb * g.ld + C) * 2u; }
;     const size_t kstep = (size_t)(BK * 2);
;     const size_t hstep = (size_t)HALF * g.ld * 2;
;     const size_t tstep = 2 * hstep;
;     const unsigned ldsw = (unsigned)wid * 1024u;
;     const int aoff = lds_byte(wr * 64 + fr, fq * 8), boff = lds_byte(wc * 32 + fr, fq * 8);
;     ...
;     if constexpr (SP2) {
;         PG8_STAGE(PG8_SB(0, 0), cB, voffB); PG8_STAGE(PG8_SB(0, 1), cB + hstep, voffB); PG8_STAGE(PG8_SA(0, 0), cA, voffA); PG8_STAGE(PG8_SA(0, 1), cA + hstep, voffA);
;         if (wr == 1) PG8_BAR;
;         PG8_WAIT_V(2); PG8_BAR;
;         PG8_STAGE(PG8_SB(1, 0), cB + kstep, voffB); PG8_STAGE(PG8_SA(1, 0), cA + kstep, voffA); PG8_STAGE(PG8_SB(1, 1), cB + hstep + kstep, voffB);
;         PG8_WAIT_V(6); PG8_BAR;
.LBB0_1241:
	s_lshl_b32 s10, s10, 5
	s_and_b32 s16, s10, 0x60
	s_lshl_b32 s10, s13, 8
	s_add_i32 s19, s10, 0
	s_mov_b64 s[10:11], 0x80
	s_add_i32 m0, s23, 0x18000
	v_lshl_add_u64 v[8:9], v[8:9], 0, s[10:11]
	s_lshl_b32 s5, s13, 13
	s_lshl_b32 s17, s16, 7
	s_ashr_i32 s47, s3, 31
	s_waitcnt vmcnt(2)
	s_barrier
	global_load_lds_dwordx4 v[8:9], off
	v_lshl_add_u64 v[6:7], v[6:7], 0, s[10:11]
	s_add_i32 m0, s23, 0x1a000
	s_add_i32 s48, s23, 0x8000
	s_add_i32 s49, s23, 0xa000
	global_load_lds_dwordx4 v[6:7], off
	v_lshl_add_u64 v[2:3], v[2:3], 0, s[10:11]
	s_mov_b32 m0, s48
	s_add_u32 s14, s40, 0x100080
	global_load_lds_dwordx4 v[2:3], off
	v_lshl_add_u64 v[2:3], v[4:5], 0, s[10:11]
	s_mov_b32 m0, s49
	s_addc_u32 s15, s41, 0
	global_load_lds_dwordx4 v[2:3], off
	s_add_i32 m0, s23, 0x1c000
	v_lshl_add_u64 v[2:3], s[14:15], 0, v[148:149]
	global_load_lds_dwordx4 v[2:3], off
	v_lshl_add_u64 v[2:3], s[14:15], 0, v[152:153]
	s_add_i32 m0, s23, 0x1e000
	s_sext_i32_i16 s53, s4
	global_load_lds_dwordx4 v[2:3], off
	s_add_u32 vcc_lo, s36, 0x100080
	s_addc_u32 vcc_hi, s37, 0
	s_add_i32 m0, s24, 0xc000
	s_nop 0
	global_load_lds_dwordx4 v146, vcc
	s_add_i32 m0, s24, 0xe000
	s_nop 0
	global_load_lds_dwordx4 v150, vcc
	v_lshlrev_b32_e32 v2, 1, v14
	v_lshlrev_b32_e32 v1, 6, v0
	s_movk_i32 s4, 0x3c0
	v_and_or_b32 v3, v1, s4, v2
	v_lshlrev_b32_e32 v1, 2, v0
	v_and_b32_e32 v4, 32, v1
	v_bitop3_b32 v166, s17, v3, v4 bitop3:0xf6
	v_lshlrev_b32_e32 v3, 10, v0
	v_and_b32_e32 v3, 0x60000, v3
	v_lshlrev_b32_e32 v4, 13, v12
	v_or3_b32 v3, v10, v3, v4
	v_lshlrev_b32_e32 v5, 2, v195
	s_cmpk_lt_u32 s12, 0x100
	v_add_u32_e32 v154, v3, v11
	v_lshlrev_b32_e32 v3, 6, v13
	v_lshl_or_b32 v1, s13, 6, v195
	v_lshl_or_b32 v2, v195, 6, v2
	v_and_b32_e32 v6, 32, v5
	s_waitcnt vmcnt(8)
	s_cselect_b64 s[12:13], -1, 0
	s_add_i32 s4, s19, 0x20000
	v_and_b32_e32 v3, 0xe0000, v3
	v_bitop3_b32 v2, v2, s5, v6 bitop3:0xde
	v_or_b32_e32 v167, s16, v14
	v_add_u32_e32 v169, s4, v5
	s_add_i32 s19, s19, 0x20200
	v_or3_b32 v3, v10, v3, v4
	s_add_i32 s50, 0, 0x10000
	s_add_i32 s51, 0, 0x14000
	v_lshl_add_u32 v168, v167, 2, s18
	v_add_u32_e32 v170, 64, v169
	v_add_u32_e32 v171, 0x80, v169
	v_add_u32_e32 v172, 0xc0, v169
	v_add_u32_e32 v173, s19, v5
	v_add_u32_e32 v174, 0x240, v169
	v_add_u32_e32 v175, 0x280, v169
	v_add_u32_e32 v176, 0x2c0, v169
	v_mov_b32_e32 v155, v149
	v_add_u32_e32 v156, v3, v11
	v_mov_b32_e32 v157, v149
	v_mov_b64_e32 v[158:159], 0x1000
	v_mov_b64_e32 v[160:161], 0xfff
	v_add_u32_e32 v177, s50, v166
	v_add_u32_e32 v178, s51, v166
	v_add_u32_e32 v179, 0, v2
	s_mov_b32 s52, 0x8080
	s_barrier
	s_branch .LBB0_1244

;     __device__ __forceinline__ bool next(int i, Unit& u) const { const long L = (long)i * G + c; if (L >= nwg) return false; std_map((int)L, nM, nN, u, wgm); u.ui = i; return true; }
;     __device__ __forceinline__ bool next(int i, Unit& u) const { if (i >= 4) return false; const int x = c & 7, r = c >> 3; u.pm = 16 * i + 4 * (x >> 1) + (r & 3); u.pn = 8 * (x & 1) + (r >> 2); u.ui = i; return true; }
; #define PG8_STAGE(bufoff, gbase, voff) do { _Pragma("unroll") for (int _i = 0; _i < 2; ++_i) \
;         __builtin_amdgcn_global_load_lds((const unsigned*)((const char*)(gbase) + (voff)[_i]), (PG8_LAS unsigned*)(lds + (bufoff) + ldsw + _i * 8192), 16, 0, 0); } while (0)
; #define PG8_WAIT_V(n) asm volatile("s_waitcnt vmcnt(" #n ")" ::: "memory")
; #define PG8_WAIT_L(n) asm volatile("s_waitcnt lgkmcnt(" #n ")" ::: "memory")
; #define PG8_BAR __builtin_amdgcn_s_barrier()
; template <class Epi, class Sched, bool ALIGN_EPI = false, bool SP2 = false>
; __device__ __forceinline__ void gemm_phase(PG8_LAS unsigned char* lds, const Gemm g, const Sched& S, const Epi& E) {
;     ...
;         const bool has_next = S.next(ui + 1, nxt);
;         const char* nA = cA; const char* nB = cB; if (has_next) S.bases(nxt, g, tstep, nA, nB);
;         for (int t = 0; t < nt; t += 2) {
;             const bool last = (t == nt - 2);
;             const char* a1 = cA + (size_t)(t + 1) * kstep;
;             const char* a2 = last ? nA : cA + (size_t)(t + 2) * kstep; const char* b2 = last ? nB : cB + (size_t)(t + 2) * kstep;
;             const char* a3 = a2 + kstep; const char* b3 = b2 + kstep;
;             if (last && has_next) S.a_ready(nxt);
;             if constexpr (Epi::MIDK) { if (t == (nt >> 1)) { E.midk(acc, wr, fr); asm volatile("s_waitcnt lgkmcnt(0)" ::: "memory"); } }
;             if constexpr (SP2) {
;             PG8_LDB(B0, 0, 0); PG8_LDB(B1, 0, 1); PG8_SCHED; PG8_LDA(At, 0, 0); PG8_STAGE(PG8_SA(1, 1), a1 + hstep, voffA);
;             PG8_WAIT_V(8); PG8_WAIT_L(0); PG8_BAR; PG8_MMA(0, 0, At, B0); PG8_MMA(0, 1, At, B1); PG8_BAR; PG8_SCHED;
;     ...
; #pragma unroll
;         for (int a = 0; a < 2; ++a)
; #pragma unroll
;             for (int b = 0; b < 2; ++b)
; #pragma unroll
;                 for (int m = 0; m < 4; ++m)
; #pragma unroll
;                     for (int n = 0; n < 2; ++n) acc[a][b][m][n] = (f32x4){0.f, 0.f, 0.f, 0.f};
;         cur = nxt; cA = nA; cB = nB; ++ui;
.LBB0_1250:
	s_ashr_i32 s17, s16, 31
	s_lshl_b64 s[18:19], s[16:17], 21
	s_add_u32 s18, s34, s18
	s_addc_u32 s19, s35, s19
	s_ashr_i32 s15, s14, 31
	s_lshl_b64 s[20:21], s[14:15], 21
	s_add_u32 s20, s30, s20
	s_addc_u32 s21, s31, s21
	s_and_b64 s[42:43], s[4:5], exec
	s_cselect_b32 s15, s19, s37
	s_cselect_b32 s17, s18, s36
	s_cselect_b32 s54, s21, s41
	s_cselect_b32 s55, s20, s40
	s_add_u32 s36, s36, 0x100080
	s_addc_u32 s37, s37, 0
	s_add_u32 s56, s40, 0x100
	v_mov_b32_e32 v2, 0
	s_addc_u32 s57, s41, 0
	s_mov_b32 s58, -2
	v_mov_b32_e32 v3, v2
	v_mov_b32_e32 v4, v2
	v_mov_b32_e32 v5, v2
	v_mov_b32_e32 v6, v2
	v_mov_b32_e32 v7, v2
	v_mov_b32_e32 v8, v2
	v_mov_b32_e32 v9, v2
	v_mov_b32_e32 v18, v2
	v_mov_b32_e32 v19, v2
	v_mov_b32_e32 v20, v2
	v_mov_b32_e32 v21, v2
	v_mov_b32_e32 v22, v2
	v_mov_b32_e32 v23, v2
	v_mov_b32_e32 v24, v2
	v_mov_b32_e32 v25, v2
	v_mov_b32_e32 v34, v2
	v_mov_b32_e32 v35, v2
	v_mov_b32_e32 v36, v2
	v_mov_b32_e32 v37, v2
	v_mov_b32_e32 v38, v2
	v_mov_b32_e32 v39, v2
	v_mov_b32_e32 v40, v2
	v_mov_b32_e32 v41, v2
	v_mov_b32_e32 v50, v2
	v_mov_b32_e32 v51, v2
	v_mov_b32_e32 v52, v2
	v_mov_b32_e32 v53, v2
	v_mov_b32_e32 v54, v2
	v_mov_b32_e32 v55, v2
	v_mov_b32_e32 v56, v2
	v_mov_b32_e32 v57, v2
	v_mov_b32_e32 v10, v2
	v_mov_b32_e32 v11, v2
	v_mov_b32_e32 v12, v2
	v_mov_b32_e32 v13, v2
	v_mov_b32_e32 v14, v2
	v_mov_b32_e32 v15, v2
	v_mov_b32_e32 v16, v2
	v_mov_b32_e32 v17, v2
	v_mov_b32_e32 v26, v2
	v_mov_b32_e32 v27, v2
	v_mov_b32_e32 v28, v2
	v_mov_b32_e32 v29, v2
	v_mov_b32_e32 v30, v2
	v_mov_b32_e32 v31, v2
	v_mov_b32_e32 v32, v2
	v_mov_b32_e32 v33, v2
	v_mov_b32_e32 v42, v2
	v_mov_b32_e32 v43, v2
	v_mov_b32_e32 v44, v2
	v_mov_b32_e32 v45, v2
	v_mov_b32_e32 v46, v2
	v_mov_b32_e32 v47, v2
	v_mov_b32_e32 v48, v2
	v_mov_b32_e32 v49, v2
	v_mov_b32_e32 v58, v2
	v_mov_b32_e32 v59, v2
	v_mov_b32_e32 v60, v2
	v_mov_b32_e32 v61, v2
	v_mov_b32_e32 v62, v2
	v_mov_b32_e32 v63, v2
	v_mov_b32_e32 v64, v2
	v_mov_b32_e32 v65, v2
	v_mov_b32_e32 v66, v2
	v_mov_b32_e32 v67, v2
	v_mov_b32_e32 v68, v2
	v_mov_b32_e32 v69, v2
	v_mov_b32_e32 v70, v2
	v_mov_b32_e32 v71, v2
	v_mov_b32_e32 v72, v2
	v_mov_b32_e32 v73, v2
	v_mov_b32_e32 v82, v2
	v_mov_b32_e32 v83, v2
	v_mov_b32_e32 v84, v2
	v_mov_b32_e32 v85, v2
	v_mov_b32_e32 v86, v2
	v_mov_b32_e32 v87, v2
	v_mov_b32_e32 v88, v2
	v_mov_b32_e32 v89, v2
	v_mov_b32_e32 v98, v2
	v_mov_b32_e32 v99, v2
	v_mov_b32_e32 v100, v2
	v_mov_b32_e32 v101, v2
	v_mov_b32_e32 v102, v2
	v_mov_b32_e32 v103, v2
	v_mov_b32_e32 v104, v2
	v_mov_b32_e32 v105, v2
	v_mov_b32_e32 v114, v2
	v_mov_b32_e32 v115, v2
	v_mov_b32_e32 v116, v2
	v_mov_b32_e32 v117, v2
	v_mov_b32_e32 v118, v2
	v_mov_b32_e32 v119, v2
	v_mov_b32_e32 v120, v2
	v_mov_b32_e32 v121, v2
	v_mov_b32_e32 v74, v2
	v_mov_b32_e32 v75, v2
	v_mov_b32_e32 v76, v2
	v_mov_b32_e32 v77, v2
	v_mov_b32_e32 v78, v2
	v_mov_b32_e32 v79, v2
	v_mov_b32_e32 v80, v2
	v_mov_b32_e32 v81, v2
	v_mov_b32_e32 v90, v2
	v_mov_b32_e32 v91, v2
	v_mov_b32_e32 v92, v2
	v_mov_b32_e32 v93, v2
	v_mov_b32_e32 v94, v2
	v_mov_b32_e32 v95, v2
	v_mov_b32_e32 v96, v2
	v_mov_b32_e32 v97, v2
	v_mov_b32_e32 v106, v2
	v_mov_b32_e32 v107, v2
	v_mov_b32_e32 v108, v2
	v_mov_b32_e32 v109, v2
	v_mov_b32_e32 v110, v2
	v_mov_b32_e32 v111, v2
	v_mov_b32_e32 v112, v2
	v_mov_b32_e32 v113, v2
	v_mov_b32_e32 v122, v2
	v_mov_b32_e32 v123, v2
	v_mov_b32_e32 v124, v2
	v_mov_b32_e32 v125, v2
	v_mov_b32_e32 v126, v2
	v_mov_b32_e32 v127, v2
	v_mov_b32_e32 v128, v2
	v_mov_b32_e32 v129, v2
	s_cmp_lt_u32 s24, 0x1000
	s_cbranch_scc0 .Lf1_h1
.LBB0_1251:
	ds_read_b128 v[130:133], v177
	ds_read_b128 v[134:137], v177 offset:1024
	ds_read_b128 v[138:141], v177 offset:2048
	ds_read_b128 v[142:145], v177 offset:3072
	ds_read_b128 v[162:165], v178
	ds_read_b128 v[180:183], v178 offset:1024
	ds_read_b128 v[184:187], v178 offset:2048
	ds_read_b128 v[188:191], v178 offset:3072
	s_add_u32 s40, s36, 0xfff00080
	s_addc_u32 s41, s37, -1
	s_cmp_eq_u32 s58, 60
	s_cselect_b32 s43, s15, s41
	s_cselect_b32 s42, s17, s40
	s_cselect_b32 s41, s54, s57
	s_cselect_b32 s40, s55, s56
	ds_read_b128 v[196:199], v179
	ds_read_b128 v[200:203], v179 offset:1024
	ds_read_b128 v[204:207], v179 offset:2048
	ds_read_b128 v[208:211], v179 offset:3072
	ds_read_b128 v[212:215], v179 offset:4096
	ds_read_b128 v[220:223], v179 offset:5120
	ds_read_b128 v[224:227], v179 offset:6144
	ds_read_b128 v[228:231], v179 offset:7168
	s_add_u32 s60, s36, 0xfff00000
	s_addc_u32 s61, s37, -1
	s_add_i32 m0, s24, 0x8000
	s_nop 0
	global_load_lds_dwordx4 v146, s[60:61]
	s_add_i32 m0, s24, 0xa000
	s_nop 0
	global_load_lds_dwordx4 v150, s[60:61]
	s_add_i32 m0, s24, 0xc000
	s_nop 0
	global_load_lds_dwordx4 v146, s[36:37]
	s_add_i32 m0, s24, 0xe000
	s_nop 0
	global_load_lds_dwordx4 v150, s[36:37]
	s_waitcnt lgkmcnt(0)
; #define PG8_STAGE(bufoff, gbase, voff) do { _Pragma("unroll") for (int _i = 0; _i < 2; ++_i) \
;         __builtin_amdgcn_global_load_lds((const unsigned*)((const char*)(gbase) + (voff)[_i]), (PG8_LAS unsigned*)(lds + (bufoff) + ldsw + _i * 8192), 16, 0, 0); } while (0)
; #define PG8_LDA(dst, b, h) do { _Pragma("unroll") for (int m = 0; m < 4; ++m) _Pragma("unroll") for (int k = 0; k < 2; ++k) dst[m][k] = *(const PG8_LAS bf16x8*)(lds + PG8_SA(b, h) + aoff + m * 2048 + k * 1024); } while (0)
; #define PG8_MMA(ai, bj, At, Bt) do { __builtin_amdgcn_s_setprio(1); _Pragma("unroll") for (int m = 0; m < 4; ++m) _Pragma("unroll") for (int n = 0; n < 2; ++n) _Pragma("unroll") for (int k = 0; k < 2; ++k) \
;         acc[ai][bj][m][n] = __builtin_amdgcn_mfma_f32_16x16x32_bf16(Bt[n][k], At[m][k], acc[ai][bj][m][n], 0, 0, 0); __builtin_amdgcn_s_setprio(0); } while (0)
; #define PG8_WAIT_V(n) asm volatile("s_waitcnt vmcnt(" #n ")" ::: "memory")
; #define PG8_WAIT_L(n) asm volatile("s_waitcnt lgkmcnt(" #n ")" ::: "memory")
; #define PG8_BAR __builtin_amdgcn_s_barrier()
; #define PG8_SCHED __builtin_amdgcn_sched_barrier(0)
; template <class Epi, class Sched, bool ALIGN_EPI = false, bool SP2 = false>
; __device__ __forceinline__ void gemm_phase(PG8_LAS unsigned char* lds, const Gemm g, const Sched& S, const Epi& E) {
;     ...
;             PG8_WAIT_V(8); PG8_WAIT_L(0); PG8_BAR; PG8_MMA(0, 0, At, B0); PG8_MMA(0, 1, At, B1); PG8_BAR; PG8_SCHED;
;             PG8_LDA(At, 0, 1); PG8_STAGE(PG8_SB(0, 0), b2, voffB); PG8_STAGE(PG8_SB(0, 1), b2 + hstep, voffB); PG8_STAGE(PG8_SA(0, 0), a2, voffA);
;             PG8_WAIT_V(8); PG8_WAIT_L(0); PG8_BAR; PG8_MMA(1, 0, At, B0); PG8_MMA(1, 1, At, B1); PG8_BAR; PG8_SCHED;
	s_setprio 1
	v_mfma_f32_16x16x32_bf16 v[126:129], v[130:133], v[196:199], v[126:129]
	v_mfma_f32_16x16x32_bf16 v[122:125], v[138:141], v[196:199], v[122:125]
	v_mfma_f32_16x16x32_bf16 v[110:113], v[130:133], v[204:207], v[110:113]
	v_mfma_f32_16x16x32_bf16 v[106:109], v[138:141], v[204:207], v[106:109]
	v_mfma_f32_16x16x32_bf16 v[94:97], v[130:133], v[212:215], v[94:97]
	v_mfma_f32_16x16x32_bf16 v[90:93], v[138:141], v[212:215], v[90:93]
	v_mfma_f32_16x16x32_bf16 v[78:81], v[130:133], v[224:227], v[78:81]
	v_mfma_f32_16x16x32_bf16 v[74:77], v[138:141], v[224:227], v[74:77]
	v_mfma_f32_16x16x32_bf16 v[126:129], v[134:137], v[200:203], v[126:129]
	v_mfma_f32_16x16x32_bf16 v[122:125], v[142:145], v[200:203], v[122:125]
	v_mfma_f32_16x16x32_bf16 v[110:113], v[134:137], v[208:211], v[110:113]
	v_mfma_f32_16x16x32_bf16 v[106:109], v[142:145], v[208:211], v[106:109]
	v_mfma_f32_16x16x32_bf16 v[94:97], v[134:137], v[220:223], v[94:97]
	v_mfma_f32_16x16x32_bf16 v[90:93], v[142:145], v[220:223], v[90:93]
	v_mfma_f32_16x16x32_bf16 v[78:81], v[134:137], v[228:231], v[78:81]
	v_mfma_f32_16x16x32_bf16 v[74:77], v[142:145], v[228:231], v[74:77]
	v_mfma_f32_16x16x32_bf16 v[118:121], v[162:165], v[196:199], v[118:121]
	v_mfma_f32_16x16x32_bf16 v[114:117], v[184:187], v[196:199], v[114:117]
	v_mfma_f32_16x16x32_bf16 v[102:105], v[162:165], v[204:207], v[102:105]
	v_mfma_f32_16x16x32_bf16 v[98:101], v[184:187], v[204:207], v[98:101]
	v_mfma_f32_16x16x32_bf16 v[86:89], v[162:165], v[212:215], v[86:89]
	v_mfma_f32_16x16x32_bf16 v[82:85], v[184:187], v[212:215], v[82:85]
	v_mfma_f32_16x16x32_bf16 v[70:73], v[162:165], v[224:227], v[70:73]
	v_mfma_f32_16x16x32_bf16 v[66:69], v[184:187], v[224:227], v[66:69]
	v_mfma_f32_16x16x32_bf16 v[118:121], v[180:183], v[200:203], v[118:121]
	v_mfma_f32_16x16x32_bf16 v[114:117], v[188:191], v[200:203], v[114:117]
	v_mfma_f32_16x16x32_bf16 v[102:105], v[180:183], v[208:211], v[102:105]
	v_mfma_f32_16x16x32_bf16 v[98:101], v[188:191], v[208:211], v[98:101]
	v_mfma_f32_16x16x32_bf16 v[86:89], v[180:183], v[220:223], v[86:89]
	v_mfma_f32_16x16x32_bf16 v[82:85], v[188:191], v[220:223], v[82:85]
	v_mfma_f32_16x16x32_bf16 v[70:73], v[180:183], v[228:231], v[70:73]
	v_mfma_f32_16x16x32_bf16 v[66:69], v[188:191], v[228:231], v[66:69]
	s_setprio 0
	s_waitcnt vmcnt(8)
	s_barrier
	ds_read_b128 v[196:199], v179 offset:16384
	ds_read_b128 v[200:203], v179 offset:17408
	ds_read_b128 v[204:207], v179 offset:18432
	ds_read_b128 v[208:211], v179 offset:19456
	ds_read_b128 v[212:215], v179 offset:20480
	ds_read_b128 v[220:223], v179 offset:21504
	ds_read_b128 v[224:227], v179 offset:22528
	ds_read_b128 v[228:231], v179 offset:23552
	s_add_u32 vcc_lo, s40, 0x100000
	s_addc_u32 vcc_hi, s41, 0
	s_add_i32 m0, s24, 0x10000
	s_nop 0
	global_load_lds_dwordx4 v148, s[40:41]
	s_add_i32 m0, s24, 0x12000
	s_nop 0
	global_load_lds_dwordx4 v152, s[40:41]
	s_add_i32 m0, s24, 0x14000
	s_nop 0
	global_load_lds_dwordx4 v148, vcc
	s_add_i32 m0, s24, 0x16000
	s_nop 0
	global_load_lds_dwordx4 v152, vcc
	s_waitcnt lgkmcnt(0)
	s_setprio 1
	v_mfma_f32_16x16x32_bf16 v[62:65], v[130:133], v[196:199], v[62:65]
	v_mfma_f32_16x16x32_bf16 v[58:61], v[138:141], v[196:199], v[58:61]
	v_mfma_f32_16x16x32_bf16 v[46:49], v[130:133], v[204:207], v[46:49]
	v_mfma_f32_16x16x32_bf16 v[42:45], v[138:141], v[204:207], v[42:45]
	v_mfma_f32_16x16x32_bf16 v[30:33], v[130:133], v[212:215], v[30:33]
	v_mfma_f32_16x16x32_bf16 v[26:29], v[138:141], v[212:215], v[26:29]
	v_mfma_f32_16x16x32_bf16 v[14:17], v[130:133], v[224:227], v[14:17]
	v_mfma_f32_16x16x32_bf16 v[10:13], v[138:141], v[224:227], v[10:13]
	v_mfma_f32_16x16x32_bf16 v[62:65], v[134:137], v[200:203], v[62:65]
	v_mfma_f32_16x16x32_bf16 v[58:61], v[142:145], v[200:203], v[58:61]
	v_mfma_f32_16x16x32_bf16 v[46:49], v[134:137], v[208:211], v[46:49]
	v_mfma_f32_16x16x32_bf16 v[42:45], v[142:145], v[208:211], v[42:45]
	v_mfma_f32_16x16x32_bf16 v[30:33], v[134:137], v[220:223], v[30:33]
	v_mfma_f32_16x16x32_bf16 v[26:29], v[142:145], v[220:223], v[26:29]
	v_mfma_f32_16x16x32_bf16 v[14:17], v[134:137], v[228:231], v[14:17]
	v_mfma_f32_16x16x32_bf16 v[10:13], v[142:145], v[228:231], v[10:13]
	v_mfma_f32_16x16x32_bf16 v[54:57], v[162:165], v[196:199], v[54:57]
	v_mfma_f32_16x16x32_bf16 v[50:53], v[184:187], v[196:199], v[50:53]
	v_mfma_f32_16x16x32_bf16 v[38:41], v[162:165], v[204:207], v[38:41]
	v_mfma_f32_16x16x32_bf16 v[34:37], v[184:187], v[204:207], v[34:37]
	v_mfma_f32_16x16x32_bf16 v[22:25], v[162:165], v[212:215], v[22:25]
	v_mfma_f32_16x16x32_bf16 v[18:21], v[184:187], v[212:215], v[18:21]
	v_mfma_f32_16x16x32_bf16 v[6:9], v[162:165], v[224:227], v[6:9]
	v_mfma_f32_16x16x32_bf16 v[2:5], v[184:187], v[224:227], v[2:5]
	v_mfma_f32_16x16x32_bf16 v[54:57], v[180:183], v[200:203], v[54:57]
	v_mfma_f32_16x16x32_bf16 v[50:53], v[188:191], v[200:203], v[50:53]
	v_mfma_f32_16x16x32_bf16 v[38:41], v[180:183], v[208:211], v[38:41]
	v_mfma_f32_16x16x32_bf16 v[34:37], v[188:191], v[208:211], v[34:37]
	v_mfma_f32_16x16x32_bf16 v[22:25], v[180:183], v[220:223], v[22:25]
	v_mfma_f32_16x16x32_bf16 v[18:21], v[188:191], v[220:223], v[18:21]
	v_mfma_f32_16x16x32_bf16 v[6:9], v[180:183], v[228:231], v[6:9]
	v_mfma_f32_16x16x32_bf16 v[2:5], v[188:191], v[228:231], v[2:5]
	s_setprio 0
	s_waitcnt vmcnt(6)
	s_barrier
; #define PG8_STAGE(bufoff, gbase, voff) do { _Pragma("unroll") for (int _i = 0; _i < 2; ++_i) \
;         __builtin_amdgcn_global_load_lds((const unsigned*)((const char*)(gbase) + (voff)[_i]), (PG8_LAS unsigned*)(lds + (bufoff) + ldsw + _i * 8192), 16, 0, 0); } while (0)
; #define PG8_LDA(dst, b, h) do { _Pragma("unroll") for (int m = 0; m < 4; ++m) _Pragma("unroll") for (int k = 0; k < 2; ++k) dst[m][k] = *(const PG8_LAS bf16x8*)(lds + PG8_SA(b, h) + aoff + m * 2048 + k * 1024); } while (0)
; #define PG8_LDB(dst, b, h) do { _Pragma("unroll") for (int n = 0; n < 2; ++n) _Pragma("unroll") for (int k = 0; k < 2; ++k) dst[n][k] = *(const PG8_LAS bf16x8*)(lds + PG8_SB(b, h) + boff + n * 2048 + k * 1024); } while (0)
; #define PG8_MMA(ai, bj, At, Bt) do { __builtin_amdgcn_s_setprio(1); _Pragma("unroll") for (int m = 0; m < 4; ++m) _Pragma("unroll") for (int n = 0; n < 2; ++n) _Pragma("unroll") for (int k = 0; k < 2; ++k) \
;         acc[ai][bj][m][n] = __builtin_amdgcn_mfma_f32_16x16x32_bf16(Bt[n][k], At[m][k], acc[ai][bj][m][n], 0, 0, 0); __builtin_amdgcn_s_setprio(0); } while (0)
; #define PG8_WAIT_V(n) asm volatile("s_waitcnt vmcnt(" #n ")" ::: "memory")
; #define PG8_WAIT_L(n) asm volatile("s_waitcnt lgkmcnt(" #n ")" ::: "memory")
; #define PG8_BAR __builtin_amdgcn_s_barrier()
; #define PG8_SCHED __builtin_amdgcn_sched_barrier(0)
; template <class Epi, class Sched, bool ALIGN_EPI = false, bool SP2 = false>
; __device__ __forceinline__ void gemm_phase(PG8_LAS unsigned char* lds, const Gemm g, const Sched& S, const Epi& E) {
;     ...
;             PG8_LDB(B0, 1, 0); PG8_LDB(B1, 1, 1); PG8_SCHED; PG8_LDA(At, 1, 0); PG8_STAGE(PG8_SA(0, 1), a2 + hstep, voffA);
;             PG8_WAIT_V(8); PG8_WAIT_L(0); PG8_BAR; PG8_MMA(0, 0, At, B0); PG8_MMA(0, 1, At, B1); PG8_BAR; PG8_SCHED;
;             PG8_LDA(At, 1, 1); PG8_STAGE(PG8_SB(1, 0), b3, voffB); PG8_STAGE(PG8_SB(1, 1), b3 + hstep, voffB); PG8_STAGE(PG8_SA(1, 0), a3, voffA);
;             PG8_WAIT_V(8); PG8_WAIT_L(0); PG8_BAR; PG8_MMA(1, 0, At, B0); PG8_MMA(1, 1, At, B1); PG8_BAR; PG8_SCHED;
	s_add_i32 s59, 0, 0x18000
	s_add_i32 s60, 0, 0x1c000
	v_add_u32_e32 v142, s59, v166
	v_add_u32_e32 v188, s60, v166
	ds_read_b128 v[130:133], v142
	ds_read_b128 v[134:137], v142 offset:1024
	ds_read_b128 v[138:141], v142 offset:2048
	ds_read_b128 v[142:145], v142 offset:3072
	ds_read_b128 v[162:165], v188
	ds_read_b128 v[180:183], v188 offset:1024
	ds_read_b128 v[184:187], v188 offset:2048
	ds_read_b128 v[188:191], v188 offset:3072
	ds_read_b128 v[196:199], v179 offset:32768
	ds_read_b128 v[200:203], v179 offset:33792
	ds_read_b128 v[204:207], v179 offset:34816
	ds_read_b128 v[208:211], v179 offset:35840
	ds_read_b128 v[212:215], v179 offset:36864
	ds_read_b128 v[220:223], v179 offset:37888
	ds_read_b128 v[224:227], v179 offset:38912
	ds_read_b128 v[228:231], v179 offset:39936
	s_add_u32 vcc_lo, s42, 0x100000
	s_addc_u32 vcc_hi, s43, 0
	s_mov_b32 m0, s24
	s_nop 0
	global_load_lds_dwordx4 v146, s[42:43]
	s_add_i32 m0, s24, 0x2000
	s_nop 0
	global_load_lds_dwordx4 v150, s[42:43]
	s_add_i32 m0, s24, 0x4000
	s_nop 0
	global_load_lds_dwordx4 v146, vcc
	s_add_i32 m0, s24, 0x6000
	s_nop 0
	global_load_lds_dwordx4 v150, vcc
	s_waitcnt lgkmcnt(0)
	s_setprio 1
	v_mfma_f32_16x16x32_bf16 v[126:129], v[130:133], v[196:199], v[126:129]
	v_mfma_f32_16x16x32_bf16 v[122:125], v[138:141], v[196:199], v[122:125]
	v_mfma_f32_16x16x32_bf16 v[110:113], v[130:133], v[204:207], v[110:113]
	v_mfma_f32_16x16x32_bf16 v[106:109], v[138:141], v[204:207], v[106:109]
	v_mfma_f32_16x16x32_bf16 v[94:97], v[130:133], v[212:215], v[94:97]
	v_mfma_f32_16x16x32_bf16 v[90:93], v[138:141], v[212:215], v[90:93]
	v_mfma_f32_16x16x32_bf16 v[78:81], v[130:133], v[224:227], v[78:81]
	v_mfma_f32_16x16x32_bf16 v[74:77], v[138:141], v[224:227], v[74:77]
	v_mfma_f32_16x16x32_bf16 v[126:129], v[134:137], v[200:203], v[126:129]
	v_mfma_f32_16x16x32_bf16 v[122:125], v[142:145], v[200:203], v[122:125]
	v_mfma_f32_16x16x32_bf16 v[110:113], v[134:137], v[208:211], v[110:113]
	v_mfma_f32_16x16x32_bf16 v[106:109], v[142:145], v[208:211], v[106:109]
	v_mfma_f32_16x16x32_bf16 v[94:97], v[134:137], v[220:223], v[94:97]
	v_mfma_f32_16x16x32_bf16 v[90:93], v[142:145], v[220:223], v[90:93]
	v_mfma_f32_16x16x32_bf16 v[78:81], v[134:137], v[228:231], v[78:81]
	v_mfma_f32_16x16x32_bf16 v[74:77], v[142:145], v[228:231], v[74:77]
	v_mfma_f32_16x16x32_bf16 v[118:121], v[162:165], v[196:199], v[118:121]
	v_mfma_f32_16x16x32_bf16 v[114:117], v[184:187], v[196:199], v[114:117]
	v_mfma_f32_16x16x32_bf16 v[102:105], v[162:165], v[204:207], v[102:105]
	v_mfma_f32_16x16x32_bf16 v[98:101], v[184:187], v[204:207], v[98:101]
	v_mfma_f32_16x16x32_bf16 v[86:89], v[162:165], v[212:215], v[86:89]
	v_mfma_f32_16x16x32_bf16 v[82:85], v[184:187], v[212:215], v[82:85]
	v_mfma_f32_16x16x32_bf16 v[70:73], v[162:165], v[224:227], v[70:73]
	v_mfma_f32_16x16x32_bf16 v[66:69], v[184:187], v[224:227], v[66:69]
	v_mfma_f32_16x16x32_bf16 v[118:121], v[180:183], v[200:203], v[118:121]
	v_mfma_f32_16x16x32_bf16 v[114:117], v[188:191], v[200:203], v[114:117]
	v_mfma_f32_16x16x32_bf16 v[102:105], v[180:183], v[208:211], v[102:105]
	v_mfma_f32_16x16x32_bf16 v[98:101], v[188:191], v[208:211], v[98:101]
	v_mfma_f32_16x16x32_bf16 v[86:89], v[180:183], v[220:223], v[86:89]
	v_mfma_f32_16x16x32_bf16 v[82:85], v[188:191], v[220:223], v[82:85]
	v_mfma_f32_16x16x32_bf16 v[70:73], v[180:183], v[228:231], v[70:73]
	v_mfma_f32_16x16x32_bf16 v[66:69], v[188:191], v[228:231], v[66:69]
	s_setprio 0
	s_waitcnt vmcnt(8)
	s_barrier
	ds_read_b128 v[196:199], v179 offset:49152
	ds_read_b128 v[200:203], v179 offset:50176
	ds_read_b128 v[204:207], v179 offset:51200
	ds_read_b128 v[208:211], v179 offset:52224
	ds_read_b128 v[212:215], v179 offset:53248
	ds_read_b128 v[220:223], v179 offset:54272
	ds_read_b128 v[224:227], v179 offset:55296
	ds_read_b128 v[228:231], v179 offset:56320
	s_add_u32 s60, s40, 0x80
	s_addc_u32 s61, s41, 0
	s_add_u32 vcc_lo, s60, 0x100000
	s_addc_u32 vcc_hi, s61, 0
	s_add_i32 m0, s24, 0x18000
	s_nop 0
	global_load_lds_dwordx4 v148, s[60:61]
	s_add_i32 m0, s24, 0x1a000
	s_nop 0
	global_load_lds_dwordx4 v152, s[60:61]
	s_add_i32 m0, s24, 0x1c000
	s_nop 0
	global_load_lds_dwordx4 v148, vcc
	s_add_i32 m0, s24, 0x1e000
	s_nop 0
	global_load_lds_dwordx4 v152, vcc
	s_waitcnt lgkmcnt(0)
	s_setprio 1
	v_mfma_f32_16x16x32_bf16 v[62:65], v[130:133], v[196:199], v[62:65]
	v_mfma_f32_16x16x32_bf16 v[58:61], v[138:141], v[196:199], v[58:61]
	v_mfma_f32_16x16x32_bf16 v[46:49], v[130:133], v[204:207], v[46:49]
	v_mfma_f32_16x16x32_bf16 v[42:45], v[138:141], v[204:207], v[42:45]
	v_mfma_f32_16x16x32_bf16 v[30:33], v[130:133], v[212:215], v[30:33]
	v_mfma_f32_16x16x32_bf16 v[26:29], v[138:141], v[212:215], v[26:29]
	v_mfma_f32_16x16x32_bf16 v[14:17], v[130:133], v[224:227], v[14:17]
	v_mfma_f32_16x16x32_bf16 v[10:13], v[138:141], v[224:227], v[10:13]
	v_mfma_f32_16x16x32_bf16 v[62:65], v[134:137], v[200:203], v[62:65]
	v_mfma_f32_16x16x32_bf16 v[58:61], v[142:145], v[200:203], v[58:61]
	v_mfma_f32_16x16x32_bf16 v[46:49], v[134:137], v[208:211], v[46:49]
	v_mfma_f32_16x16x32_bf16 v[42:45], v[142:145], v[208:211], v[42:45]
	v_mfma_f32_16x16x32_bf16 v[30:33], v[134:137], v[220:223], v[30:33]
	v_mfma_f32_16x16x32_bf16 v[26:29], v[142:145], v[220:223], v[26:29]
	v_mfma_f32_16x16x32_bf16 v[14:17], v[134:137], v[228:231], v[14:17]
	v_mfma_f32_16x16x32_bf16 v[10:13], v[142:145], v[228:231], v[10:13]
	v_mfma_f32_16x16x32_bf16 v[54:57], v[162:165], v[196:199], v[54:57]
	v_mfma_f32_16x16x32_bf16 v[50:53], v[184:187], v[196:199], v[50:53]
	v_mfma_f32_16x16x32_bf16 v[38:41], v[162:165], v[204:207], v[38:41]
	v_mfma_f32_16x16x32_bf16 v[34:37], v[184:187], v[204:207], v[34:37]
	v_mfma_f32_16x16x32_bf16 v[22:25], v[162:165], v[212:215], v[22:25]
	v_mfma_f32_16x16x32_bf16 v[18:21], v[184:187], v[212:215], v[18:21]
	v_mfma_f32_16x16x32_bf16 v[6:9], v[162:165], v[224:227], v[6:9]
	v_mfma_f32_16x16x32_bf16 v[2:5], v[184:187], v[224:227], v[2:5]
	v_mfma_f32_16x16x32_bf16 v[54:57], v[180:183], v[200:203], v[54:57]
	v_mfma_f32_16x16x32_bf16 v[50:53], v[188:191], v[200:203], v[50:53]
	v_mfma_f32_16x16x32_bf16 v[38:41], v[180:183], v[208:211], v[38:41]
	v_mfma_f32_16x16x32_bf16 v[34:37], v[188:191], v[208:211], v[34:37]
	v_mfma_f32_16x16x32_bf16 v[22:25], v[180:183], v[220:223], v[22:25]
	v_mfma_f32_16x16x32_bf16 v[18:21], v[188:191], v[220:223], v[18:21]
	v_mfma_f32_16x16x32_bf16 v[6:9], v[180:183], v[228:231], v[6:9]
	v_mfma_f32_16x16x32_bf16 v[2:5], v[188:191], v[228:231], v[2:5]
	s_setprio 0
	s_waitcnt vmcnt(6)
	s_barrier
	s_add_i32 s58, s58, 2
	s_add_u32 s36, s36, 0x100
	s_addc_u32 s37, s37, 0
	s_add_u32 s56, s56, 0x100
	s_addc_u32 s57, s57, 0
	s_cmp_gt_u32 s58, 61
	s_cbranch_scc0 .LBB0_1251
	s_branch .Lf1_exit
; #define PG8_STAGE(bufoff, gbase, voff) do { _Pragma("unroll") for (int _i = 0; _i < 2; ++_i) \
;         __builtin_amdgcn_global_load_lds((const unsigned*)((const char*)(gbase) + (voff)[_i]), (PG8_LAS unsigned*)(lds + (bufoff) + ldsw + _i * 8192), 16, 0, 0); } while (0)
; #define PG8_LDA(dst, b, h) do { _Pragma("unroll") for (int m = 0; m < 4; ++m) _Pragma("unroll") for (int k = 0; k < 2; ++k) dst[m][k] = *(const PG8_LAS bf16x8*)(lds + PG8_SA(b, h) + aoff + m * 2048 + k * 1024); } while (0)
; #define PG8_LDB(dst, b, h) do { _Pragma("unroll") for (int n = 0; n < 2; ++n) _Pragma("unroll") for (int k = 0; k < 2; ++k) dst[n][k] = *(const PG8_LAS bf16x8*)(lds + PG8_SB(b, h) + boff + n * 2048 + k * 1024); } while (0)
; #define PG8_MMA(ai, bj, At, Bt) do { __builtin_amdgcn_s_setprio(1); _Pragma("unroll") for (int m = 0; m < 4; ++m) _Pragma("unroll") for (int n = 0; n < 2; ++n) _Pragma("unroll") for (int k = 0; k < 2; ++k) \
;         acc[ai][bj][m][n] = __builtin_amdgcn_mfma_f32_16x16x32_bf16(Bt[n][k], At[m][k], acc[ai][bj][m][n], 0, 0, 0); __builtin_amdgcn_s_setprio(0); } while (0)
; #define PG8_WAIT_V(n) asm volatile("s_waitcnt vmcnt(" #n ")" ::: "memory")
; #define PG8_WAIT_L(n) asm volatile("s_waitcnt lgkmcnt(" #n ")" ::: "memory")
; #define PG8_BAR __builtin_amdgcn_s_barrier()
; #define PG8_SCHED __builtin_amdgcn_sched_barrier(0)
; template <class Epi, class Sched, bool ALIGN_EPI = false, bool SP2 = false>
; __device__ __forceinline__ void gemm_phase(PG8_LAS unsigned char* lds, const Gemm g, const Sched& S, const Epi& E) {
;     ...
;             PG8_LDB(B0, 0, 0); PG8_LDB(B1, 0, 1); PG8_SCHED; PG8_LDA(At, 0, 0); PG8_STAGE(PG8_SA(1, 1), a1 + hstep, voffA);
;             PG8_WAIT_V(8); PG8_WAIT_L(0); PG8_BAR; PG8_MMA(0, 0, At, B0); PG8_MMA(0, 1, At, B1); PG8_BAR; PG8_SCHED;
;             PG8_LDA(At, 0, 1); PG8_STAGE(PG8_SB(0, 0), b2, voffB); PG8_STAGE(PG8_SB(0, 1), b2 + hstep, voffB); PG8_STAGE(PG8_SA(0, 0), a2, voffA);
;             PG8_WAIT_V(8); PG8_WAIT_L(0); PG8_BAR; PG8_MMA(1, 0, At, B0); PG8_MMA(1, 1, At, B1); PG8_BAR; PG8_SCHED;
.Lf1_h1:
	ds_read_b128 v[130:133], v177
	ds_read_b128 v[134:137], v177 offset:1024
	ds_read_b128 v[138:141], v177 offset:2048
	ds_read_b128 v[142:145], v177 offset:3072
	ds_read_b128 v[162:165], v178
	ds_read_b128 v[180:183], v178 offset:1024
	ds_read_b128 v[184:187], v178 offset:2048
	ds_read_b128 v[188:191], v178 offset:3072
	s_add_u32 s40, s36, 0xfff00080
	s_addc_u32 s41, s37, -1
	s_cmp_eq_u32 s58, 60
	s_cselect_b32 s43, s15, s41
	s_cselect_b32 s42, s17, s40
	s_cselect_b32 s41, s54, s57
	s_cselect_b32 s40, s55, s56
	ds_read_b128 v[196:199], v179
	ds_read_b128 v[200:203], v179 offset:1024
	ds_read_b128 v[204:207], v179 offset:2048
	ds_read_b128 v[208:211], v179 offset:3072
	ds_read_b128 v[212:215], v179 offset:4096
	ds_read_b128 v[220:223], v179 offset:5120
	ds_read_b128 v[224:227], v179 offset:6144
	ds_read_b128 v[228:231], v179 offset:7168
	s_add_u32 s60, s36, 0xfff00000
	s_addc_u32 s61, s37, -1
	s_add_i32 m0, s24, 0x8000
	s_nop 0
	global_load_lds_dwordx4 v146, s[60:61]
	s_add_i32 m0, s24, 0xa000
	s_nop 0
	global_load_lds_dwordx4 v150, s[60:61]
	s_add_i32 m0, s24, 0xc000
	s_nop 0
	global_load_lds_dwordx4 v146, s[36:37]
	s_add_i32 m0, s24, 0xe000
	s_nop 0
	global_load_lds_dwordx4 v150, s[36:37]
	s_sleep 2
	s_waitcnt lgkmcnt(0)
	s_waitcnt vmcnt(8)
	s_barrier
	s_setprio 2
	v_mfma_f32_16x16x32_bf16 v[126:129], v[130:133], v[196:199], v[126:129]
	v_mfma_f32_16x16x32_bf16 v[122:125], v[138:141], v[196:199], v[122:125]
	v_mfma_f32_16x16x32_bf16 v[110:113], v[130:133], v[204:207], v[110:113]
	v_mfma_f32_16x16x32_bf16 v[106:109], v[138:141], v[204:207], v[106:109]
	v_mfma_f32_16x16x32_bf16 v[94:97], v[130:133], v[212:215], v[94:97]
	v_mfma_f32_16x16x32_bf16 v[90:93], v[138:141], v[212:215], v[90:93]
	v_mfma_f32_16x16x32_bf16 v[78:81], v[130:133], v[224:227], v[78:81]
	v_mfma_f32_16x16x32_bf16 v[74:77], v[138:141], v[224:227], v[74:77]
	v_mfma_f32_16x16x32_bf16 v[126:129], v[134:137], v[200:203], v[126:129]
	v_mfma_f32_16x16x32_bf16 v[122:125], v[142:145], v[200:203], v[122:125]
	v_mfma_f32_16x16x32_bf16 v[110:113], v[134:137], v[208:211], v[110:113]
	v_mfma_f32_16x16x32_bf16 v[106:109], v[142:145], v[208:211], v[106:109]
	v_mfma_f32_16x16x32_bf16 v[94:97], v[134:137], v[220:223], v[94:97]
	v_mfma_f32_16x16x32_bf16 v[90:93], v[142:145], v[220:223], v[90:93]
	v_mfma_f32_16x16x32_bf16 v[78:81], v[134:137], v[228:231], v[78:81]
	v_mfma_f32_16x16x32_bf16 v[74:77], v[142:145], v[228:231], v[74:77]
	v_mfma_f32_16x16x32_bf16 v[118:121], v[162:165], v[196:199], v[118:121]
	v_mfma_f32_16x16x32_bf16 v[114:117], v[184:187], v[196:199], v[114:117]
	v_mfma_f32_16x16x32_bf16 v[102:105], v[162:165], v[204:207], v[102:105]
	v_mfma_f32_16x16x32_bf16 v[98:101], v[184:187], v[204:207], v[98:101]
	v_mfma_f32_16x16x32_bf16 v[86:89], v[162:165], v[212:215], v[86:89]
	v_mfma_f32_16x16x32_bf16 v[82:85], v[184:187], v[212:215], v[82:85]
	v_mfma_f32_16x16x32_bf16 v[70:73], v[162:165], v[224:227], v[70:73]
	v_mfma_f32_16x16x32_bf16 v[66:69], v[184:187], v[224:227], v[66:69]
	v_mfma_f32_16x16x32_bf16 v[118:121], v[180:183], v[200:203], v[118:121]
	v_mfma_f32_16x16x32_bf16 v[114:117], v[188:191], v[200:203], v[114:117]
	v_mfma_f32_16x16x32_bf16 v[102:105], v[180:183], v[208:211], v[102:105]
	v_mfma_f32_16x16x32_bf16 v[98:101], v[188:191], v[208:211], v[98:101]
	v_mfma_f32_16x16x32_bf16 v[86:89], v[180:183], v[220:223], v[86:89]
	v_mfma_f32_16x16x32_bf16 v[82:85], v[188:191], v[220:223], v[82:85]
	v_mfma_f32_16x16x32_bf16 v[70:73], v[180:183], v[228:231], v[70:73]
	v_mfma_f32_16x16x32_bf16 v[66:69], v[188:191], v[228:231], v[66:69]
	s_setprio 0
	ds_read_b128 v[196:199], v179 offset:16384
	ds_read_b128 v[200:203], v179 offset:17408
	ds_read_b128 v[204:207], v179 offset:18432
	ds_read_b128 v[208:211], v179 offset:19456
	ds_read_b128 v[212:215], v179 offset:20480
	ds_read_b128 v[220:223], v179 offset:21504
	ds_read_b128 v[224:227], v179 offset:22528
	ds_read_b128 v[228:231], v179 offset:23552
	s_add_u32 vcc_lo, s40, 0x100000
	s_addc_u32 vcc_hi, s41, 0
	s_add_i32 m0, s24, 0x10000
	s_nop 0
	global_load_lds_dwordx4 v148, s[40:41]
	s_add_i32 m0, s24, 0x12000
	s_nop 0
	global_load_lds_dwordx4 v152, s[40:41]
	s_add_i32 m0, s24, 0x14000
	s_nop 0
	global_load_lds_dwordx4 v148, vcc
	s_add_i32 m0, s24, 0x16000
	s_nop 0
	global_load_lds_dwordx4 v152, vcc
	s_sleep 2
	s_waitcnt lgkmcnt(0)
	s_waitcnt vmcnt(6)
	s_barrier
; #define PG8_STAGE(bufoff, gbase, voff) do { _Pragma("unroll") for (int _i = 0; _i < 2; ++_i) \
;         __builtin_amdgcn_global_load_lds((const unsigned*)((const char*)(gbase) + (voff)[_i]), (PG8_LAS unsigned*)(lds + (bufoff) + ldsw + _i * 8192), 16, 0, 0); } while (0)
; #define PG8_LDA(dst, b, h) do { _Pragma("unroll") for (int m = 0; m < 4; ++m) _Pragma("unroll") for (int k = 0; k < 2; ++k) dst[m][k] = *(const PG8_LAS bf16x8*)(lds + PG8_SA(b, h) + aoff + m * 2048 + k * 1024); } while (0)
; #define PG8_LDB(dst, b, h) do { _Pragma("unroll") for (int n = 0; n < 2; ++n) _Pragma("unroll") for (int k = 0; k < 2; ++k) dst[n][k] = *(const PG8_LAS bf16x8*)(lds + PG8_SB(b, h) + boff + n * 2048 + k * 1024); } while (0)
; #define PG8_MMA(ai, bj, At, Bt) do { __builtin_amdgcn_s_setprio(1); _Pragma("unroll") for (int m = 0; m < 4; ++m) _Pragma("unroll") for (int n = 0; n < 2; ++n) _Pragma("unroll") for (int k = 0; k < 2; ++k) \
;         acc[ai][bj][m][n] = __builtin_amdgcn_mfma_f32_16x16x32_bf16(Bt[n][k], At[m][k], acc[ai][bj][m][n], 0, 0, 0); __builtin_amdgcn_s_setprio(0); } while (0)
; #define PG8_WAIT_V(n) asm volatile("s_waitcnt vmcnt(" #n ")" ::: "memory")
; #define PG8_WAIT_L(n) asm volatile("s_waitcnt lgkmcnt(" #n ")" ::: "memory")
; #define PG8_BAR __builtin_amdgcn_s_barrier()
; #define PG8_SCHED __builtin_amdgcn_sched_barrier(0)
; template <class Epi, class Sched, bool ALIGN_EPI = false, bool SP2 = false>
; __device__ __forceinline__ void gemm_phase(PG8_LAS unsigned char* lds, const Gemm g, const Sched& S, const Epi& E) {
;     ...
;             PG8_WAIT_V(8); PG8_WAIT_L(0); PG8_BAR; PG8_MMA(1, 0, At, B0); PG8_MMA(1, 1, At, B1); PG8_BAR; PG8_SCHED;
;             PG8_LDB(B0, 1, 0); PG8_LDB(B1, 1, 1); PG8_SCHED; PG8_LDA(At, 1, 0); PG8_STAGE(PG8_SA(0, 1), a2 + hstep, voffA);
;             PG8_WAIT_V(8); PG8_WAIT_L(0); PG8_BAR; PG8_MMA(0, 0, At, B0); PG8_MMA(0, 1, At, B1); PG8_BAR; PG8_SCHED;
;             PG8_LDA(At, 1, 1); PG8_STAGE(PG8_SB(1, 0), b3, voffB); PG8_STAGE(PG8_SB(1, 1), b3 + hstep, voffB); PG8_STAGE(PG8_SA(1, 0), a3, voffA);
	s_setprio 2
	v_mfma_f32_16x16x32_bf16 v[62:65], v[130:133], v[196:199], v[62:65]
	v_mfma_f32_16x16x32_bf16 v[58:61], v[138:141], v[196:199], v[58:61]
	v_mfma_f32_16x16x32_bf16 v[46:49], v[130:133], v[204:207], v[46:49]
	v_mfma_f32_16x16x32_bf16 v[42:45], v[138:141], v[204:207], v[42:45]
	v_mfma_f32_16x16x32_bf16 v[30:33], v[130:133], v[212:215], v[30:33]
	v_mfma_f32_16x16x32_bf16 v[26:29], v[138:141], v[212:215], v[26:29]
	v_mfma_f32_16x16x32_bf16 v[14:17], v[130:133], v[224:227], v[14:17]
	v_mfma_f32_16x16x32_bf16 v[10:13], v[138:141], v[224:227], v[10:13]
	v_mfma_f32_16x16x32_bf16 v[62:65], v[134:137], v[200:203], v[62:65]
	v_mfma_f32_16x16x32_bf16 v[58:61], v[142:145], v[200:203], v[58:61]
	v_mfma_f32_16x16x32_bf16 v[46:49], v[134:137], v[208:211], v[46:49]
	v_mfma_f32_16x16x32_bf16 v[42:45], v[142:145], v[208:211], v[42:45]
	v_mfma_f32_16x16x32_bf16 v[30:33], v[134:137], v[220:223], v[30:33]
	v_mfma_f32_16x16x32_bf16 v[26:29], v[142:145], v[220:223], v[26:29]
	v_mfma_f32_16x16x32_bf16 v[14:17], v[134:137], v[228:231], v[14:17]
	v_mfma_f32_16x16x32_bf16 v[10:13], v[142:145], v[228:231], v[10:13]
	v_mfma_f32_16x16x32_bf16 v[54:57], v[162:165], v[196:199], v[54:57]
	v_mfma_f32_16x16x32_bf16 v[50:53], v[184:187], v[196:199], v[50:53]
	v_mfma_f32_16x16x32_bf16 v[38:41], v[162:165], v[204:207], v[38:41]
	v_mfma_f32_16x16x32_bf16 v[34:37], v[184:187], v[204:207], v[34:37]
	v_mfma_f32_16x16x32_bf16 v[22:25], v[162:165], v[212:215], v[22:25]
	v_mfma_f32_16x16x32_bf16 v[18:21], v[184:187], v[212:215], v[18:21]
	v_mfma_f32_16x16x32_bf16 v[6:9], v[162:165], v[224:227], v[6:9]
	v_mfma_f32_16x16x32_bf16 v[2:5], v[184:187], v[224:227], v[2:5]
	v_mfma_f32_16x16x32_bf16 v[54:57], v[180:183], v[200:203], v[54:57]
	v_mfma_f32_16x16x32_bf16 v[50:53], v[188:191], v[200:203], v[50:53]
	v_mfma_f32_16x16x32_bf16 v[38:41], v[180:183], v[208:211], v[38:41]
	v_mfma_f32_16x16x32_bf16 v[34:37], v[188:191], v[208:211], v[34:37]
	v_mfma_f32_16x16x32_bf16 v[22:25], v[180:183], v[220:223], v[22:25]
	v_mfma_f32_16x16x32_bf16 v[18:21], v[188:191], v[220:223], v[18:21]
	v_mfma_f32_16x16x32_bf16 v[6:9], v[180:183], v[228:231], v[6:9]
	v_mfma_f32_16x16x32_bf16 v[2:5], v[188:191], v[228:231], v[2:5]
	s_setprio 0
	s_add_i32 s59, 0, 0x18000
	s_add_i32 s60, 0, 0x1c000
	v_add_u32_e32 v142, s59, v166
	v_add_u32_e32 v188, s60, v166
	ds_read_b128 v[130:133], v142
	ds_read_b128 v[134:137], v142 offset:1024
	ds_read_b128 v[138:141], v142 offset:2048
	ds_read_b128 v[142:145], v142 offset:3072
	ds_read_b128 v[162:165], v188
	ds_read_b128 v[180:183], v188 offset:1024
	ds_read_b128 v[184:187], v188 offset:2048
	ds_read_b128 v[188:191], v188 offset:3072
	ds_read_b128 v[196:199], v179 offset:32768
	ds_read_b128 v[200:203], v179 offset:33792
	ds_read_b128 v[204:207], v179 offset:34816
	ds_read_b128 v[208:211], v179 offset:35840
	ds_read_b128 v[212:215], v179 offset:36864
	ds_read_b128 v[220:223], v179 offset:37888
	ds_read_b128 v[224:227], v179 offset:38912
	ds_read_b128 v[228:231], v179 offset:39936
	s_add_u32 vcc_lo, s42, 0x100000
	s_addc_u32 vcc_hi, s43, 0
	s_mov_b32 m0, s24
	s_nop 0
	global_load_lds_dwordx4 v146, s[42:43]
	s_add_i32 m0, s24, 0x2000
	s_nop 0
	global_load_lds_dwordx4 v150, s[42:43]
	s_add_i32 m0, s24, 0x4000
	s_nop 0
	global_load_lds_dwordx4 v146, vcc
	s_add_i32 m0, s24, 0x6000
	s_nop 0
	global_load_lds_dwordx4 v150, vcc
	s_sleep 2
	s_waitcnt lgkmcnt(0)
	s_waitcnt vmcnt(8)
	s_barrier
	s_setprio 2
	v_mfma_f32_16x16x32_bf16 v[126:129], v[130:133], v[196:199], v[126:129]
	v_mfma_f32_16x16x32_bf16 v[122:125], v[138:141], v[196:199], v[122:125]
	v_mfma_f32_16x16x32_bf16 v[110:113], v[130:133], v[204:207], v[110:113]
	v_mfma_f32_16x16x32_bf16 v[106:109], v[138:141], v[204:207], v[106:109]
	v_mfma_f32_16x16x32_bf16 v[94:97], v[130:133], v[212:215], v[94:97]
	v_mfma_f32_16x16x32_bf16 v[90:93], v[138:141], v[212:215], v[90:93]
	v_mfma_f32_16x16x32_bf16 v[78:81], v[130:133], v[224:227], v[78:81]
	v_mfma_f32_16x16x32_bf16 v[74:77], v[138:141], v[224:227], v[74:77]
	v_mfma_f32_16x16x32_bf16 v[126:129], v[134:137], v[200:203], v[126:129]
	v_mfma_f32_16x16x32_bf16 v[122:125], v[142:145], v[200:203], v[122:125]
	v_mfma_f32_16x16x32_bf16 v[110:113], v[134:137], v[208:211], v[110:113]
	v_mfma_f32_16x16x32_bf16 v[106:109], v[142:145], v[208:211], v[106:109]
	v_mfma_f32_16x16x32_bf16 v[94:97], v[134:137], v[220:223], v[94:97]
	v_mfma_f32_16x16x32_bf16 v[90:93], v[142:145], v[220:223], v[90:93]
	v_mfma_f32_16x16x32_bf16 v[78:81], v[134:137], v[228:231], v[78:81]
	v_mfma_f32_16x16x32_bf16 v[74:77], v[142:145], v[228:231], v[74:77]
	v_mfma_f32_16x16x32_bf16 v[118:121], v[162:165], v[196:199], v[118:121]
	v_mfma_f32_16x16x32_bf16 v[114:117], v[184:187], v[196:199], v[114:117]
	v_mfma_f32_16x16x32_bf16 v[102:105], v[162:165], v[204:207], v[102:105]
	v_mfma_f32_16x16x32_bf16 v[98:101], v[184:187], v[204:207], v[98:101]
	v_mfma_f32_16x16x32_bf16 v[86:89], v[162:165], v[212:215], v[86:89]
	v_mfma_f32_16x16x32_bf16 v[82:85], v[184:187], v[212:215], v[82:85]
	v_mfma_f32_16x16x32_bf16 v[70:73], v[162:165], v[224:227], v[70:73]
	v_mfma_f32_16x16x32_bf16 v[66:69], v[184:187], v[224:227], v[66:69]
	v_mfma_f32_16x16x32_bf16 v[118:121], v[180:183], v[200:203], v[118:121]
	v_mfma_f32_16x16x32_bf16 v[114:117], v[188:191], v[200:203], v[114:117]
	v_mfma_f32_16x16x32_bf16 v[102:105], v[180:183], v[208:211], v[102:105]
	v_mfma_f32_16x16x32_bf16 v[98:101], v[188:191], v[208:211], v[98:101]
	v_mfma_f32_16x16x32_bf16 v[86:89], v[180:183], v[220:223], v[86:89]
	v_mfma_f32_16x16x32_bf16 v[82:85], v[188:191], v[220:223], v[82:85]
	v_mfma_f32_16x16x32_bf16 v[70:73], v[180:183], v[228:231], v[70:73]
	v_mfma_f32_16x16x32_bf16 v[66:69], v[188:191], v[228:231], v[66:69]
	s_setprio 0
	ds_read_b128 v[196:199], v179 offset:49152
	ds_read_b128 v[200:203], v179 offset:50176
	ds_read_b128 v[204:207], v179 offset:51200
	ds_read_b128 v[208:211], v179 offset:52224
	ds_read_b128 v[212:215], v179 offset:53248
	ds_read_b128 v[220:223], v179 offset:54272
	ds_read_b128 v[224:227], v179 offset:55296
	ds_read_b128 v[228:231], v179 offset:56320
	s_add_u32 s60, s40, 0x80
	s_addc_u32 s61, s41, 0
	s_add_u32 vcc_lo, s60, 0x100000
	s_addc_u32 vcc_hi, s61, 0
	s_add_i32 m0, s24, 0x18000
	s_nop 0
	global_load_lds_dwordx4 v148, s[60:61]
	s_add_i32 m0, s24, 0x1a000
	s_nop 0
	global_load_lds_dwordx4 v152, s[60:61]
	s_add_i32 m0, s24, 0x1c000
	s_nop 0
	global_load_lds_dwordx4 v148, vcc
	s_add_i32 m0, s24, 0x1e000
	s_nop 0
	global_load_lds_dwordx4 v152, vcc
	s_sleep 2
	s_waitcnt lgkmcnt(0)
	s_waitcnt vmcnt(6)
	s_barrier
; #define PG8_LAS __attribute__((address_space(3)))
; __device__ __forceinline__ unsigned cvt_pk_bf16(float lo, float hi) { unsigned r; asm volatile("v_cvt_pk_bf16_f32 %0, %1, %2" : "=v"(r) : "v"(lo), "v"(hi)); return r; }
; __device__ __forceinline__ f32x4 lds_ld4(const PG8_LAS float* p) { f32x4 v; asm volatile("ds_read_b128 %0, %1\n\ts_waitcnt lgkmcnt(0)" : "=v"(v) : "v"((unsigned)(size_t)p) : "memory"); return v; }
; __device__ __forceinline__ float lds_ld1(const PG8_LAS float* p) { float v; asm volatile("ds_read_b32 %0, %1\n\ts_waitcnt lgkmcnt(0)" : "=v"(v) : "v"((unsigned)(size_t)p) : "memory"); return v; }
; #define PG8_WAIT_V(n) asm volatile("s_waitcnt vmcnt(" #n ")" ::: "memory")
; #define PG8_WAIT_L(n) asm volatile("s_waitcnt lgkmcnt(" #n ")" ::: "memory")
;     __device__ __forceinline__ void operator()(const f32x4 (&acc)[2][2][4][2], const Unit& u, int wr, int wc, int fr, int fq) const {
;         const int row0 = u.pm * BM + wr * 64 + fr, cin = wc * 32 + 8 * fq, col0 = u.pn * BM + cin;
;         const PG8_LAS float* bp = cb + (u.pn >> 2) * BM + cin;
;         f32x4 bv[2][2];
; #pragma unroll
;         for (int bj = 0; bj < 2; ++bj)
; #pragma unroll
;             for (int n = 0; n < 2; ++n) bv[bj][n] = lds_ld4(bp + bj * HALF + 4 * n);
; #pragma unroll
;         for (int ai = 0; ai < 2; ++ai)
; #pragma unroll
;             for (int m = 0; m < 4; ++m) { bf16_t* rowp = O + (size_t)(row0 + ai * HALF + m * 16) * ldc + col0; const float r = lds_ld1(rs + ai * HALF + wr * 64 + m * 16 + fr);
; #pragma unroll
;                 for (int bj = 0; bj < 2; ++bj) { f32x4 v0 = acc[ai][bj][m][0] * r + bv[bj][0], v1 = acc[ai][bj][m][1] * r + bv[bj][1];
; #pragma unroll
;                     for (int j = 0; j < 4; ++j) { const float a = fmaxf(v0[j], 0.f), b = fmaxf(v1[j], 0.f); v0[j] = a * a; v1[j] = b * b; }
;                     u32x4 w; w.x = cvt_pk_bf16(v0[0], v0[1]); w.y = cvt_pk_bf16(v0[2], v0[3]); w.z = cvt_pk_bf16(v1[0], v1[1]); w.w = cvt_pk_bf16(v1[2], v1[3]);
;                     *(u32x4*)(rowp + bj * HALF) = w; } }
; template <class Epi, class Sched, bool ALIGN_EPI = false, bool SP2 = false>
; __device__ __forceinline__ void gemm_phase(PG8_LAS unsigned char* lds, const Gemm g, const Sched& S, const Epi& E) {
;     ...
;             PG8_WAIT_V(8); PG8_WAIT_L(0); PG8_BAR; PG8_MMA(1, 0, At, B0); PG8_MMA(1, 1, At, B1); PG8_BAR; PG8_SCHED;
	s_setprio 2
	v_mfma_f32_16x16x32_bf16 v[62:65], v[130:133], v[196:199], v[62:65]
	v_mfma_f32_16x16x32_bf16 v[58:61], v[138:141], v[196:199], v[58:61]
	v_mfma_f32_16x16x32_bf16 v[46:49], v[130:133], v[204:207], v[46:49]
	v_mfma_f32_16x16x32_bf16 v[42:45], v[138:141], v[204:207], v[42:45]
	v_mfma_f32_16x16x32_bf16 v[30:33], v[130:133], v[212:215], v[30:33]
	v_mfma_f32_16x16x32_bf16 v[26:29], v[138:141], v[212:215], v[26:29]
	v_mfma_f32_16x16x32_bf16 v[14:17], v[130:133], v[224:227], v[14:17]
	v_mfma_f32_16x16x32_bf16 v[10:13], v[138:141], v[224:227], v[10:13]
	v_mfma_f32_16x16x32_bf16 v[62:65], v[134:137], v[200:203], v[62:65]
	v_mfma_f32_16x16x32_bf16 v[58:61], v[142:145], v[200:203], v[58:61]
	v_mfma_f32_16x16x32_bf16 v[46:49], v[134:137], v[208:211], v[46:49]
	v_mfma_f32_16x16x32_bf16 v[42:45], v[142:145], v[208:211], v[42:45]
	v_mfma_f32_16x16x32_bf16 v[30:33], v[134:137], v[220:223], v[30:33]
	v_mfma_f32_16x16x32_bf16 v[26:29], v[142:145], v[220:223], v[26:29]
	v_mfma_f32_16x16x32_bf16 v[14:17], v[134:137], v[228:231], v[14:17]
	v_mfma_f32_16x16x32_bf16 v[10:13], v[142:145], v[228:231], v[10:13]
	v_mfma_f32_16x16x32_bf16 v[54:57], v[162:165], v[196:199], v[54:57]
	v_mfma_f32_16x16x32_bf16 v[50:53], v[184:187], v[196:199], v[50:53]
	v_mfma_f32_16x16x32_bf16 v[38:41], v[162:165], v[204:207], v[38:41]
	v_mfma_f32_16x16x32_bf16 v[34:37], v[184:187], v[204:207], v[34:37]
	v_mfma_f32_16x16x32_bf16 v[22:25], v[162:165], v[212:215], v[22:25]
	v_mfma_f32_16x16x32_bf16 v[18:21], v[184:187], v[212:215], v[18:21]
	v_mfma_f32_16x16x32_bf16 v[6:9], v[162:165], v[224:227], v[6:9]
	v_mfma_f32_16x16x32_bf16 v[2:5], v[184:187], v[224:227], v[2:5]
	v_mfma_f32_16x16x32_bf16 v[54:57], v[180:183], v[200:203], v[54:57]
	v_mfma_f32_16x16x32_bf16 v[50:53], v[188:191], v[200:203], v[50:53]
	v_mfma_f32_16x16x32_bf16 v[38:41], v[180:183], v[208:211], v[38:41]
	v_mfma_f32_16x16x32_bf16 v[34:37], v[188:191], v[208:211], v[34:37]
	v_mfma_f32_16x16x32_bf16 v[22:25], v[180:183], v[220:223], v[22:25]
	v_mfma_f32_16x16x32_bf16 v[18:21], v[188:191], v[220:223], v[18:21]
	v_mfma_f32_16x16x32_bf16 v[6:9], v[180:183], v[228:231], v[6:9]
	v_mfma_f32_16x16x32_bf16 v[2:5], v[188:191], v[228:231], v[2:5]
	s_setprio 0
	s_add_i32 s58, s58, 2
	s_add_u32 s36, s36, 0x100
	s_addc_u32 s37, s37, 0
	s_add_u32 s56, s56, 0x100
	s_addc_u32 s57, s57, 0
	s_cmp_gt_u32 s58, 61
	s_cbranch_scc0 .Lf1_h1
.Lf1_exit:
	s_and_b64 vcc, exec, s[12:13]
	s_cbranch_vccz .LBB0_1254
.LBB0_1254:
	s_lshl_b32 s15, s53, 8
	s_and_b32 s17, s15, 0xfffffc00
	v_add_u32_e32 v130, s17, v168
	ds_read_b128 v[142:145], v130
	s_waitcnt lgkmcnt(0)
	v_add_u32_e32 v131, 16, v130
	ds_read_b128 v[138:141], v131
	s_waitcnt lgkmcnt(0)
	v_add_u32_e32 v131, 0x200, v130
	ds_read_b128 v[134:137], v131
	s_waitcnt lgkmcnt(0)
	v_add_u32_e32 v130, 0x210, v130
	ds_read_b128 v[130:133], v130
	s_waitcnt lgkmcnt(0)
	ds_read_b32 v184, v169
	s_waitcnt lgkmcnt(0)
	v_or_b32_e32 v164, s15, v167
	v_pk_fma_f32 v[122:123], v[122:123], v[184:185], v[138:139] op_sel_hi:[1,0,1]
	v_pk_fma_f32 v[126:127], v[126:127], v[184:185], v[142:143] op_sel_hi:[1,0,1]
	v_pk_fma_f32 v[124:125], v[124:125], v[184:185], v[140:141] op_sel_hi:[1,0,1]
	v_max_f32_e32 v122, 0, v122
	v_lshl_add_u32 v180, s22, 8, v1
	v_ashrrev_i32_e32 v165, 31, v164
	v_mov_b64_e32 v[162:163], s[44:45]
	v_pk_fma_f32 v[128:129], v[128:129], v[184:185], v[144:145] op_sel_hi:[1,0,1]
	v_mul_f32_e32 v181, v122, v122
	v_max_f32_e32 v122, 0, v127
	v_max_f32_e32 v123, 0, v123
	v_max_f32_e32 v124, 0, v124
	v_mad_i64_i32 v[182:183], s[36:37], v180, s52, v[162:163]
	v_lshlrev_b64 v[164:165], 1, v[164:165]
	v_max_f32_e32 v126, 0, v126
	v_mul_f32_e32 v122, v122, v122
	v_mul_f32_e32 v127, v123, v123
	v_max_f32_e32 v123, 0, v128
	v_mul_f32_e32 v128, v124, v124
	v_max_f32_e32 v124, 0, v129
	v_max_f32_e32 v125, 0, v125
	v_pk_fma_f32 v[116:117], v[116:117], v[184:185], v[132:133] op_sel_hi:[1,0,1]
	v_pk_fma_f32 v[114:115], v[114:115], v[184:185], v[130:131] op_sel_hi:[1,0,1]
	v_lshl_add_u64 v[182:183], v[182:183], 0, v[164:165]
	v_mul_f32_e32 v126, v126, v126
	v_mul_f32_e32 v123, v123, v123
	v_mul_f32_e32 v124, v124, v124
	v_mul_f32_e32 v125, v125, v125
	v_cvt_pk_bf16_f32 v122, v126, v122
	v_pk_fma_f32 v[120:121], v[120:121], v[184:185], v[136:137] op_sel_hi:[1,0,1]
	v_pk_fma_f32 v[118:119], v[118:119], v[184:185], v[134:135] op_sel_hi:[1,0,1]
	v_max_f32_e32 v114, 0, v114
	v_max_f32_e32 v115, 0, v115
	v_max_f32_e32 v116, 0, v116
	v_cvt_pk_bf16_f32 v123, v123, v124
	v_cvt_pk_bf16_f32 v124, v181, v127
	v_cvt_pk_bf16_f32 v125, v128, v125
	global_store_dwordx4 v[182:183], v[122:125], off
	v_max_f32_e32 v117, 0, v117
	v_max_f32_e32 v118, 0, v118
	v_mul_f32_e32 v122, v114, v114
	v_max_f32_e32 v114, 0, v119
	v_mul_f32_e32 v119, v115, v115
	v_max_f32_e32 v115, 0, v120
	v_mul_f32_e32 v120, v116, v116
	v_max_f32_e32 v116, 0, v121
	v_mul_f32_e32 v114, v114, v114
	v_mul_f32_e32 v115, v115, v115
	v_mul_f32_e32 v116, v116, v116
	v_mul_f32_e32 v117, v117, v117
	v_mul_f32_e32 v118, v118, v118
	v_cvt_pk_bf16_f32 v114, v118, v114
	v_cvt_pk_bf16_f32 v115, v115, v116
	v_cvt_pk_bf16_f32 v116, v122, v119
	v_cvt_pk_bf16_f32 v117, v120, v117
	global_store_dwordx4 v[182:183], v[114:117], off offset:256
	s_andn2_b64 vcc, exec, s[4:5]
	s_mov_b64 s[4:5], -1
	ds_read_b32 v116, v170
	s_waitcnt lgkmcnt(0)
; __device__ __forceinline__ unsigned cvt_pk_bf16(float lo, float hi) { unsigned r; asm volatile("v_cvt_pk_bf16_f32 %0, %1, %2" : "=v"(r) : "v"(lo), "v"(hi)); return r; }
; __device__ __forceinline__ float lds_ld1(const PG8_LAS float* p) { float v; asm volatile("ds_read_b32 %0, %1\n\ts_waitcnt lgkmcnt(0)" : "=v"(v) : "v"((unsigned)(size_t)p) : "memory"); return v; }
;     __device__ __forceinline__ void operator()(const f32x4 (&acc)[2][2][4][2], const Unit& u, int wr, int wc, int fr, int fq) const {
;     ...
;         for (int ai = 0; ai < 2; ++ai)
; #pragma unroll
;             for (int m = 0; m < 4; ++m) { bf16_t* rowp = O + (size_t)(row0 + ai * HALF + m * 16) * ldc + col0; const float r = lds_ld1(rs + ai * HALF + wr * 64 + m * 16 + fr);
; #pragma unroll
;                 for (int bj = 0; bj < 2; ++bj) { f32x4 v0 = acc[ai][bj][m][0] * r + bv[bj][0], v1 = acc[ai][bj][m][1] * r + bv[bj][1];
; #pragma unroll
;                     for (int j = 0; j < 4; ++j) { const float a = fmaxf(v0[j], 0.f), b = fmaxf(v1[j], 0.f); v0[j] = a * a; v1[j] = b * b; }
;                     u32x4 w; w.x = cvt_pk_bf16(v0[0], v0[1]); w.y = cvt_pk_bf16(v0[2], v0[3]); w.z = cvt_pk_bf16(v1[0], v1[1]); w.w = cvt_pk_bf16(v1[2], v1[3]);
;                     *(u32x4*)(rowp + bj * HALF) = w; } }
	v_or_b32_e32 v114, 16, v180
	v_pk_fma_f32 v[106:107], v[106:107], v[116:117], v[138:139] op_sel_hi:[1,0,1]
	v_pk_fma_f32 v[110:111], v[110:111], v[116:117], v[142:143] op_sel_hi:[1,0,1]
	v_pk_fma_f32 v[108:109], v[108:109], v[116:117], v[140:141] op_sel_hi:[1,0,1]
	v_max_f32_e32 v106, 0, v106
	v_pk_fma_f32 v[112:113], v[112:113], v[116:117], v[144:145] op_sel_hi:[1,0,1]
	v_mul_f32_e32 v117, v106, v106
	v_max_f32_e32 v106, 0, v111
	v_max_f32_e32 v107, 0, v107
	v_max_f32_e32 v108, 0, v108
	v_mad_i64_i32 v[114:115], s[36:37], v114, s52, v[162:163]
	v_max_f32_e32 v110, 0, v110
	v_mul_f32_e32 v106, v106, v106
	v_mul_f32_e32 v111, v107, v107
	v_max_f32_e32 v107, 0, v112
	v_mul_f32_e32 v112, v108, v108
	v_max_f32_e32 v108, 0, v113
	v_max_f32_e32 v109, 0, v109
	v_pk_fma_f32 v[100:101], v[100:101], v[116:117], v[132:133] op_sel_hi:[1,0,1]
	v_pk_fma_f32 v[98:99], v[98:99], v[116:117], v[130:131] op_sel_hi:[1,0,1]
	v_lshl_add_u64 v[114:115], v[114:115], 0, v[164:165]
	v_mul_f32_e32 v110, v110, v110
	v_mul_f32_e32 v107, v107, v107
	v_mul_f32_e32 v108, v108, v108
	v_mul_f32_e32 v109, v109, v109
	v_cvt_pk_bf16_f32 v106, v110, v106
	v_pk_fma_f32 v[104:105], v[104:105], v[116:117], v[136:137] op_sel_hi:[1,0,1]
	v_pk_fma_f32 v[102:103], v[102:103], v[116:117], v[134:135] op_sel_hi:[1,0,1]
	v_max_f32_e32 v98, 0, v98
	v_max_f32_e32 v99, 0, v99
	v_max_f32_e32 v100, 0, v100
	v_cvt_pk_bf16_f32 v107, v107, v108
	v_cvt_pk_bf16_f32 v108, v117, v111
	v_cvt_pk_bf16_f32 v109, v112, v109
	global_store_dwordx4 v[114:115], v[106:109], off
	v_max_f32_e32 v101, 0, v101
	v_max_f32_e32 v102, 0, v102
	v_mul_f32_e32 v106, v98, v98
	v_max_f32_e32 v98, 0, v103
	v_mul_f32_e32 v103, v99, v99
	v_max_f32_e32 v99, 0, v104
	v_mul_f32_e32 v104, v100, v100
	v_max_f32_e32 v100, 0, v105
	v_mul_f32_e32 v98, v98, v98
	v_mul_f32_e32 v99, v99, v99
	v_mul_f32_e32 v100, v100, v100
	v_mul_f32_e32 v101, v101, v101
	v_mul_f32_e32 v102, v102, v102
	v_cvt_pk_bf16_f32 v98, v102, v98
	v_cvt_pk_bf16_f32 v99, v99, v100
	v_cvt_pk_bf16_f32 v100, v106, v103
	v_cvt_pk_bf16_f32 v101, v104, v101
	global_store_dwordx4 v[114:115], v[98:101], off offset:256
	s_nop 1
	ds_read_b32 v100, v171
	s_waitcnt lgkmcnt(0)
	v_or_b32_e32 v98, 32, v180
	v_pk_fma_f32 v[90:91], v[90:91], v[100:101], v[138:139] op_sel_hi:[1,0,1]
	v_pk_fma_f32 v[94:95], v[94:95], v[100:101], v[142:143] op_sel_hi:[1,0,1]
	v_pk_fma_f32 v[92:93], v[92:93], v[100:101], v[140:141] op_sel_hi:[1,0,1]
	v_max_f32_e32 v90, 0, v90
	v_pk_fma_f32 v[96:97], v[96:97], v[100:101], v[144:145] op_sel_hi:[1,0,1]
	v_mul_f32_e32 v101, v90, v90
	v_max_f32_e32 v90, 0, v95
	v_max_f32_e32 v91, 0, v91
	v_max_f32_e32 v92, 0, v92
	v_mad_i64_i32 v[98:99], s[36:37], v98, s52, v[162:163]
	v_max_f32_e32 v94, 0, v94
	v_mul_f32_e32 v90, v90, v90
	v_mul_f32_e32 v95, v91, v91
	v_max_f32_e32 v91, 0, v96
	v_mul_f32_e32 v96, v92, v92
	v_max_f32_e32 v92, 0, v97
	v_max_f32_e32 v93, 0, v93
	v_pk_fma_f32 v[84:85], v[84:85], v[100:101], v[132:133] op_sel_hi:[1,0,1]
	v_pk_fma_f32 v[82:83], v[82:83], v[100:101], v[130:131] op_sel_hi:[1,0,1]
	v_lshl_add_u64 v[98:99], v[98:99], 0, v[164:165]
	v_mul_f32_e32 v94, v94, v94
	v_mul_f32_e32 v91, v91, v91
	v_mul_f32_e32 v92, v92, v92
	v_mul_f32_e32 v93, v93, v93
	v_cvt_pk_bf16_f32 v90, v94, v90
	v_pk_fma_f32 v[88:89], v[88:89], v[100:101], v[136:137] op_sel_hi:[1,0,1]
	v_pk_fma_f32 v[86:87], v[86:87], v[100:101], v[134:135] op_sel_hi:[1,0,1]
	v_max_f32_e32 v82, 0, v82
	v_max_f32_e32 v83, 0, v83
	v_max_f32_e32 v84, 0, v84
	v_cvt_pk_bf16_f32 v91, v91, v92
	v_cvt_pk_bf16_f32 v92, v101, v95
	v_cvt_pk_bf16_f32 v93, v96, v93
	global_store_dwordx4 v[98:99], v[90:93], off
	v_max_f32_e32 v85, 0, v85
	v_max_f32_e32 v86, 0, v86
	v_mul_f32_e32 v90, v82, v82
	v_max_f32_e32 v82, 0, v87
	v_mul_f32_e32 v87, v83, v83
	v_max_f32_e32 v83, 0, v88
	v_mul_f32_e32 v88, v84, v84
	v_max_f32_e32 v84, 0, v89
	v_mul_f32_e32 v82, v82, v82
	v_mul_f32_e32 v83, v83, v83
	v_mul_f32_e32 v84, v84, v84
	v_mul_f32_e32 v85, v85, v85
	v_mul_f32_e32 v86, v86, v86
	v_cvt_pk_bf16_f32 v82, v86, v82
	v_cvt_pk_bf16_f32 v83, v83, v84
	v_cvt_pk_bf16_f32 v84, v90, v87
	v_cvt_pk_bf16_f32 v85, v88, v85
	global_store_dwordx4 v[98:99], v[82:85], off offset:256
	s_nop 1
	ds_read_b32 v84, v172
	s_waitcnt lgkmcnt(0)
	v_or_b32_e32 v82, 48, v180
	v_pk_fma_f32 v[74:75], v[74:75], v[84:85], v[138:139] op_sel_hi:[1,0,1]
	v_pk_fma_f32 v[78:79], v[78:79], v[84:85], v[142:143] op_sel_hi:[1,0,1]
	v_pk_fma_f32 v[76:77], v[76:77], v[84:85], v[140:141] op_sel_hi:[1,0,1]
	v_max_f32_e32 v74, 0, v74
	v_pk_fma_f32 v[80:81], v[80:81], v[84:85], v[144:145] op_sel_hi:[1,0,1]
	v_mul_f32_e32 v85, v74, v74
	v_max_f32_e32 v74, 0, v79
	v_max_f32_e32 v75, 0, v75
	v_max_f32_e32 v76, 0, v76
	v_mad_i64_i32 v[82:83], s[36:37], v82, s52, v[162:163]
	v_max_f32_e32 v78, 0, v78
	v_mul_f32_e32 v74, v74, v74
	v_mul_f32_e32 v79, v75, v75
	v_max_f32_e32 v75, 0, v80
	v_mul_f32_e32 v80, v76, v76
	v_max_f32_e32 v76, 0, v81
	v_max_f32_e32 v77, 0, v77
	v_pk_fma_f32 v[68:69], v[68:69], v[84:85], v[132:133] op_sel_hi:[1,0,1]
	v_pk_fma_f32 v[66:67], v[66:67], v[84:85], v[130:131] op_sel_hi:[1,0,1]
	v_lshl_add_u64 v[82:83], v[82:83], 0, v[164:165]
	v_mul_f32_e32 v78, v78, v78
	v_mul_f32_e32 v75, v75, v75
	v_mul_f32_e32 v76, v76, v76
	v_mul_f32_e32 v77, v77, v77
	v_cvt_pk_bf16_f32 v74, v78, v74
	v_pk_fma_f32 v[72:73], v[72:73], v[84:85], v[136:137] op_sel_hi:[1,0,1]
	v_pk_fma_f32 v[70:71], v[70:71], v[84:85], v[134:135] op_sel_hi:[1,0,1]
	v_max_f32_e32 v66, 0, v66
	v_max_f32_e32 v67, 0, v67
	v_max_f32_e32 v68, 0, v68
	v_cvt_pk_bf16_f32 v75, v75, v76
	v_cvt_pk_bf16_f32 v76, v85, v79
	v_cvt_pk_bf16_f32 v77, v80, v77
	global_store_dwordx4 v[82:83], v[74:77], off
	v_max_f32_e32 v69, 0, v69
	v_max_f32_e32 v70, 0, v70
	v_mul_f32_e32 v74, v66, v66
	v_max_f32_e32 v66, 0, v71
	v_mul_f32_e32 v71, v67, v67
	v_max_f32_e32 v67, 0, v72
	v_mul_f32_e32 v72, v68, v68
	v_max_f32_e32 v68, 0, v73
	v_mul_f32_e32 v66, v66, v66
	v_mul_f32_e32 v67, v67, v67
	v_mul_f32_e32 v68, v68, v68
	v_mul_f32_e32 v69, v69, v69
	v_mul_f32_e32 v70, v70, v70
	v_cvt_pk_bf16_f32 v66, v70, v66
	v_cvt_pk_bf16_f32 v67, v67, v68
	v_cvt_pk_bf16_f32 v68, v74, v71
	v_cvt_pk_bf16_f32 v69, v72, v69
	global_store_dwordx4 v[82:83], v[66:69], off offset:256
	s_nop 1
	ds_read_b32 v68, v173
	s_waitcnt lgkmcnt(0)
; __device__ __forceinline__ unsigned cvt_pk_bf16(float lo, float hi) { unsigned r; asm volatile("v_cvt_pk_bf16_f32 %0, %1, %2" : "=v"(r) : "v"(lo), "v"(hi)); return r; }
; __device__ __forceinline__ float lds_ld1(const PG8_LAS float* p) { float v; asm volatile("ds_read_b32 %0, %1\n\ts_waitcnt lgkmcnt(0)" : "=v"(v) : "v"((unsigned)(size_t)p) : "memory"); return v; }
;     __device__ __forceinline__ void operator()(const f32x4 (&acc)[2][2][4][2], const Unit& u, int wr, int wc, int fr, int fq) const {
;     ...
;         for (int ai = 0; ai < 2; ++ai)
; #pragma unroll
;             for (int m = 0; m < 4; ++m) { bf16_t* rowp = O + (size_t)(row0 + ai * HALF + m * 16) * ldc + col0; const float r = lds_ld1(rs + ai * HALF + wr * 64 + m * 16 + fr);
; #pragma unroll
;                 for (int bj = 0; bj < 2; ++bj) { f32x4 v0 = acc[ai][bj][m][0] * r + bv[bj][0], v1 = acc[ai][bj][m][1] * r + bv[bj][1];
; #pragma unroll
;                     for (int j = 0; j < 4; ++j) { const float a = fmaxf(v0[j], 0.f), b = fmaxf(v1[j], 0.f); v0[j] = a * a; v1[j] = b * b; }
;                     u32x4 w; w.x = cvt_pk_bf16(v0[0], v0[1]); w.y = cvt_pk_bf16(v0[2], v0[3]); w.z = cvt_pk_bf16(v1[0], v1[1]); w.w = cvt_pk_bf16(v1[2], v1[3]);
;                     *(u32x4*)(rowp + bj * HALF) = w; } }
	v_add_u32_e32 v66, 0x80, v180
	v_pk_fma_f32 v[58:59], v[58:59], v[68:69], v[138:139] op_sel_hi:[1,0,1]
	v_pk_fma_f32 v[62:63], v[62:63], v[68:69], v[142:143] op_sel_hi:[1,0,1]
	v_pk_fma_f32 v[60:61], v[60:61], v[68:69], v[140:141] op_sel_hi:[1,0,1]
	v_max_f32_e32 v58, 0, v58
	v_pk_fma_f32 v[64:65], v[64:65], v[68:69], v[144:145] op_sel_hi:[1,0,1]
	v_mul_f32_e32 v69, v58, v58
	v_max_f32_e32 v58, 0, v63
	v_max_f32_e32 v59, 0, v59
	v_max_f32_e32 v60, 0, v60
	v_mad_i64_i32 v[66:67], s[36:37], v66, s52, v[162:163]
	v_max_f32_e32 v62, 0, v62
	v_mul_f32_e32 v58, v58, v58
	v_mul_f32_e32 v63, v59, v59
	v_max_f32_e32 v59, 0, v64
	v_mul_f32_e32 v64, v60, v60
	v_max_f32_e32 v60, 0, v65
	v_max_f32_e32 v61, 0, v61
	v_pk_fma_f32 v[52:53], v[52:53], v[68:69], v[132:133] op_sel_hi:[1,0,1]
	v_pk_fma_f32 v[50:51], v[50:51], v[68:69], v[130:131] op_sel_hi:[1,0,1]
	v_lshl_add_u64 v[66:67], v[66:67], 0, v[164:165]
	v_mul_f32_e32 v62, v62, v62
	v_mul_f32_e32 v59, v59, v59
	v_mul_f32_e32 v60, v60, v60
	v_mul_f32_e32 v61, v61, v61
	v_cvt_pk_bf16_f32 v58, v62, v58
	v_pk_fma_f32 v[56:57], v[56:57], v[68:69], v[136:137] op_sel_hi:[1,0,1]
	v_pk_fma_f32 v[54:55], v[54:55], v[68:69], v[134:135] op_sel_hi:[1,0,1]
	v_max_f32_e32 v50, 0, v50
	v_max_f32_e32 v51, 0, v51
	v_max_f32_e32 v52, 0, v52
	v_cvt_pk_bf16_f32 v59, v59, v60
	v_cvt_pk_bf16_f32 v60, v69, v63
	v_cvt_pk_bf16_f32 v61, v64, v61
	global_store_dwordx4 v[66:67], v[58:61], off
	v_max_f32_e32 v53, 0, v53
	v_max_f32_e32 v54, 0, v54
	v_mul_f32_e32 v58, v50, v50
	v_max_f32_e32 v50, 0, v55
	v_mul_f32_e32 v55, v51, v51
	v_max_f32_e32 v51, 0, v56
	v_mul_f32_e32 v56, v52, v52
	v_max_f32_e32 v52, 0, v57
	v_mul_f32_e32 v50, v50, v50
	v_mul_f32_e32 v51, v51, v51
	v_mul_f32_e32 v52, v52, v52
	v_mul_f32_e32 v53, v53, v53
	v_mul_f32_e32 v54, v54, v54
	v_cvt_pk_bf16_f32 v50, v54, v50
	v_cvt_pk_bf16_f32 v51, v51, v52
	v_cvt_pk_bf16_f32 v52, v58, v55
	v_cvt_pk_bf16_f32 v53, v56, v53
	global_store_dwordx4 v[66:67], v[50:53], off offset:256
	s_nop 1
	ds_read_b32 v52, v174
	s_waitcnt lgkmcnt(0)
	v_add_u32_e32 v50, 0x90, v180
	v_pk_fma_f32 v[42:43], v[42:43], v[52:53], v[138:139] op_sel_hi:[1,0,1]
	v_pk_fma_f32 v[46:47], v[46:47], v[52:53], v[142:143] op_sel_hi:[1,0,1]
	v_pk_fma_f32 v[44:45], v[44:45], v[52:53], v[140:141] op_sel_hi:[1,0,1]
	v_max_f32_e32 v42, 0, v42
	v_pk_fma_f32 v[48:49], v[48:49], v[52:53], v[144:145] op_sel_hi:[1,0,1]
	v_mul_f32_e32 v53, v42, v42
	v_max_f32_e32 v42, 0, v47
	v_max_f32_e32 v43, 0, v43
	v_max_f32_e32 v44, 0, v44
	v_mad_i64_i32 v[50:51], s[36:37], v50, s52, v[162:163]
	v_max_f32_e32 v46, 0, v46
	v_mul_f32_e32 v42, v42, v42
	v_mul_f32_e32 v47, v43, v43
	v_max_f32_e32 v43, 0, v48
	v_mul_f32_e32 v48, v44, v44
	v_max_f32_e32 v44, 0, v49
	v_max_f32_e32 v45, 0, v45
	v_pk_fma_f32 v[36:37], v[36:37], v[52:53], v[132:133] op_sel_hi:[1,0,1]
	v_pk_fma_f32 v[34:35], v[34:35], v[52:53], v[130:131] op_sel_hi:[1,0,1]
	v_lshl_add_u64 v[50:51], v[50:51], 0, v[164:165]
	v_mul_f32_e32 v46, v46, v46
	v_mul_f32_e32 v43, v43, v43
	v_mul_f32_e32 v44, v44, v44
	v_mul_f32_e32 v45, v45, v45
	v_cvt_pk_bf16_f32 v42, v46, v42
	v_pk_fma_f32 v[40:41], v[40:41], v[52:53], v[136:137] op_sel_hi:[1,0,1]
	v_pk_fma_f32 v[38:39], v[38:39], v[52:53], v[134:135] op_sel_hi:[1,0,1]
	v_max_f32_e32 v34, 0, v34
	v_max_f32_e32 v35, 0, v35
	v_max_f32_e32 v36, 0, v36
	v_cvt_pk_bf16_f32 v43, v43, v44
	v_cvt_pk_bf16_f32 v44, v53, v47
	v_cvt_pk_bf16_f32 v45, v48, v45
	global_store_dwordx4 v[50:51], v[42:45], off
	v_max_f32_e32 v37, 0, v37
	v_max_f32_e32 v38, 0, v38
	v_mul_f32_e32 v42, v34, v34
	v_max_f32_e32 v34, 0, v39
	v_mul_f32_e32 v39, v35, v35
	v_max_f32_e32 v35, 0, v40
	v_mul_f32_e32 v40, v36, v36
	v_max_f32_e32 v36, 0, v41
	v_mul_f32_e32 v34, v34, v34
	v_mul_f32_e32 v35, v35, v35
	v_mul_f32_e32 v36, v36, v36
	v_mul_f32_e32 v37, v37, v37
	v_mul_f32_e32 v38, v38, v38
	v_cvt_pk_bf16_f32 v34, v38, v34
	v_cvt_pk_bf16_f32 v35, v35, v36
	v_cvt_pk_bf16_f32 v36, v42, v39
	v_cvt_pk_bf16_f32 v37, v40, v37
	global_store_dwordx4 v[50:51], v[34:37], off offset:256
	s_nop 1
	ds_read_b32 v36, v175
	s_waitcnt lgkmcnt(0)
; __device__ __forceinline__ unsigned cvt_pk_bf16(float lo, float hi) { unsigned r; asm volatile("v_cvt_pk_bf16_f32 %0, %1, %2" : "=v"(r) : "v"(lo), "v"(hi)); return r; }
; __device__ __forceinline__ float lds_ld1(const PG8_LAS float* p) { float v; asm volatile("ds_read_b32 %0, %1\n\ts_waitcnt lgkmcnt(0)" : "=v"(v) : "v"((unsigned)(size_t)p) : "memory"); return v; }
;     __device__ __forceinline__ void operator()(const f32x4 (&acc)[2][2][4][2], const Unit& u, int wr, int wc, int fr, int fq) const {
;     ...
;         for (int ai = 0; ai < 2; ++ai)
; #pragma unroll
;             for (int m = 0; m < 4; ++m) { bf16_t* rowp = O + (size_t)(row0 + ai * HALF + m * 16) * ldc + col0; const float r = lds_ld1(rs + ai * HALF + wr * 64 + m * 16 + fr);
; #pragma unroll
;                 for (int bj = 0; bj < 2; ++bj) { f32x4 v0 = acc[ai][bj][m][0] * r + bv[bj][0], v1 = acc[ai][bj][m][1] * r + bv[bj][1];
; #pragma unroll
;                     for (int j = 0; j < 4; ++j) { const float a = fmaxf(v0[j], 0.f), b = fmaxf(v1[j], 0.f); v0[j] = a * a; v1[j] = b * b; }
;                     u32x4 w; w.x = cvt_pk_bf16(v0[0], v0[1]); w.y = cvt_pk_bf16(v0[2], v0[3]); w.z = cvt_pk_bf16(v1[0], v1[1]); w.w = cvt_pk_bf16(v1[2], v1[3]);
;                     *(u32x4*)(rowp + bj * HALF) = w; } }
; template <class Epi, class Sched, bool ALIGN_EPI = false, bool SP2 = false>
; __device__ __forceinline__ void gemm_phase(PG8_LAS unsigned char* lds, const Gemm g, const Sched& S, const Epi& E) {
;     ...
;         if (!has_next) break;
	v_add_u32_e32 v34, 0xa0, v180
	v_pk_fma_f32 v[26:27], v[26:27], v[36:37], v[138:139] op_sel_hi:[1,0,1]
	v_pk_fma_f32 v[30:31], v[30:31], v[36:37], v[142:143] op_sel_hi:[1,0,1]
	v_pk_fma_f32 v[28:29], v[28:29], v[36:37], v[140:141] op_sel_hi:[1,0,1]
	v_max_f32_e32 v26, 0, v26
	v_pk_fma_f32 v[32:33], v[32:33], v[36:37], v[144:145] op_sel_hi:[1,0,1]
	v_mul_f32_e32 v37, v26, v26
	v_max_f32_e32 v26, 0, v31
	v_max_f32_e32 v27, 0, v27
	v_max_f32_e32 v28, 0, v28
	v_mad_i64_i32 v[34:35], s[36:37], v34, s52, v[162:163]
	v_max_f32_e32 v30, 0, v30
	v_mul_f32_e32 v26, v26, v26
	v_mul_f32_e32 v31, v27, v27
	v_max_f32_e32 v27, 0, v32
	v_mul_f32_e32 v32, v28, v28
	v_max_f32_e32 v28, 0, v33
	v_max_f32_e32 v29, 0, v29
	v_pk_fma_f32 v[20:21], v[20:21], v[36:37], v[132:133] op_sel_hi:[1,0,1]
	v_pk_fma_f32 v[18:19], v[18:19], v[36:37], v[130:131] op_sel_hi:[1,0,1]
	v_lshl_add_u64 v[34:35], v[34:35], 0, v[164:165]
	v_mul_f32_e32 v30, v30, v30
	v_mul_f32_e32 v27, v27, v27
	v_mul_f32_e32 v28, v28, v28
	v_mul_f32_e32 v29, v29, v29
	v_cvt_pk_bf16_f32 v26, v30, v26
	v_pk_fma_f32 v[24:25], v[24:25], v[36:37], v[136:137] op_sel_hi:[1,0,1]
	v_pk_fma_f32 v[22:23], v[22:23], v[36:37], v[134:135] op_sel_hi:[1,0,1]
	v_max_f32_e32 v18, 0, v18
	v_max_f32_e32 v19, 0, v19
	v_max_f32_e32 v20, 0, v20
	v_cvt_pk_bf16_f32 v27, v27, v28
	v_cvt_pk_bf16_f32 v28, v37, v31
	v_cvt_pk_bf16_f32 v29, v32, v29
	global_store_dwordx4 v[34:35], v[26:29], off
	v_max_f32_e32 v21, 0, v21
	v_max_f32_e32 v22, 0, v22
	v_mul_f32_e32 v26, v18, v18
	v_max_f32_e32 v18, 0, v23
	v_mul_f32_e32 v23, v19, v19
	v_max_f32_e32 v19, 0, v24
	v_mul_f32_e32 v24, v20, v20
	v_max_f32_e32 v20, 0, v25
	v_mul_f32_e32 v18, v18, v18
	v_mul_f32_e32 v19, v19, v19
	v_mul_f32_e32 v20, v20, v20
	v_mul_f32_e32 v21, v21, v21
	v_mul_f32_e32 v22, v22, v22
	v_cvt_pk_bf16_f32 v18, v22, v18
	v_cvt_pk_bf16_f32 v19, v19, v20
	v_cvt_pk_bf16_f32 v20, v26, v23
	v_cvt_pk_bf16_f32 v21, v24, v21
	global_store_dwordx4 v[34:35], v[18:21], off offset:256
	s_nop 1
	ds_read_b32 v20, v176
	s_waitcnt lgkmcnt(0)
	v_add_u32_e32 v18, 0xb0, v180
	v_pk_fma_f32 v[10:11], v[10:11], v[20:21], v[138:139] op_sel_hi:[1,0,1]
	v_pk_fma_f32 v[14:15], v[14:15], v[20:21], v[142:143] op_sel_hi:[1,0,1]
	v_pk_fma_f32 v[12:13], v[12:13], v[20:21], v[140:141] op_sel_hi:[1,0,1]
	v_max_f32_e32 v10, 0, v10
	v_pk_fma_f32 v[16:17], v[16:17], v[20:21], v[144:145] op_sel_hi:[1,0,1]
	v_mul_f32_e32 v21, v10, v10
	v_max_f32_e32 v10, 0, v15
	v_max_f32_e32 v11, 0, v11
	v_max_f32_e32 v12, 0, v12
	v_mad_i64_i32 v[18:19], s[36:37], v18, s52, v[162:163]
	v_max_f32_e32 v14, 0, v14
	v_mul_f32_e32 v10, v10, v10
	v_mul_f32_e32 v15, v11, v11
	v_max_f32_e32 v11, 0, v16
	v_mul_f32_e32 v16, v12, v12
	v_max_f32_e32 v12, 0, v17
	v_max_f32_e32 v13, 0, v13
	v_pk_fma_f32 v[4:5], v[4:5], v[20:21], v[132:133] op_sel_hi:[1,0,1]
	v_pk_fma_f32 v[2:3], v[2:3], v[20:21], v[130:131] op_sel_hi:[1,0,1]
	v_lshl_add_u64 v[18:19], v[18:19], 0, v[164:165]
	v_mul_f32_e32 v14, v14, v14
	v_mul_f32_e32 v11, v11, v11
	v_mul_f32_e32 v12, v12, v12
	v_mul_f32_e32 v13, v13, v13
	v_cvt_pk_bf16_f32 v10, v14, v10
	v_pk_fma_f32 v[8:9], v[8:9], v[20:21], v[136:137] op_sel_hi:[1,0,1]
	v_pk_fma_f32 v[6:7], v[6:7], v[20:21], v[134:135] op_sel_hi:[1,0,1]
	v_max_f32_e32 v2, 0, v2
	v_max_f32_e32 v3, 0, v3
	v_max_f32_e32 v4, 0, v4
	v_cvt_pk_bf16_f32 v11, v11, v12
	v_cvt_pk_bf16_f32 v12, v21, v15
	v_cvt_pk_bf16_f32 v13, v16, v13
	global_store_dwordx4 v[18:19], v[10:13], off
	v_max_f32_e32 v5, 0, v5
	v_max_f32_e32 v6, 0, v6
	v_mul_f32_e32 v10, v2, v2
	v_max_f32_e32 v2, 0, v7
	v_mul_f32_e32 v7, v3, v3
	v_max_f32_e32 v3, 0, v8
	v_mul_f32_e32 v8, v4, v4
	v_max_f32_e32 v4, 0, v9
	v_mul_f32_e32 v2, v2, v2
	v_mul_f32_e32 v3, v3, v3
	v_mul_f32_e32 v4, v4, v4
	v_mul_f32_e32 v5, v5, v5
	v_mul_f32_e32 v6, v6, v6
	v_cvt_pk_bf16_f32 v2, v6, v2
	v_cvt_pk_bf16_f32 v3, v3, v4
	v_cvt_pk_bf16_f32 v4, v10, v7
	v_cvt_pk_bf16_f32 v5, v8, v5
	global_store_dwordx4 v[18:19], v[2:5], off offset:256
	s_cbranch_vccnz .LBB0_1243
	s_andn2_b64 vcc, exec, s[6:7]
	s_cbranch_vccnz .LBB0_1242
	s_branch .LBB0_1242

; #define PG8_STAGE(bufoff, gbase, voff) do { _Pragma("unroll") for (int _i = 0; _i < 2; ++_i) \
;         __builtin_amdgcn_global_load_lds((const unsigned*)((const char*)(gbase) + (voff)[_i]), (PG8_LAS unsigned*)(lds + (bufoff) + ldsw + _i * 8192), 16, 0, 0); } while (0)
; #define PG8_WAIT_V(n) asm volatile("s_waitcnt vmcnt(" #n ")" ::: "memory")
; #define PG8_BAR __builtin_amdgcn_s_barrier()
; template <class Epi, class Sched, bool ALIGN_EPI = false, bool SP2 = false>
; __device__ __forceinline__ void gemm_phase(PG8_LAS unsigned char* lds, const Gemm g, const Sched& S, const Epi& E) {
;     const int tid = threadIdx.x, wid = __builtin_amdgcn_readfirstlane(tid >> 6), lane = tid & 63, wr = wid >> 2, wc = wid & 3, fr = lane & 15, fq = lane >> 4;
;     const int K = g.K, nt = K / BK;
;     unsigned voffA[2], voffB[2];
; #pragma unroll
;     for (int i = 0; i < 2; ++i) { int R, C; stage_rc(tid * 16 + i * 8192, R, C); const int Rb = Epi::PERM ? ((R & ~31) + perm32(R & 31)) : R;
;         voffA[i] = (unsigned)(R * g.ld + C) * 2u; voffB[i] = (unsigned)(Rb * g.ld + C) * 2u; }
;     const size_t kstep = (size_t)(BK * 2);
;     const size_t hstep = (size_t)HALF * g.ld * 2;
;     const size_t tstep = 2 * hstep;
;     const unsigned ldsw = (unsigned)wid * 1024u;
;     const int aoff = lds_byte(wr * 64 + fr, fq * 8), boff = lds_byte(wc * 32 + fr, fq * 8);
;     ...
;     if constexpr (SP2) {
;         PG8_STAGE(PG8_SB(0, 0), cB, voffB); PG8_STAGE(PG8_SB(0, 1), cB + hstep, voffB); PG8_STAGE(PG8_SA(0, 0), cA, voffA); PG8_STAGE(PG8_SA(0, 1), cA + hstep, voffA);
;         if (wr == 1) PG8_BAR;
;         PG8_WAIT_V(2); PG8_BAR;
;         PG8_STAGE(PG8_SB(1, 0), cB + kstep, voffB); PG8_STAGE(PG8_SA(1, 0), cA + kstep, voffA); PG8_STAGE(PG8_SB(1, 1), cB + hstep + kstep, voffB);
;         PG8_WAIT_V(6); PG8_BAR;
.LBB0_1317:
	s_lshl_b32 s12, s12, 5
	s_and_b32 s21, s12, 0x60
	s_mov_b64 s[12:13], 0x80
	s_add_i32 m0, s24, 0x18000
	v_lshl_add_u64 v[10:11], v[10:11], 0, s[12:13]
	s_lshl_b32 s20, s15, 13
	s_lshl_b32 s22, s21, 7
	s_waitcnt vmcnt(2)
	s_barrier
	global_load_lds_dwordx4 v[10:11], off
	v_lshl_add_u64 v[8:9], v[8:9], 0, s[12:13]
	s_add_i32 m0, s24, 0x1a000
	s_add_i32 s29, s24, 0x8000
	s_add_i32 s30, s24, 0xa000
	global_load_lds_dwordx4 v[8:9], off
	v_lshl_add_u64 v[4:5], v[4:5], 0, s[12:13]
	s_mov_b32 m0, s29
	s_add_u32 s18, s4, 0x404080
	global_load_lds_dwordx4 v[4:5], off
	v_lshl_add_u64 v[4:5], v[6:7], 0, s[12:13]
	s_mov_b32 m0, s30
	s_addc_u32 s19, s5, 0
	global_load_lds_dwordx4 v[4:5], off
	s_add_i32 m0, s24, 0x1c000
	v_lshl_add_u64 v[4:5], s[18:19], 0, v[138:139]
	global_load_lds_dwordx4 v[4:5], off
	v_lshl_add_u64 v[4:5], s[18:19], 0, v[142:143]
	s_add_i32 m0, s24, 0x1e000
	v_lshl_or_b32 v154, s15, 6, v195
	global_load_lds_dwordx4 v[4:5], off
	s_add_u32 vcc_lo, s6, 0x404080
	s_addc_u32 vcc_hi, s7, 0
	s_add_i32 m0, s24, 0xc000
	s_nop 0
	global_load_lds_dwordx4 v136, vcc
	s_add_i32 m0, s24, 0xe000
	s_nop 0
	global_load_lds_dwordx4 v140, vcc
	v_lshlrev_b32_e32 v4, 1, v13
	v_lshlrev_b32_e32 v0, 6, v0
	s_movk_i32 s15, 0x3c0
	s_cmpk_lt_u32 s14, 0x100
	v_lshl_or_b32 v5, v195, 6, v4
	v_and_or_b32 v0, v0, s15, v4
	v_and_b32_e32 v2, 32, v2
	s_cselect_b64 s[14:15], -1, 0
	v_or_b32_e32 v4, s21, v13
	s_add_i32 s18, 0, 0x20800
	v_bitop3_b32 v0, s22, v0, v2 bitop3:0xf6
	s_waitcnt vmcnt(8)
	v_lshl_add_u32 v155, v4, 2, s18
	v_or_b32_e32 v4, s16, v4
	v_add_u16_e32 v1, v1, v3
	s_add_i32 s35, 0, 0x10000
	s_add_i32 s37, 0, 0x14000
	s_add_i32 s50, 0, 0x18000
	s_add_i32 s52, 0, 0x1c000
	v_bitop3_b32 v2, v5, s20, v2 bitop3:0xde
	v_ashrrev_i32_e32 v5, 31, v4
	v_lshrrev_b16_e32 v1, 1, v1
	v_add_u32_e32 v156, s35, v0
	v_add_u32_e32 v157, s37, v0
	s_add_i32 s35, s35, s17
	s_add_i32 s37, s37, s17
	v_add_u32_e32 v159, s50, v0
	v_add_u32_e32 v160, s52, v0
	s_add_i32 s50, s50, s17
	s_add_i32 s52, s52, s17
	v_lshl_add_u64 v[144:145], v[4:5], 1, s[8:9]
	v_add_lshl_u32 v146, v12, v1, 1
	v_mov_b32_e32 v147, v139
	v_add_lshl_u32 v148, v14, v1, 1
	v_mov_b32_e32 v149, v139
	v_add_u32_e32 v158, 0, v2
	s_add_i32 s31, s24, 0xc000
	s_add_i32 s34, s24, 0xe000
	s_add_i32 s36, s35, 0x2000
	s_add_i32 s40, s37, 0x2000
	s_mov_b32 s41, 0x20000
	s_mov_b32 s42, 0x40000
	s_mov_b32 s43, 0x60000
	s_mov_b32 s46, 0x100000
	s_mov_b32 s47, 0x120000
	s_mov_b32 s48, 0x140000
	s_mov_b32 s49, 0x160000
	s_add_i32 s51, s50, 0x2000
	s_add_i32 s53, s52, 0x2000
	s_mov_b32 s54, s2
	s_mov_b64 s[16:17], s[4:5]
	s_barrier
	s_branch .LBB0_1320

;     __device__ __forceinline__ bool next(int i, Unit& u) const { const long L = (long)i * G + c; if (L >= nwg) return false; std_map((int)L, nM, nN, u, wgm); u.ui = i; return true; }
;     __device__ __forceinline__ bool next(int i, Unit& u) const { if (i >= 4) return false; const int x = c & 7, r = c >> 3; u.pm = 16 * i + 4 * (x >> 1) + (r & 3); u.pn = 8 * (x & 1) + (r >> 2); u.ui = i; return true; }
; #define PG8_STAGE(bufoff, gbase, voff) do { _Pragma("unroll") for (int _i = 0; _i < 2; ++_i) \
;         __builtin_amdgcn_global_load_lds((const unsigned*)((const char*)(gbase) + (voff)[_i]), (PG8_LAS unsigned*)(lds + (bufoff) + ldsw + _i * 8192), 16, 0, 0); } while (0)
; #define PG8_LDA(dst, b, h) do { _Pragma("unroll") for (int m = 0; m < 4; ++m) _Pragma("unroll") for (int k = 0; k < 2; ++k) dst[m][k] = *(const PG8_LAS bf16x8*)(lds + PG8_SA(b, h) + aoff + m * 2048 + k * 1024); } while (0)
; #define PG8_LDB(dst, b, h) do { _Pragma("unroll") for (int n = 0; n < 2; ++n) _Pragma("unroll") for (int k = 0; k < 2; ++k) dst[n][k] = *(const PG8_LAS bf16x8*)(lds + PG8_SB(b, h) + boff + n * 2048 + k * 1024); } while (0)
; #define PG8_WAIT_V(n) asm volatile("s_waitcnt vmcnt(" #n ")" ::: "memory")
; template <class Epi, class Sched, bool ALIGN_EPI = false, bool SP2 = false>
; __device__ __forceinline__ void gemm_phase(PG8_LAS unsigned char* lds, const Gemm g, const Sched& S, const Epi& E) {
;     ...
;         const bool has_next = S.next(ui + 1, nxt);
;         const char* nA = cA; const char* nB = cB; if (has_next) S.bases(nxt, g, tstep, nA, nB);
;         for (int t = 0; t < nt; t += 2) {
;             const bool last = (t == nt - 2);
;             const char* a1 = cA + (size_t)(t + 1) * kstep;
;             const char* a2 = last ? nA : cA + (size_t)(t + 2) * kstep; const char* b2 = last ? nB : cB + (size_t)(t + 2) * kstep;
;             const char* a3 = a2 + kstep; const char* b3 = b2 + kstep;
;             if (last && has_next) S.a_ready(nxt);
;             if constexpr (Epi::MIDK) { if (t == (nt >> 1)) { E.midk(acc, wr, fr); asm volatile("s_waitcnt lgkmcnt(0)" ::: "memory"); } }
;             if constexpr (SP2) {
;             PG8_LDB(B0, 0, 0); PG8_LDB(B1, 0, 1); PG8_SCHED; PG8_LDA(At, 0, 0); PG8_STAGE(PG8_SA(1, 1), a1 + hstep, voffA);
;             PG8_WAIT_V(8); PG8_WAIT_L(0); PG8_BAR; PG8_MMA(0, 0, At, B0); PG8_MMA(0, 1, At, B1); PG8_BAR; PG8_SCHED;
.LBB0_1320:
	s_mov_b32 s55, s28
	s_add_i32 s28, s28, 1
	s_mov_b64 s[18:19], s[6:7]
	s_lshl_b32 s6, s28, 4
	s_mov_b32 s56, s54
	s_or_b32 s54, s6, s2
	s_mul_i32 s6, s54, 0x808000
	s_add_u32 s6, s44, s6
	s_addc_u32 s7, s45, 0
	s_cmp_lt_u32 s55, 3
	s_mov_b64 s[20:21], s[16:17]
	s_cselect_b32 s7, s7, s19
	s_cselect_b32 s6, s6, s18
	s_cselect_b32 s17, s5, s21
	s_cselect_b32 s16, s4, s20
	s_add_u32 s18, s18, 0x404080
	s_addc_u32 s19, s19, 0
	s_add_u32 s57, s20, 0x100
	v_mov_b32_e32 v0, 0
	s_addc_u32 s58, s21, 0
	s_mov_b32 s59, -2
	v_mov_b32_e32 v1, v0
	v_mov_b32_e32 v2, v0
	v_mov_b32_e32 v3, v0
	v_mov_b32_e32 v4, v0
	v_mov_b32_e32 v5, v0
	v_mov_b32_e32 v6, v0
	v_mov_b32_e32 v7, v0
	v_mov_b32_e32 v8, v0
	v_mov_b32_e32 v9, v0
	v_mov_b32_e32 v10, v0
	v_mov_b32_e32 v11, v0
	v_mov_b32_e32 v12, v0
	v_mov_b32_e32 v13, v0
	v_mov_b32_e32 v14, v0
	v_mov_b32_e32 v15, v0
	v_mov_b32_e32 v16, v0
	v_mov_b32_e32 v17, v0
	v_mov_b32_e32 v18, v0
	v_mov_b32_e32 v19, v0
	v_mov_b32_e32 v20, v0
	v_mov_b32_e32 v21, v0
	v_mov_b32_e32 v22, v0
	v_mov_b32_e32 v23, v0
	v_mov_b32_e32 v24, v0
	v_mov_b32_e32 v25, v0
	v_mov_b32_e32 v26, v0
	v_mov_b32_e32 v27, v0
	v_mov_b32_e32 v28, v0
	v_mov_b32_e32 v29, v0
	v_mov_b32_e32 v30, v0
	v_mov_b32_e32 v31, v0
	v_mov_b32_e32 v56, v0
	v_mov_b32_e32 v57, v0
	v_mov_b32_e32 v58, v0
	v_mov_b32_e32 v59, v0
	v_mov_b32_e32 v60, v0
	v_mov_b32_e32 v61, v0
	v_mov_b32_e32 v62, v0
	v_mov_b32_e32 v63, v0
	v_mov_b32_e32 v72, v0
	v_mov_b32_e32 v73, v0
	v_mov_b32_e32 v74, v0
	v_mov_b32_e32 v75, v0
	v_mov_b32_e32 v76, v0
	v_mov_b32_e32 v77, v0
	v_mov_b32_e32 v78, v0
	v_mov_b32_e32 v79, v0
	v_mov_b32_e32 v80, v0
	v_mov_b32_e32 v81, v0
	v_mov_b32_e32 v82, v0
	v_mov_b32_e32 v83, v0
	v_mov_b32_e32 v84, v0
	v_mov_b32_e32 v85, v0
	v_mov_b32_e32 v86, v0
	v_mov_b32_e32 v87, v0
	v_mov_b32_e32 v88, v0
	v_mov_b32_e32 v89, v0
	v_mov_b32_e32 v90, v0
	v_mov_b32_e32 v91, v0
	v_mov_b32_e32 v92, v0
	v_mov_b32_e32 v93, v0
	v_mov_b32_e32 v94, v0
	v_mov_b32_e32 v95, v0
	v_mov_b32_e32 v32, v0
	v_mov_b32_e32 v33, v0
	v_mov_b32_e32 v34, v0
	v_mov_b32_e32 v35, v0
	v_mov_b32_e32 v36, v0
	v_mov_b32_e32 v37, v0
	v_mov_b32_e32 v38, v0
	v_mov_b32_e32 v39, v0
	v_mov_b32_e32 v40, v0
	v_mov_b32_e32 v41, v0
	v_mov_b32_e32 v42, v0
	v_mov_b32_e32 v43, v0
	v_mov_b32_e32 v44, v0
	v_mov_b32_e32 v45, v0
	v_mov_b32_e32 v46, v0
	v_mov_b32_e32 v47, v0
	v_mov_b32_e32 v48, v0
	v_mov_b32_e32 v49, v0
	v_mov_b32_e32 v50, v0
	v_mov_b32_e32 v51, v0
	v_mov_b32_e32 v52, v0
	v_mov_b32_e32 v53, v0
	v_mov_b32_e32 v54, v0
	v_mov_b32_e32 v55, v0
	v_mov_b32_e32 v64, v0
	v_mov_b32_e32 v65, v0
	v_mov_b32_e32 v66, v0
	v_mov_b32_e32 v67, v0
	v_mov_b32_e32 v68, v0
	v_mov_b32_e32 v69, v0
	v_mov_b32_e32 v70, v0
	v_mov_b32_e32 v71, v0
	v_mov_b32_e32 v96, v0
	v_mov_b32_e32 v97, v0
	v_mov_b32_e32 v98, v0
	v_mov_b32_e32 v99, v0
	v_mov_b32_e32 v100, v0
	v_mov_b32_e32 v101, v0
	v_mov_b32_e32 v102, v0
	v_mov_b32_e32 v103, v0
	v_mov_b32_e32 v104, v0
	v_mov_b32_e32 v105, v0
	v_mov_b32_e32 v106, v0
	v_mov_b32_e32 v107, v0
	v_mov_b32_e32 v108, v0
	v_mov_b32_e32 v109, v0
	v_mov_b32_e32 v110, v0
	v_mov_b32_e32 v111, v0
	v_mov_b32_e32 v112, v0
	v_mov_b32_e32 v113, v0
	v_mov_b32_e32 v114, v0
	v_mov_b32_e32 v115, v0
	v_mov_b32_e32 v116, v0
	v_mov_b32_e32 v117, v0
	v_mov_b32_e32 v118, v0
	v_mov_b32_e32 v119, v0
	v_mov_b32_e32 v120, v0
	v_mov_b32_e32 v121, v0
	v_mov_b32_e32 v122, v0
	v_mov_b32_e32 v123, v0
	v_mov_b32_e32 v124, v0
	v_mov_b32_e32 v125, v0
	v_mov_b32_e32 v126, v0
	v_mov_b32_e32 v127, v0
	s_cmp_lt_u32 s24, 0x1000
	s_cbranch_scc0 .Lf2_h1
.LBB0_1321:
	ds_read_b128 v[128:131], v156
	ds_read_b128 v[132:135], v156 offset:1024
	ds_read_b128 v[150:153], v156 offset:2048
	ds_read_b128 v[162:165], v156 offset:3072
	ds_read_b128 v[166:169], v157
	ds_read_b128 v[170:173], v157 offset:1024
	ds_read_b128 v[174:177], v157 offset:2048
	ds_read_b128 v[178:181], v157 offset:3072
	s_add_u32 s20, s18, 0xffbfc080
	s_addc_u32 s21, s19, -1
	s_cmpk_eq_i32 s59, 0xfc
	s_cselect_b32 s23, s7, s21
	s_cselect_b32 s22, s6, s20
	s_cselect_b32 s21, s17, s58
	s_cselect_b32 s20, s16, s57
	ds_read_b128 v[182:185], v158
	ds_read_b128 v[186:189], v158 offset:1024
	ds_read_b128 v[190:193], v158 offset:2048
	ds_read_b128 v[194:197], v158 offset:3072
	ds_read_b128 v[198:201], v158 offset:4096
	ds_read_b128 v[202:205], v158 offset:5120
	ds_read_b128 v[206:209], v158 offset:6144
	ds_read_b128 v[210:213], v158 offset:7168
	s_add_u32 s60, s18, 0xffbfc000
	s_addc_u32 s61, s19, -1
	s_add_i32 m0, s24, 0x8000
	s_nop 0
	global_load_lds_dwordx4 v136, s[60:61]
	s_add_i32 m0, s24, 0xa000
	s_nop 0
	global_load_lds_dwordx4 v140, s[60:61]
	s_add_i32 m0, s24, 0xc000
	s_nop 0
	global_load_lds_dwordx4 v136, s[18:19]
	s_add_i32 m0, s24, 0xe000
	s_nop 0
	global_load_lds_dwordx4 v140, s[18:19]
	s_waitcnt lgkmcnt(0)
; #define PG8_STAGE(bufoff, gbase, voff) do { _Pragma("unroll") for (int _i = 0; _i < 2; ++_i) \
;         __builtin_amdgcn_global_load_lds((const unsigned*)((const char*)(gbase) + (voff)[_i]), (PG8_LAS unsigned*)(lds + (bufoff) + ldsw + _i * 8192), 16, 0, 0); } while (0)
; #define PG8_LDA(dst, b, h) do { _Pragma("unroll") for (int m = 0; m < 4; ++m) _Pragma("unroll") for (int k = 0; k < 2; ++k) dst[m][k] = *(const PG8_LAS bf16x8*)(lds + PG8_SA(b, h) + aoff + m * 2048 + k * 1024); } while (0)
; #define PG8_MMA(ai, bj, At, Bt) do { __builtin_amdgcn_s_setprio(1); _Pragma("unroll") for (int m = 0; m < 4; ++m) _Pragma("unroll") for (int n = 0; n < 2; ++n) _Pragma("unroll") for (int k = 0; k < 2; ++k) \
;         acc[ai][bj][m][n] = __builtin_amdgcn_mfma_f32_16x16x32_bf16(Bt[n][k], At[m][k], acc[ai][bj][m][n], 0, 0, 0); __builtin_amdgcn_s_setprio(0); } while (0)
; #define PG8_WAIT_V(n) asm volatile("s_waitcnt vmcnt(" #n ")" ::: "memory")
; #define PG8_WAIT_L(n) asm volatile("s_waitcnt lgkmcnt(" #n ")" ::: "memory")
; #define PG8_BAR __builtin_amdgcn_s_barrier()
; #define PG8_SCHED __builtin_amdgcn_sched_barrier(0)
; template <class Epi, class Sched, bool ALIGN_EPI = false, bool SP2 = false>
; __device__ __forceinline__ void gemm_phase(PG8_LAS unsigned char* lds, const Gemm g, const Sched& S, const Epi& E) {
;     ...
;             PG8_WAIT_V(8); PG8_WAIT_L(0); PG8_BAR; PG8_MMA(0, 0, At, B0); PG8_MMA(0, 1, At, B1); PG8_BAR; PG8_SCHED;
;             PG8_LDA(At, 0, 1); PG8_STAGE(PG8_SB(0, 0), b2, voffB); PG8_STAGE(PG8_SB(0, 1), b2 + hstep, voffB); PG8_STAGE(PG8_SA(0, 0), a2, voffA);
;             PG8_WAIT_V(8); PG8_WAIT_L(0); PG8_BAR; PG8_MMA(1, 0, At, B0); PG8_MMA(1, 1, At, B1); PG8_BAR; PG8_SCHED;
	s_setprio 1
	v_mfma_f32_16x16x32_bf16 v[124:127], v[128:131], v[182:185], v[124:127]
	v_mfma_f32_16x16x32_bf16 v[120:123], v[150:153], v[182:185], v[120:123]
	v_mfma_f32_16x16x32_bf16 v[116:119], v[128:131], v[190:193], v[116:119]
	v_mfma_f32_16x16x32_bf16 v[112:115], v[150:153], v[190:193], v[112:115]
	v_mfma_f32_16x16x32_bf16 v[108:111], v[128:131], v[198:201], v[108:111]
	v_mfma_f32_16x16x32_bf16 v[104:107], v[150:153], v[198:201], v[104:107]
	v_mfma_f32_16x16x32_bf16 v[100:103], v[128:131], v[206:209], v[100:103]
	v_mfma_f32_16x16x32_bf16 v[96:99], v[150:153], v[206:209], v[96:99]
	v_mfma_f32_16x16x32_bf16 v[124:127], v[132:135], v[186:189], v[124:127]
	v_mfma_f32_16x16x32_bf16 v[120:123], v[162:165], v[186:189], v[120:123]
	v_mfma_f32_16x16x32_bf16 v[116:119], v[132:135], v[194:197], v[116:119]
	v_mfma_f32_16x16x32_bf16 v[112:115], v[162:165], v[194:197], v[112:115]
	v_mfma_f32_16x16x32_bf16 v[108:111], v[132:135], v[202:205], v[108:111]
	v_mfma_f32_16x16x32_bf16 v[104:107], v[162:165], v[202:205], v[104:107]
	v_mfma_f32_16x16x32_bf16 v[100:103], v[132:135], v[210:213], v[100:103]
	v_mfma_f32_16x16x32_bf16 v[96:99], v[162:165], v[210:213], v[96:99]
	v_mfma_f32_16x16x32_bf16 v[68:71], v[166:169], v[182:185], v[68:71]
	v_mfma_f32_16x16x32_bf16 v[64:67], v[174:177], v[182:185], v[64:67]
	v_mfma_f32_16x16x32_bf16 v[52:55], v[166:169], v[190:193], v[52:55]
	v_mfma_f32_16x16x32_bf16 v[48:51], v[174:177], v[190:193], v[48:51]
	v_mfma_f32_16x16x32_bf16 v[44:47], v[166:169], v[198:201], v[44:47]
	v_mfma_f32_16x16x32_bf16 v[40:43], v[174:177], v[198:201], v[40:43]
	v_mfma_f32_16x16x32_bf16 v[36:39], v[166:169], v[206:209], v[36:39]
	v_mfma_f32_16x16x32_bf16 v[32:35], v[174:177], v[206:209], v[32:35]
	v_mfma_f32_16x16x32_bf16 v[68:71], v[170:173], v[186:189], v[68:71]
	v_mfma_f32_16x16x32_bf16 v[64:67], v[178:181], v[186:189], v[64:67]
	v_mfma_f32_16x16x32_bf16 v[52:55], v[170:173], v[194:197], v[52:55]
	v_mfma_f32_16x16x32_bf16 v[48:51], v[178:181], v[194:197], v[48:51]
	v_mfma_f32_16x16x32_bf16 v[44:47], v[170:173], v[202:205], v[44:47]
	v_mfma_f32_16x16x32_bf16 v[40:43], v[178:181], v[202:205], v[40:43]
	v_mfma_f32_16x16x32_bf16 v[36:39], v[170:173], v[210:213], v[36:39]
	v_mfma_f32_16x16x32_bf16 v[32:35], v[178:181], v[210:213], v[32:35]
	s_setprio 0
	s_waitcnt vmcnt(8)
	s_barrier
	ds_read_b128 v[182:185], v158 offset:16384
	ds_read_b128 v[186:189], v158 offset:17408
	ds_read_b128 v[190:193], v158 offset:18432
	ds_read_b128 v[194:197], v158 offset:19456
	ds_read_b128 v[198:201], v158 offset:20480
	ds_read_b128 v[202:205], v158 offset:21504
	ds_read_b128 v[206:209], v158 offset:22528
	ds_read_b128 v[210:213], v158 offset:23552
	s_add_u32 vcc_lo, s20, 0x404000
	s_addc_u32 vcc_hi, s21, 0
	s_add_i32 m0, s24, 0x10000
	s_nop 0
	global_load_lds_dwordx4 v138, s[20:21]
	s_add_i32 m0, s24, 0x12000
	s_nop 0
	global_load_lds_dwordx4 v142, s[20:21]
	s_add_i32 m0, s24, 0x14000
	s_nop 0
	global_load_lds_dwordx4 v138, vcc
	s_add_i32 m0, s24, 0x16000
	s_nop 0
	global_load_lds_dwordx4 v142, vcc
	s_waitcnt lgkmcnt(0)
	s_setprio 1
	v_mfma_f32_16x16x32_bf16 v[92:95], v[128:131], v[182:185], v[92:95]
	v_mfma_f32_16x16x32_bf16 v[88:91], v[150:153], v[182:185], v[88:91]
	v_mfma_f32_16x16x32_bf16 v[84:87], v[128:131], v[190:193], v[84:87]
	v_mfma_f32_16x16x32_bf16 v[80:83], v[150:153], v[190:193], v[80:83]
	v_mfma_f32_16x16x32_bf16 v[76:79], v[128:131], v[198:201], v[76:79]
	v_mfma_f32_16x16x32_bf16 v[72:75], v[150:153], v[198:201], v[72:75]
	v_mfma_f32_16x16x32_bf16 v[60:63], v[128:131], v[206:209], v[60:63]
	v_mfma_f32_16x16x32_bf16 v[56:59], v[150:153], v[206:209], v[56:59]
	v_mfma_f32_16x16x32_bf16 v[92:95], v[132:135], v[186:189], v[92:95]
	v_mfma_f32_16x16x32_bf16 v[88:91], v[162:165], v[186:189], v[88:91]
	v_mfma_f32_16x16x32_bf16 v[84:87], v[132:135], v[194:197], v[84:87]
	v_mfma_f32_16x16x32_bf16 v[80:83], v[162:165], v[194:197], v[80:83]
	v_mfma_f32_16x16x32_bf16 v[76:79], v[132:135], v[202:205], v[76:79]
	v_mfma_f32_16x16x32_bf16 v[72:75], v[162:165], v[202:205], v[72:75]
	v_mfma_f32_16x16x32_bf16 v[60:63], v[132:135], v[210:213], v[60:63]
	v_mfma_f32_16x16x32_bf16 v[56:59], v[162:165], v[210:213], v[56:59]
	v_mfma_f32_16x16x32_bf16 v[28:31], v[166:169], v[182:185], v[28:31]
	v_mfma_f32_16x16x32_bf16 v[24:27], v[174:177], v[182:185], v[24:27]
	v_mfma_f32_16x16x32_bf16 v[20:23], v[166:169], v[190:193], v[20:23]
	v_mfma_f32_16x16x32_bf16 v[16:19], v[174:177], v[190:193], v[16:19]
	v_mfma_f32_16x16x32_bf16 v[12:15], v[166:169], v[198:201], v[12:15]
	v_mfma_f32_16x16x32_bf16 v[8:11], v[174:177], v[198:201], v[8:11]
	v_mfma_f32_16x16x32_bf16 v[4:7], v[166:169], v[206:209], v[4:7]
	v_mfma_f32_16x16x32_bf16 v[0:3], v[174:177], v[206:209], v[0:3]
	v_mfma_f32_16x16x32_bf16 v[28:31], v[170:173], v[186:189], v[28:31]
	v_mfma_f32_16x16x32_bf16 v[24:27], v[178:181], v[186:189], v[24:27]
	v_mfma_f32_16x16x32_bf16 v[20:23], v[170:173], v[194:197], v[20:23]
	v_mfma_f32_16x16x32_bf16 v[16:19], v[178:181], v[194:197], v[16:19]
	v_mfma_f32_16x16x32_bf16 v[12:15], v[170:173], v[202:205], v[12:15]
	v_mfma_f32_16x16x32_bf16 v[8:11], v[178:181], v[202:205], v[8:11]
	v_mfma_f32_16x16x32_bf16 v[4:7], v[170:173], v[210:213], v[4:7]
	v_mfma_f32_16x16x32_bf16 v[0:3], v[178:181], v[210:213], v[0:3]
	s_setprio 0
	s_waitcnt vmcnt(6)
	s_barrier
; #define PG8_STAGE(bufoff, gbase, voff) do { _Pragma("unroll") for (int _i = 0; _i < 2; ++_i) \
;         __builtin_amdgcn_global_load_lds((const unsigned*)((const char*)(gbase) + (voff)[_i]), (PG8_LAS unsigned*)(lds + (bufoff) + ldsw + _i * 8192), 16, 0, 0); } while (0)
; #define PG8_LDA(dst, b, h) do { _Pragma("unroll") for (int m = 0; m < 4; ++m) _Pragma("unroll") for (int k = 0; k < 2; ++k) dst[m][k] = *(const PG8_LAS bf16x8*)(lds + PG8_SA(b, h) + aoff + m * 2048 + k * 1024); } while (0)
; #define PG8_LDB(dst, b, h) do { _Pragma("unroll") for (int n = 0; n < 2; ++n) _Pragma("unroll") for (int k = 0; k < 2; ++k) dst[n][k] = *(const PG8_LAS bf16x8*)(lds + PG8_SB(b, h) + boff + n * 2048 + k * 1024); } while (0)
; #define PG8_MMA(ai, bj, At, Bt) do { __builtin_amdgcn_s_setprio(1); _Pragma("unroll") for (int m = 0; m < 4; ++m) _Pragma("unroll") for (int n = 0; n < 2; ++n) _Pragma("unroll") for (int k = 0; k < 2; ++k) \
;         acc[ai][bj][m][n] = __builtin_amdgcn_mfma_f32_16x16x32_bf16(Bt[n][k], At[m][k], acc[ai][bj][m][n], 0, 0, 0); __builtin_amdgcn_s_setprio(0); } while (0)
; #define PG8_WAIT_V(n) asm volatile("s_waitcnt vmcnt(" #n ")" ::: "memory")
; #define PG8_WAIT_L(n) asm volatile("s_waitcnt lgkmcnt(" #n ")" ::: "memory")
; #define PG8_BAR __builtin_amdgcn_s_barrier()
; #define PG8_SCHED __builtin_amdgcn_sched_barrier(0)
; template <class Epi, class Sched, bool ALIGN_EPI = false, bool SP2 = false>
; __device__ __forceinline__ void gemm_phase(PG8_LAS unsigned char* lds, const Gemm g, const Sched& S, const Epi& E) {
;     ...
;             PG8_LDB(B0, 1, 0); PG8_LDB(B1, 1, 1); PG8_SCHED; PG8_LDA(At, 1, 0); PG8_STAGE(PG8_SA(0, 1), a2 + hstep, voffA);
;             PG8_WAIT_V(8); PG8_WAIT_L(0); PG8_BAR; PG8_MMA(0, 0, At, B0); PG8_MMA(0, 1, At, B1); PG8_BAR; PG8_SCHED;
;             PG8_LDA(At, 1, 1); PG8_STAGE(PG8_SB(1, 0), b3, voffB); PG8_STAGE(PG8_SB(1, 1), b3 + hstep, voffB); PG8_STAGE(PG8_SA(1, 0), a3, voffA);
;             PG8_WAIT_V(8); PG8_WAIT_L(0); PG8_BAR; PG8_MMA(1, 0, At, B0); PG8_MMA(1, 1, At, B1); PG8_BAR; PG8_SCHED;
	ds_read_b128 v[128:131], v159
	ds_read_b128 v[132:135], v159 offset:1024
	ds_read_b128 v[150:153], v159 offset:2048
	ds_read_b128 v[162:165], v159 offset:3072
	ds_read_b128 v[166:169], v160
	ds_read_b128 v[170:173], v160 offset:1024
	ds_read_b128 v[174:177], v160 offset:2048
	ds_read_b128 v[178:181], v160 offset:3072
	ds_read_b128 v[182:185], v158 offset:32768
	ds_read_b128 v[186:189], v158 offset:33792
	ds_read_b128 v[190:193], v158 offset:34816
	ds_read_b128 v[194:197], v158 offset:35840
	ds_read_b128 v[198:201], v158 offset:36864
	ds_read_b128 v[202:205], v158 offset:37888
	ds_read_b128 v[206:209], v158 offset:38912
	ds_read_b128 v[210:213], v158 offset:39936
	s_add_u32 vcc_lo, s22, 0x404000
	s_addc_u32 vcc_hi, s23, 0
	s_mov_b32 m0, s24
	s_nop 0
	global_load_lds_dwordx4 v136, s[22:23]
	s_add_i32 m0, s24, 0x2000
	s_nop 0
	global_load_lds_dwordx4 v140, s[22:23]
	s_add_i32 m0, s24, 0x4000
	s_nop 0
	global_load_lds_dwordx4 v136, vcc
	s_add_i32 m0, s24, 0x6000
	s_nop 0
	global_load_lds_dwordx4 v140, vcc
	s_waitcnt lgkmcnt(0)
	s_setprio 1
	v_mfma_f32_16x16x32_bf16 v[124:127], v[128:131], v[182:185], v[124:127]
	v_mfma_f32_16x16x32_bf16 v[120:123], v[150:153], v[182:185], v[120:123]
	v_mfma_f32_16x16x32_bf16 v[116:119], v[128:131], v[190:193], v[116:119]
	v_mfma_f32_16x16x32_bf16 v[112:115], v[150:153], v[190:193], v[112:115]
	v_mfma_f32_16x16x32_bf16 v[108:111], v[128:131], v[198:201], v[108:111]
	v_mfma_f32_16x16x32_bf16 v[104:107], v[150:153], v[198:201], v[104:107]
	v_mfma_f32_16x16x32_bf16 v[100:103], v[128:131], v[206:209], v[100:103]
	v_mfma_f32_16x16x32_bf16 v[96:99], v[150:153], v[206:209], v[96:99]
	v_mfma_f32_16x16x32_bf16 v[124:127], v[132:135], v[186:189], v[124:127]
	v_mfma_f32_16x16x32_bf16 v[120:123], v[162:165], v[186:189], v[120:123]
	v_mfma_f32_16x16x32_bf16 v[116:119], v[132:135], v[194:197], v[116:119]
	v_mfma_f32_16x16x32_bf16 v[112:115], v[162:165], v[194:197], v[112:115]
	v_mfma_f32_16x16x32_bf16 v[108:111], v[132:135], v[202:205], v[108:111]
	v_mfma_f32_16x16x32_bf16 v[104:107], v[162:165], v[202:205], v[104:107]
	v_mfma_f32_16x16x32_bf16 v[100:103], v[132:135], v[210:213], v[100:103]
	v_mfma_f32_16x16x32_bf16 v[96:99], v[162:165], v[210:213], v[96:99]
	v_mfma_f32_16x16x32_bf16 v[68:71], v[166:169], v[182:185], v[68:71]
	v_mfma_f32_16x16x32_bf16 v[64:67], v[174:177], v[182:185], v[64:67]
	v_mfma_f32_16x16x32_bf16 v[52:55], v[166:169], v[190:193], v[52:55]
	v_mfma_f32_16x16x32_bf16 v[48:51], v[174:177], v[190:193], v[48:51]
	v_mfma_f32_16x16x32_bf16 v[44:47], v[166:169], v[198:201], v[44:47]
	v_mfma_f32_16x16x32_bf16 v[40:43], v[174:177], v[198:201], v[40:43]
	v_mfma_f32_16x16x32_bf16 v[36:39], v[166:169], v[206:209], v[36:39]
	v_mfma_f32_16x16x32_bf16 v[32:35], v[174:177], v[206:209], v[32:35]
	v_mfma_f32_16x16x32_bf16 v[68:71], v[170:173], v[186:189], v[68:71]
	v_mfma_f32_16x16x32_bf16 v[64:67], v[178:181], v[186:189], v[64:67]
	v_mfma_f32_16x16x32_bf16 v[52:55], v[170:173], v[194:197], v[52:55]
	v_mfma_f32_16x16x32_bf16 v[48:51], v[178:181], v[194:197], v[48:51]
	v_mfma_f32_16x16x32_bf16 v[44:47], v[170:173], v[202:205], v[44:47]
	v_mfma_f32_16x16x32_bf16 v[40:43], v[178:181], v[202:205], v[40:43]
	v_mfma_f32_16x16x32_bf16 v[36:39], v[170:173], v[210:213], v[36:39]
	v_mfma_f32_16x16x32_bf16 v[32:35], v[178:181], v[210:213], v[32:35]
	s_setprio 0
	s_waitcnt vmcnt(8)
	s_barrier
	ds_read_b128 v[182:185], v158 offset:49152
	ds_read_b128 v[186:189], v158 offset:50176
	ds_read_b128 v[190:193], v158 offset:51200
	ds_read_b128 v[194:197], v158 offset:52224
	ds_read_b128 v[198:201], v158 offset:53248
	ds_read_b128 v[202:205], v158 offset:54272
	ds_read_b128 v[206:209], v158 offset:55296
	ds_read_b128 v[210:213], v158 offset:56320
	s_add_u32 s60, s20, 0x80
	s_addc_u32 s61, s21, 0
	s_add_u32 vcc_lo, s60, 0x404000
	s_addc_u32 vcc_hi, s61, 0
	s_add_i32 m0, s24, 0x18000
	s_nop 0
	global_load_lds_dwordx4 v138, s[60:61]
	s_add_i32 m0, s24, 0x1a000
	s_nop 0
	global_load_lds_dwordx4 v142, s[60:61]
	s_add_i32 m0, s24, 0x1c000
	s_nop 0
	global_load_lds_dwordx4 v138, vcc
	s_add_i32 m0, s24, 0x1e000
	s_nop 0
	global_load_lds_dwordx4 v142, vcc
	s_waitcnt lgkmcnt(0)
	s_setprio 1
	v_mfma_f32_16x16x32_bf16 v[92:95], v[128:131], v[182:185], v[92:95]
	v_mfma_f32_16x16x32_bf16 v[88:91], v[150:153], v[182:185], v[88:91]
	v_mfma_f32_16x16x32_bf16 v[84:87], v[128:131], v[190:193], v[84:87]
	v_mfma_f32_16x16x32_bf16 v[80:83], v[150:153], v[190:193], v[80:83]
	v_mfma_f32_16x16x32_bf16 v[76:79], v[128:131], v[198:201], v[76:79]
	v_mfma_f32_16x16x32_bf16 v[72:75], v[150:153], v[198:201], v[72:75]
	v_mfma_f32_16x16x32_bf16 v[60:63], v[128:131], v[206:209], v[60:63]
	v_mfma_f32_16x16x32_bf16 v[56:59], v[150:153], v[206:209], v[56:59]
	v_mfma_f32_16x16x32_bf16 v[92:95], v[132:135], v[186:189], v[92:95]
	v_mfma_f32_16x16x32_bf16 v[88:91], v[162:165], v[186:189], v[88:91]
	v_mfma_f32_16x16x32_bf16 v[84:87], v[132:135], v[194:197], v[84:87]
	v_mfma_f32_16x16x32_bf16 v[80:83], v[162:165], v[194:197], v[80:83]
	v_mfma_f32_16x16x32_bf16 v[76:79], v[132:135], v[202:205], v[76:79]
	v_mfma_f32_16x16x32_bf16 v[72:75], v[162:165], v[202:205], v[72:75]
	v_mfma_f32_16x16x32_bf16 v[60:63], v[132:135], v[210:213], v[60:63]
	v_mfma_f32_16x16x32_bf16 v[56:59], v[162:165], v[210:213], v[56:59]
	v_mfma_f32_16x16x32_bf16 v[28:31], v[166:169], v[182:185], v[28:31]
	v_mfma_f32_16x16x32_bf16 v[24:27], v[174:177], v[182:185], v[24:27]
	v_mfma_f32_16x16x32_bf16 v[20:23], v[166:169], v[190:193], v[20:23]
	v_mfma_f32_16x16x32_bf16 v[16:19], v[174:177], v[190:193], v[16:19]
	v_mfma_f32_16x16x32_bf16 v[12:15], v[166:169], v[198:201], v[12:15]
	v_mfma_f32_16x16x32_bf16 v[8:11], v[174:177], v[198:201], v[8:11]
	v_mfma_f32_16x16x32_bf16 v[4:7], v[166:169], v[206:209], v[4:7]
	v_mfma_f32_16x16x32_bf16 v[0:3], v[174:177], v[206:209], v[0:3]
	v_mfma_f32_16x16x32_bf16 v[28:31], v[170:173], v[186:189], v[28:31]
	v_mfma_f32_16x16x32_bf16 v[24:27], v[178:181], v[186:189], v[24:27]
	v_mfma_f32_16x16x32_bf16 v[20:23], v[170:173], v[194:197], v[20:23]
	v_mfma_f32_16x16x32_bf16 v[16:19], v[178:181], v[194:197], v[16:19]
	v_mfma_f32_16x16x32_bf16 v[12:15], v[170:173], v[202:205], v[12:15]
	v_mfma_f32_16x16x32_bf16 v[8:11], v[178:181], v[202:205], v[8:11]
	v_mfma_f32_16x16x32_bf16 v[4:7], v[170:173], v[210:213], v[4:7]
	v_mfma_f32_16x16x32_bf16 v[0:3], v[178:181], v[210:213], v[0:3]
	s_setprio 0
	s_waitcnt vmcnt(6)
	s_barrier
	s_add_i32 s59, s59, 2
	s_add_u32 s18, s18, 0x100
	s_addc_u32 s19, s19, 0
	s_add_u32 s57, s57, 0x100
	s_addc_u32 s58, s58, 0
	s_cmpk_gt_u32 s59, 0xfd
	s_cbranch_scc0 .LBB0_1321
	s_branch .Lf2_exit
; #define PG8_STAGE(bufoff, gbase, voff) do { _Pragma("unroll") for (int _i = 0; _i < 2; ++_i) \
;         __builtin_amdgcn_global_load_lds((const unsigned*)((const char*)(gbase) + (voff)[_i]), (PG8_LAS unsigned*)(lds + (bufoff) + ldsw + _i * 8192), 16, 0, 0); } while (0)
; #define PG8_LDA(dst, b, h) do { _Pragma("unroll") for (int m = 0; m < 4; ++m) _Pragma("unroll") for (int k = 0; k < 2; ++k) dst[m][k] = *(const PG8_LAS bf16x8*)(lds + PG8_SA(b, h) + aoff + m * 2048 + k * 1024); } while (0)
; #define PG8_LDB(dst, b, h) do { _Pragma("unroll") for (int n = 0; n < 2; ++n) _Pragma("unroll") for (int k = 0; k < 2; ++k) dst[n][k] = *(const PG8_LAS bf16x8*)(lds + PG8_SB(b, h) + boff + n * 2048 + k * 1024); } while (0)
; #define PG8_MMA(ai, bj, At, Bt) do { __builtin_amdgcn_s_setprio(1); _Pragma("unroll") for (int m = 0; m < 4; ++m) _Pragma("unroll") for (int n = 0; n < 2; ++n) _Pragma("unroll") for (int k = 0; k < 2; ++k) \
;         acc[ai][bj][m][n] = __builtin_amdgcn_mfma_f32_16x16x32_bf16(Bt[n][k], At[m][k], acc[ai][bj][m][n], 0, 0, 0); __builtin_amdgcn_s_setprio(0); } while (0)
; #define PG8_WAIT_V(n) asm volatile("s_waitcnt vmcnt(" #n ")" ::: "memory")
; #define PG8_WAIT_L(n) asm volatile("s_waitcnt lgkmcnt(" #n ")" ::: "memory")
; #define PG8_BAR __builtin_amdgcn_s_barrier()
; #define PG8_SCHED __builtin_amdgcn_sched_barrier(0)
; template <class Epi, class Sched, bool ALIGN_EPI = false, bool SP2 = false>
; __device__ __forceinline__ void gemm_phase(PG8_LAS unsigned char* lds, const Gemm g, const Sched& S, const Epi& E) {
;     ...
;             PG8_LDB(B0, 0, 0); PG8_LDB(B1, 0, 1); PG8_SCHED; PG8_LDA(At, 0, 0); PG8_STAGE(PG8_SA(1, 1), a1 + hstep, voffA);
;             PG8_WAIT_V(8); PG8_WAIT_L(0); PG8_BAR; PG8_MMA(0, 0, At, B0); PG8_MMA(0, 1, At, B1); PG8_BAR; PG8_SCHED;
;             PG8_LDA(At, 0, 1); PG8_STAGE(PG8_SB(0, 0), b2, voffB); PG8_STAGE(PG8_SB(0, 1), b2 + hstep, voffB); PG8_STAGE(PG8_SA(0, 0), a2, voffA);
;             PG8_WAIT_V(8); PG8_WAIT_L(0); PG8_BAR; PG8_MMA(1, 0, At, B0); PG8_MMA(1, 1, At, B1); PG8_BAR; PG8_SCHED;
.Lf2_h1:
	ds_read_b128 v[128:131], v156
	ds_read_b128 v[132:135], v156 offset:1024
	ds_read_b128 v[150:153], v156 offset:2048
	ds_read_b128 v[162:165], v156 offset:3072
	ds_read_b128 v[166:169], v157
	ds_read_b128 v[170:173], v157 offset:1024
	ds_read_b128 v[174:177], v157 offset:2048
	ds_read_b128 v[178:181], v157 offset:3072
	s_add_u32 s20, s18, 0xffbfc080
	s_addc_u32 s21, s19, -1
	s_cmpk_eq_i32 s59, 0xfc
	s_cselect_b32 s23, s7, s21
	s_cselect_b32 s22, s6, s20
	s_cselect_b32 s21, s17, s58
	s_cselect_b32 s20, s16, s57
	ds_read_b128 v[182:185], v158
	ds_read_b128 v[186:189], v158 offset:1024
	ds_read_b128 v[190:193], v158 offset:2048
	ds_read_b128 v[194:197], v158 offset:3072
	ds_read_b128 v[198:201], v158 offset:4096
	ds_read_b128 v[202:205], v158 offset:5120
	ds_read_b128 v[206:209], v158 offset:6144
	ds_read_b128 v[210:213], v158 offset:7168
	s_add_u32 s60, s18, 0xffbfc000
	s_addc_u32 s61, s19, -1
	s_add_i32 m0, s24, 0x8000
	s_nop 0
	global_load_lds_dwordx4 v136, s[60:61]
	s_add_i32 m0, s24, 0xa000
	s_nop 0
	global_load_lds_dwordx4 v140, s[60:61]
	s_add_i32 m0, s24, 0xc000
	s_nop 0
	global_load_lds_dwordx4 v136, s[18:19]
	s_add_i32 m0, s24, 0xe000
	s_nop 0
	global_load_lds_dwordx4 v140, s[18:19]
	s_sleep 2
	s_waitcnt lgkmcnt(0)
	s_waitcnt vmcnt(8)
	s_barrier
	s_setprio 2
	v_mfma_f32_16x16x32_bf16 v[124:127], v[128:131], v[182:185], v[124:127]
	v_mfma_f32_16x16x32_bf16 v[120:123], v[150:153], v[182:185], v[120:123]
	v_mfma_f32_16x16x32_bf16 v[116:119], v[128:131], v[190:193], v[116:119]
	v_mfma_f32_16x16x32_bf16 v[112:115], v[150:153], v[190:193], v[112:115]
	v_mfma_f32_16x16x32_bf16 v[108:111], v[128:131], v[198:201], v[108:111]
	v_mfma_f32_16x16x32_bf16 v[104:107], v[150:153], v[198:201], v[104:107]
	v_mfma_f32_16x16x32_bf16 v[100:103], v[128:131], v[206:209], v[100:103]
	v_mfma_f32_16x16x32_bf16 v[96:99], v[150:153], v[206:209], v[96:99]
	v_mfma_f32_16x16x32_bf16 v[124:127], v[132:135], v[186:189], v[124:127]
	v_mfma_f32_16x16x32_bf16 v[120:123], v[162:165], v[186:189], v[120:123]
	v_mfma_f32_16x16x32_bf16 v[116:119], v[132:135], v[194:197], v[116:119]
	v_mfma_f32_16x16x32_bf16 v[112:115], v[162:165], v[194:197], v[112:115]
	v_mfma_f32_16x16x32_bf16 v[108:111], v[132:135], v[202:205], v[108:111]
	v_mfma_f32_16x16x32_bf16 v[104:107], v[162:165], v[202:205], v[104:107]
	v_mfma_f32_16x16x32_bf16 v[100:103], v[132:135], v[210:213], v[100:103]
	v_mfma_f32_16x16x32_bf16 v[96:99], v[162:165], v[210:213], v[96:99]
	v_mfma_f32_16x16x32_bf16 v[68:71], v[166:169], v[182:185], v[68:71]
	v_mfma_f32_16x16x32_bf16 v[64:67], v[174:177], v[182:185], v[64:67]
	v_mfma_f32_16x16x32_bf16 v[52:55], v[166:169], v[190:193], v[52:55]
	v_mfma_f32_16x16x32_bf16 v[48:51], v[174:177], v[190:193], v[48:51]
	v_mfma_f32_16x16x32_bf16 v[44:47], v[166:169], v[198:201], v[44:47]
	v_mfma_f32_16x16x32_bf16 v[40:43], v[174:177], v[198:201], v[40:43]
	v_mfma_f32_16x16x32_bf16 v[36:39], v[166:169], v[206:209], v[36:39]
	v_mfma_f32_16x16x32_bf16 v[32:35], v[174:177], v[206:209], v[32:35]
	v_mfma_f32_16x16x32_bf16 v[68:71], v[170:173], v[186:189], v[68:71]
	v_mfma_f32_16x16x32_bf16 v[64:67], v[178:181], v[186:189], v[64:67]
	v_mfma_f32_16x16x32_bf16 v[52:55], v[170:173], v[194:197], v[52:55]
	v_mfma_f32_16x16x32_bf16 v[48:51], v[178:181], v[194:197], v[48:51]
	v_mfma_f32_16x16x32_bf16 v[44:47], v[170:173], v[202:205], v[44:47]
	v_mfma_f32_16x16x32_bf16 v[40:43], v[178:181], v[202:205], v[40:43]
	v_mfma_f32_16x16x32_bf16 v[36:39], v[170:173], v[210:213], v[36:39]
	v_mfma_f32_16x16x32_bf16 v[32:35], v[178:181], v[210:213], v[32:35]
	s_setprio 0
	ds_read_b128 v[182:185], v158 offset:16384
	ds_read_b128 v[186:189], v158 offset:17408
	ds_read_b128 v[190:193], v158 offset:18432
	ds_read_b128 v[194:197], v158 offset:19456
	ds_read_b128 v[198:201], v158 offset:20480
	ds_read_b128 v[202:205], v158 offset:21504
	ds_read_b128 v[206:209], v158 offset:22528
	ds_read_b128 v[210:213], v158 offset:23552
	s_add_u32 vcc_lo, s20, 0x404000
	s_addc_u32 vcc_hi, s21, 0
	s_add_i32 m0, s24, 0x10000
	s_nop 0
	global_load_lds_dwordx4 v138, s[20:21]
	s_add_i32 m0, s24, 0x12000
	s_nop 0
	global_load_lds_dwordx4 v142, s[20:21]
	s_add_i32 m0, s24, 0x14000
	s_nop 0
	global_load_lds_dwordx4 v138, vcc
	s_add_i32 m0, s24, 0x16000
	s_nop 0
	global_load_lds_dwordx4 v142, vcc
	s_sleep 2
	s_waitcnt lgkmcnt(0)
	s_waitcnt vmcnt(6)
	s_barrier
; #define PG8_STAGE(bufoff, gbase, voff) do { _Pragma("unroll") for (int _i = 0; _i < 2; ++_i) \
;         __builtin_amdgcn_global_load_lds((const unsigned*)((const char*)(gbase) + (voff)[_i]), (PG8_LAS unsigned*)(lds + (bufoff) + ldsw + _i * 8192), 16, 0, 0); } while (0)
; #define PG8_LDA(dst, b, h) do { _Pragma("unroll") for (int m = 0; m < 4; ++m) _Pragma("unroll") for (int k = 0; k < 2; ++k) dst[m][k] = *(const PG8_LAS bf16x8*)(lds + PG8_SA(b, h) + aoff + m * 2048 + k * 1024); } while (0)
; #define PG8_LDB(dst, b, h) do { _Pragma("unroll") for (int n = 0; n < 2; ++n) _Pragma("unroll") for (int k = 0; k < 2; ++k) dst[n][k] = *(const PG8_LAS bf16x8*)(lds + PG8_SB(b, h) + boff + n * 2048 + k * 1024); } while (0)
; #define PG8_MMA(ai, bj, At, Bt) do { __builtin_amdgcn_s_setprio(1); _Pragma("unroll") for (int m = 0; m < 4; ++m) _Pragma("unroll") for (int n = 0; n < 2; ++n) _Pragma("unroll") for (int k = 0; k < 2; ++k) \
;         acc[ai][bj][m][n] = __builtin_amdgcn_mfma_f32_16x16x32_bf16(Bt[n][k], At[m][k], acc[ai][bj][m][n], 0, 0, 0); __builtin_amdgcn_s_setprio(0); } while (0)
; #define PG8_WAIT_V(n) asm volatile("s_waitcnt vmcnt(" #n ")" ::: "memory")
; #define PG8_WAIT_L(n) asm volatile("s_waitcnt lgkmcnt(" #n ")" ::: "memory")
; #define PG8_BAR __builtin_amdgcn_s_barrier()
; #define PG8_SCHED __builtin_amdgcn_sched_barrier(0)
; template <class Epi, class Sched, bool ALIGN_EPI = false, bool SP2 = false>
; __device__ __forceinline__ void gemm_phase(PG8_LAS unsigned char* lds, const Gemm g, const Sched& S, const Epi& E) {
;     ...
;             PG8_WAIT_V(8); PG8_WAIT_L(0); PG8_BAR; PG8_MMA(1, 0, At, B0); PG8_MMA(1, 1, At, B1); PG8_BAR; PG8_SCHED;
;             PG8_LDB(B0, 1, 0); PG8_LDB(B1, 1, 1); PG8_SCHED; PG8_LDA(At, 1, 0); PG8_STAGE(PG8_SA(0, 1), a2 + hstep, voffA);
;             PG8_WAIT_V(8); PG8_WAIT_L(0); PG8_BAR; PG8_MMA(0, 0, At, B0); PG8_MMA(0, 1, At, B1); PG8_BAR; PG8_SCHED;
;             PG8_LDA(At, 1, 1); PG8_STAGE(PG8_SB(1, 0), b3, voffB); PG8_STAGE(PG8_SB(1, 1), b3 + hstep, voffB); PG8_STAGE(PG8_SA(1, 0), a3, voffA);
;             PG8_WAIT_V(8); PG8_WAIT_L(0); PG8_BAR; PG8_MMA(1, 0, At, B0); PG8_MMA(1, 1, At, B1); PG8_BAR; PG8_SCHED;
	s_setprio 2
	v_mfma_f32_16x16x32_bf16 v[92:95], v[128:131], v[182:185], v[92:95]
	v_mfma_f32_16x16x32_bf16 v[88:91], v[150:153], v[182:185], v[88:91]
	v_mfma_f32_16x16x32_bf16 v[84:87], v[128:131], v[190:193], v[84:87]
	v_mfma_f32_16x16x32_bf16 v[80:83], v[150:153], v[190:193], v[80:83]
	v_mfma_f32_16x16x32_bf16 v[76:79], v[128:131], v[198:201], v[76:79]
	v_mfma_f32_16x16x32_bf16 v[72:75], v[150:153], v[198:201], v[72:75]
	v_mfma_f32_16x16x32_bf16 v[60:63], v[128:131], v[206:209], v[60:63]
	v_mfma_f32_16x16x32_bf16 v[56:59], v[150:153], v[206:209], v[56:59]
	v_mfma_f32_16x16x32_bf16 v[92:95], v[132:135], v[186:189], v[92:95]
	v_mfma_f32_16x16x32_bf16 v[88:91], v[162:165], v[186:189], v[88:91]
	v_mfma_f32_16x16x32_bf16 v[84:87], v[132:135], v[194:197], v[84:87]
	v_mfma_f32_16x16x32_bf16 v[80:83], v[162:165], v[194:197], v[80:83]
	v_mfma_f32_16x16x32_bf16 v[76:79], v[132:135], v[202:205], v[76:79]
	v_mfma_f32_16x16x32_bf16 v[72:75], v[162:165], v[202:205], v[72:75]
	v_mfma_f32_16x16x32_bf16 v[60:63], v[132:135], v[210:213], v[60:63]
	v_mfma_f32_16x16x32_bf16 v[56:59], v[162:165], v[210:213], v[56:59]
	v_mfma_f32_16x16x32_bf16 v[28:31], v[166:169], v[182:185], v[28:31]
	v_mfma_f32_16x16x32_bf16 v[24:27], v[174:177], v[182:185], v[24:27]
	v_mfma_f32_16x16x32_bf16 v[20:23], v[166:169], v[190:193], v[20:23]
	v_mfma_f32_16x16x32_bf16 v[16:19], v[174:177], v[190:193], v[16:19]
	v_mfma_f32_16x16x32_bf16 v[12:15], v[166:169], v[198:201], v[12:15]
	v_mfma_f32_16x16x32_bf16 v[8:11], v[174:177], v[198:201], v[8:11]
	v_mfma_f32_16x16x32_bf16 v[4:7], v[166:169], v[206:209], v[4:7]
	v_mfma_f32_16x16x32_bf16 v[0:3], v[174:177], v[206:209], v[0:3]
	v_mfma_f32_16x16x32_bf16 v[28:31], v[170:173], v[186:189], v[28:31]
	v_mfma_f32_16x16x32_bf16 v[24:27], v[178:181], v[186:189], v[24:27]
	v_mfma_f32_16x16x32_bf16 v[20:23], v[170:173], v[194:197], v[20:23]
	v_mfma_f32_16x16x32_bf16 v[16:19], v[178:181], v[194:197], v[16:19]
	v_mfma_f32_16x16x32_bf16 v[12:15], v[170:173], v[202:205], v[12:15]
	v_mfma_f32_16x16x32_bf16 v[8:11], v[178:181], v[202:205], v[8:11]
	v_mfma_f32_16x16x32_bf16 v[4:7], v[170:173], v[210:213], v[4:7]
	v_mfma_f32_16x16x32_bf16 v[0:3], v[178:181], v[210:213], v[0:3]
	s_setprio 0
	ds_read_b128 v[128:131], v159
	ds_read_b128 v[132:135], v159 offset:1024
	ds_read_b128 v[150:153], v159 offset:2048
	ds_read_b128 v[162:165], v159 offset:3072
	ds_read_b128 v[166:169], v160
	ds_read_b128 v[170:173], v160 offset:1024
	ds_read_b128 v[174:177], v160 offset:2048
	ds_read_b128 v[178:181], v160 offset:3072
	ds_read_b128 v[182:185], v158 offset:32768
	ds_read_b128 v[186:189], v158 offset:33792
	ds_read_b128 v[190:193], v158 offset:34816
	ds_read_b128 v[194:197], v158 offset:35840
	ds_read_b128 v[198:201], v158 offset:36864
	ds_read_b128 v[202:205], v158 offset:37888
	ds_read_b128 v[206:209], v158 offset:38912
	ds_read_b128 v[210:213], v158 offset:39936
	s_add_u32 vcc_lo, s22, 0x404000
	s_addc_u32 vcc_hi, s23, 0
	s_mov_b32 m0, s24
	s_nop 0
	global_load_lds_dwordx4 v136, s[22:23]
	s_add_i32 m0, s24, 0x2000
	s_nop 0
	global_load_lds_dwordx4 v140, s[22:23]
	s_add_i32 m0, s24, 0x4000
	s_nop 0
	global_load_lds_dwordx4 v136, vcc
	s_add_i32 m0, s24, 0x6000
	s_nop 0
	global_load_lds_dwordx4 v140, vcc
	s_sleep 2
	s_waitcnt lgkmcnt(0)
	s_waitcnt vmcnt(8)
	s_barrier
	s_setprio 2
	v_mfma_f32_16x16x32_bf16 v[124:127], v[128:131], v[182:185], v[124:127]
	v_mfma_f32_16x16x32_bf16 v[120:123], v[150:153], v[182:185], v[120:123]
	v_mfma_f32_16x16x32_bf16 v[116:119], v[128:131], v[190:193], v[116:119]
	v_mfma_f32_16x16x32_bf16 v[112:115], v[150:153], v[190:193], v[112:115]
	v_mfma_f32_16x16x32_bf16 v[108:111], v[128:131], v[198:201], v[108:111]
	v_mfma_f32_16x16x32_bf16 v[104:107], v[150:153], v[198:201], v[104:107]
	v_mfma_f32_16x16x32_bf16 v[100:103], v[128:131], v[206:209], v[100:103]
	v_mfma_f32_16x16x32_bf16 v[96:99], v[150:153], v[206:209], v[96:99]
	v_mfma_f32_16x16x32_bf16 v[124:127], v[132:135], v[186:189], v[124:127]
	v_mfma_f32_16x16x32_bf16 v[120:123], v[162:165], v[186:189], v[120:123]
	v_mfma_f32_16x16x32_bf16 v[116:119], v[132:135], v[194:197], v[116:119]
	v_mfma_f32_16x16x32_bf16 v[112:115], v[162:165], v[194:197], v[112:115]
	v_mfma_f32_16x16x32_bf16 v[108:111], v[132:135], v[202:205], v[108:111]
	v_mfma_f32_16x16x32_bf16 v[104:107], v[162:165], v[202:205], v[104:107]
	v_mfma_f32_16x16x32_bf16 v[100:103], v[132:135], v[210:213], v[100:103]
	v_mfma_f32_16x16x32_bf16 v[96:99], v[162:165], v[210:213], v[96:99]
	v_mfma_f32_16x16x32_bf16 v[68:71], v[166:169], v[182:185], v[68:71]
	v_mfma_f32_16x16x32_bf16 v[64:67], v[174:177], v[182:185], v[64:67]
	v_mfma_f32_16x16x32_bf16 v[52:55], v[166:169], v[190:193], v[52:55]
	v_mfma_f32_16x16x32_bf16 v[48:51], v[174:177], v[190:193], v[48:51]
	v_mfma_f32_16x16x32_bf16 v[44:47], v[166:169], v[198:201], v[44:47]
	v_mfma_f32_16x16x32_bf16 v[40:43], v[174:177], v[198:201], v[40:43]
	v_mfma_f32_16x16x32_bf16 v[36:39], v[166:169], v[206:209], v[36:39]
	v_mfma_f32_16x16x32_bf16 v[32:35], v[174:177], v[206:209], v[32:35]
	v_mfma_f32_16x16x32_bf16 v[68:71], v[170:173], v[186:189], v[68:71]
	v_mfma_f32_16x16x32_bf16 v[64:67], v[178:181], v[186:189], v[64:67]
	v_mfma_f32_16x16x32_bf16 v[52:55], v[170:173], v[194:197], v[52:55]
	v_mfma_f32_16x16x32_bf16 v[48:51], v[178:181], v[194:197], v[48:51]
	v_mfma_f32_16x16x32_bf16 v[44:47], v[170:173], v[202:205], v[44:47]
	v_mfma_f32_16x16x32_bf16 v[40:43], v[178:181], v[202:205], v[40:43]
	v_mfma_f32_16x16x32_bf16 v[36:39], v[170:173], v[210:213], v[36:39]
	v_mfma_f32_16x16x32_bf16 v[32:35], v[178:181], v[210:213], v[32:35]
	s_setprio 0
	ds_read_b128 v[182:185], v158 offset:49152
	ds_read_b128 v[186:189], v158 offset:50176
	ds_read_b128 v[190:193], v158 offset:51200
	ds_read_b128 v[194:197], v158 offset:52224
	ds_read_b128 v[198:201], v158 offset:53248
	ds_read_b128 v[202:205], v158 offset:54272
	ds_read_b128 v[206:209], v158 offset:55296
	ds_read_b128 v[210:213], v158 offset:56320
	s_add_u32 s60, s20, 0x80
	s_addc_u32 s61, s21, 0
	s_add_u32 vcc_lo, s60, 0x404000
	s_addc_u32 vcc_hi, s61, 0
	s_add_i32 m0, s24, 0x18000
	s_nop 0
	global_load_lds_dwordx4 v138, s[60:61]
	s_add_i32 m0, s24, 0x1a000
	s_nop 0
	global_load_lds_dwordx4 v142, s[60:61]
	s_add_i32 m0, s24, 0x1c000
	s_nop 0
	global_load_lds_dwordx4 v138, vcc
	s_add_i32 m0, s24, 0x1e000
	s_nop 0
	global_load_lds_dwordx4 v142, vcc
	s_sleep 2
	s_waitcnt lgkmcnt(0)
	s_waitcnt vmcnt(6)
	s_barrier
; #define PG8_WAIT_V(n) asm volatile("s_waitcnt vmcnt(" #n ")" ::: "memory")
;     __device__ __forceinline__ void operator()(const f32x4 (&acc)[2][2][4][2], const Unit& u, int wr, int wc, int fr, int fq) const {
;         const int cin = wc * 32 + 8 * fq, col0 = u.pn * BM + cin, ct0 = u.ui * BM + cin;
;         const size_t off0 = (size_t)(u.pm * BM + wr * 64 + fr) * 4096 + col0;
; #pragma unroll
;         for (int bj = 0; bj < 2; ++bj) {
;             const f32x4 g0 = lds_ld4(gvt + ct0 + bj * HALF), g1 = lds_ld4(gvt + ct0 + bj * HALF + 4);
; #pragma unroll
;             for (int ai = 0; ai < 2; ++ai)
; #pragma unroll
;                 for (int m = 0; m < 4; ++m) { const size_t off = off0 + (size_t)(ai * HALF + m * 16) * 4096 + bj * HALF;
;                     const u32x4 b = *(const u32x4*)(xb + off);
;                     const f32x4 v0 = (f32x4){__uint_as_float(b.x << 16), __uint_as_float(b.x & 0xffff0000u), __uint_as_float(b.y << 16), __uint_as_float(b.y & 0xffff0000u)} + g0 * acc[ai][bj][m][0];
;                     const f32x4 v1 = (f32x4){__uint_as_float(b.z << 16), __uint_as_float(b.z & 0xffff0000u), __uint_as_float(b.w << 16), __uint_as_float(b.w & 0xffff0000u)} + g1 * acc[ai][bj][m][1];
;                     u32x4 w; w.x = cvt_pk_bf16(v0.x, v0.y); w.y = cvt_pk_bf16(v0.z, v0.w); w.z = cvt_pk_bf16(v1.x, v1.y); w.w = cvt_pk_bf16(v1.z, v1.w);
;                     *(u32x4*)(xb + off) = w; }
; template <class Epi, class Sched, bool ALIGN_EPI = false, bool SP2 = false>
; __device__ __forceinline__ void gemm_phase(PG8_LAS unsigned char* lds, const Gemm g, const Sched& S, const Epi& E) {
;     ...
;             PG8_WAIT_V(8); PG8_WAIT_L(0); PG8_BAR; PG8_MMA(1, 0, At, B0); PG8_MMA(1, 1, At, B1); PG8_BAR; PG8_SCHED;
;             } else {
;             PG8_LDB(B0, 0, 0); PG8_SCHED; PG8_LDA(At, 0, 0); PG8_STAGE(PG8_SA(1, 1), a1 + hstep, voffA);
;             PG8_WAIT_L(8); PG8_BAR; PG8_WAIT_L(0); PG8_MMA(0, 0, At, B0); PG8_BAR; PG8_SCHED;
;             PG8_LDB(B1, 0, 1); PG8_STAGE(PG8_SB(0, 0), b2, voffB);
;             PG8_BAR; PG8_WAIT_L(0); PG8_MMA(0, 1, At, B1); PG8_BAR;
;             PG8_LDA(At, 0, 1); PG8_STAGE(PG8_SA(0, 0), a2, voffA);
;             PG8_BAR; PG8_WAIT_L(0); PG8_MMA(1, 0, At, B0); PG8_BAR; PG8_SCHED;
;             PG8_STAGE(PG8_SB(0, 1), b2 + hstep, voffB);
;             PG8_WAIT_V(6); PG8_BAR; PG8_MMA(1, 1, At, B1); PG8_BAR;
	s_setprio 2
	v_mfma_f32_16x16x32_bf16 v[92:95], v[128:131], v[182:185], v[92:95]
	v_mfma_f32_16x16x32_bf16 v[88:91], v[150:153], v[182:185], v[88:91]
	v_mfma_f32_16x16x32_bf16 v[84:87], v[128:131], v[190:193], v[84:87]
	v_mfma_f32_16x16x32_bf16 v[80:83], v[150:153], v[190:193], v[80:83]
	v_mfma_f32_16x16x32_bf16 v[76:79], v[128:131], v[198:201], v[76:79]
	v_mfma_f32_16x16x32_bf16 v[72:75], v[150:153], v[198:201], v[72:75]
	v_mfma_f32_16x16x32_bf16 v[60:63], v[128:131], v[206:209], v[60:63]
	v_mfma_f32_16x16x32_bf16 v[56:59], v[150:153], v[206:209], v[56:59]
	v_mfma_f32_16x16x32_bf16 v[92:95], v[132:135], v[186:189], v[92:95]
	v_mfma_f32_16x16x32_bf16 v[88:91], v[162:165], v[186:189], v[88:91]
	v_mfma_f32_16x16x32_bf16 v[84:87], v[132:135], v[194:197], v[84:87]
	v_mfma_f32_16x16x32_bf16 v[80:83], v[162:165], v[194:197], v[80:83]
	v_mfma_f32_16x16x32_bf16 v[76:79], v[132:135], v[202:205], v[76:79]
	v_mfma_f32_16x16x32_bf16 v[72:75], v[162:165], v[202:205], v[72:75]
	v_mfma_f32_16x16x32_bf16 v[60:63], v[132:135], v[210:213], v[60:63]
	v_mfma_f32_16x16x32_bf16 v[56:59], v[162:165], v[210:213], v[56:59]
	v_mfma_f32_16x16x32_bf16 v[28:31], v[166:169], v[182:185], v[28:31]
	v_mfma_f32_16x16x32_bf16 v[24:27], v[174:177], v[182:185], v[24:27]
	v_mfma_f32_16x16x32_bf16 v[20:23], v[166:169], v[190:193], v[20:23]
	v_mfma_f32_16x16x32_bf16 v[16:19], v[174:177], v[190:193], v[16:19]
	v_mfma_f32_16x16x32_bf16 v[12:15], v[166:169], v[198:201], v[12:15]
	v_mfma_f32_16x16x32_bf16 v[8:11], v[174:177], v[198:201], v[8:11]
	v_mfma_f32_16x16x32_bf16 v[4:7], v[166:169], v[206:209], v[4:7]
	v_mfma_f32_16x16x32_bf16 v[0:3], v[174:177], v[206:209], v[0:3]
	v_mfma_f32_16x16x32_bf16 v[28:31], v[170:173], v[186:189], v[28:31]
	v_mfma_f32_16x16x32_bf16 v[24:27], v[178:181], v[186:189], v[24:27]
	v_mfma_f32_16x16x32_bf16 v[20:23], v[170:173], v[194:197], v[20:23]
	v_mfma_f32_16x16x32_bf16 v[16:19], v[178:181], v[194:197], v[16:19]
	v_mfma_f32_16x16x32_bf16 v[12:15], v[170:173], v[202:205], v[12:15]
	v_mfma_f32_16x16x32_bf16 v[8:11], v[178:181], v[202:205], v[8:11]
	v_mfma_f32_16x16x32_bf16 v[4:7], v[170:173], v[210:213], v[4:7]
	v_mfma_f32_16x16x32_bf16 v[0:3], v[178:181], v[210:213], v[0:3]
	s_setprio 0
	s_add_i32 s59, s59, 2
	s_add_u32 s18, s18, 0x100
	s_addc_u32 s19, s19, 0
	s_add_u32 s57, s57, 0x100
	s_addc_u32 s58, s58, 0
	s_cmpk_gt_u32 s59, 0xfd
	s_cbranch_scc0 .Lf2_h1
.Lf2_exit:
	s_and_b64 vcc, exec, s[14:15]
	s_cbranch_vccz .LBB0_1324
.LBB0_1324:
	v_lshl_add_u32 v150, s56, 8, v154
	v_ashrrev_i32_e32 v151, 31, v150
	v_lshl_add_u32 v161, s55, 10, v155
	ds_read_b128 v[128:131], v161
	s_waitcnt lgkmcnt(0)
	v_add_u32_e32 v132, 16, v161
	v_lshlrev_b64 v[150:151], 13, v[150:151]
	ds_read_b128 v[132:135], v132
	s_waitcnt lgkmcnt(0)
	v_lshl_add_u64 v[150:151], v[144:145], 0, v[150:151]
	global_load_dwordx4 v[162:165], v[150:151], off
	v_add_co_u32_e32 v152, vcc, s41, v150
	s_cmp_eq_u32 s55, 3
	s_nop 0
	v_addc_co_u32_e32 v153, vcc, 0, v151, vcc
	s_mov_b64 s[18:19], -1
	s_waitcnt vmcnt(0)
	v_lshlrev_b32_e32 v166, 16, v162
	v_and_b32_e32 v167, 0xffff0000, v162
	v_lshlrev_b32_e32 v162, 16, v163
	v_and_b32_e32 v163, 0xffff0000, v163
	v_lshlrev_b32_e32 v168, 16, v164
	v_and_b32_e32 v169, 0xffff0000, v164
	v_lshlrev_b32_e32 v164, 16, v165
	v_and_b32_e32 v165, 0xffff0000, v165
	v_pk_fma_f32 v[126:127], v[126:127], v[130:131], v[162:163]
	v_pk_fma_f32 v[124:125], v[124:125], v[128:129], v[166:167]
	v_pk_fma_f32 v[162:163], v[122:123], v[134:135], v[164:165]
	v_pk_fma_f32 v[120:121], v[120:121], v[132:133], v[168:169]
	v_cvt_pk_bf16_f32 v122, v124, v125
	v_cvt_pk_bf16_f32 v123, v126, v127
	s_nop 0
	v_cvt_pk_bf16_f32 v124, v120, v121
	v_cvt_pk_bf16_f32 v125, v162, v163
	global_load_dwordx4 v[162:165], v[152:153], off
	v_add_co_u32_e32 v120, vcc, s42, v150
	global_store_dwordx4 v[150:151], v[122:125], off
	s_nop 0
	v_addc_co_u32_e32 v121, vcc, 0, v151, vcc
	s_waitcnt vmcnt(1)
	v_lshlrev_b32_e32 v122, 16, v162
	v_and_b32_e32 v123, 0xffff0000, v162
	v_lshlrev_b32_e32 v124, 16, v163
	v_and_b32_e32 v125, 0xffff0000, v163
	v_lshlrev_b32_e32 v162, 16, v165
	v_and_b32_e32 v163, 0xffff0000, v165
	v_lshlrev_b32_e32 v126, 16, v164
	v_and_b32_e32 v127, 0xffff0000, v164
	v_pk_fma_f32 v[116:117], v[116:117], v[128:129], v[122:123]
	v_pk_fma_f32 v[122:123], v[114:115], v[134:135], v[162:163]
	v_pk_fma_f32 v[118:119], v[118:119], v[130:131], v[124:125]
	v_pk_fma_f32 v[112:113], v[112:113], v[132:133], v[126:127]
	v_cvt_pk_bf16_f32 v114, v116, v117
	v_cvt_pk_bf16_f32 v115, v118, v119
	s_nop 0
	v_cvt_pk_bf16_f32 v116, v112, v113
	v_cvt_pk_bf16_f32 v117, v122, v123
	global_load_dwordx4 v[122:125], v[120:121], off
	v_add_co_u32_e32 v112, vcc, s43, v150
	global_store_dwordx4 v[152:153], v[114:117], off
	s_nop 0
	v_addc_co_u32_e32 v113, vcc, 0, v151, vcc
	s_waitcnt vmcnt(1)
	v_lshlrev_b32_e32 v114, 16, v122
	v_and_b32_e32 v115, 0xffff0000, v122
	v_lshlrev_b32_e32 v116, 16, v123
	v_and_b32_e32 v117, 0xffff0000, v123
	v_lshlrev_b32_e32 v122, 16, v125
	v_and_b32_e32 v123, 0xffff0000, v125
	v_lshlrev_b32_e32 v118, 16, v124
	v_and_b32_e32 v119, 0xffff0000, v124
	v_pk_fma_f32 v[108:109], v[108:109], v[128:129], v[114:115]
	v_pk_fma_f32 v[114:115], v[106:107], v[134:135], v[122:123]
	v_pk_fma_f32 v[110:111], v[110:111], v[130:131], v[116:117]
	v_pk_fma_f32 v[104:105], v[104:105], v[132:133], v[118:119]
	v_cvt_pk_bf16_f32 v106, v108, v109
	v_cvt_pk_bf16_f32 v107, v110, v111
	s_nop 0
	v_cvt_pk_bf16_f32 v108, v104, v105
	v_cvt_pk_bf16_f32 v109, v114, v115
	global_load_dwordx4 v[114:117], v[112:113], off
	v_add_co_u32_e32 v104, vcc, s46, v150
	global_store_dwordx4 v[120:121], v[106:109], off
	s_nop 0
	v_addc_co_u32_e32 v105, vcc, 0, v151, vcc
	s_waitcnt vmcnt(1)
; __device__ __forceinline__ unsigned cvt_pk_bf16(float lo, float hi) { unsigned r; asm volatile("v_cvt_pk_bf16_f32 %0, %1, %2" : "=v"(r) : "v"(lo), "v"(hi)); return r; }
; __device__ __forceinline__ f32x4 lds_ld4(const PG8_LAS float* p) { f32x4 v; asm volatile("ds_read_b128 %0, %1\n\ts_waitcnt lgkmcnt(0)" : "=v"(v) : "v"((unsigned)(size_t)p) : "memory"); return v; }
;     __device__ __forceinline__ void operator()(const f32x4 (&acc)[2][2][4][2], const Unit& u, int wr, int wc, int fr, int fq) const {
;     ...
;             const f32x4 g0 = lds_ld4(gvt + ct0 + bj * HALF), g1 = lds_ld4(gvt + ct0 + bj * HALF + 4);
; #pragma unroll
;             for (int ai = 0; ai < 2; ++ai)
; #pragma unroll
;                 for (int m = 0; m < 4; ++m) { const size_t off = off0 + (size_t)(ai * HALF + m * 16) * 4096 + bj * HALF;
;                     const u32x4 b = *(const u32x4*)(xb + off);
;                     const f32x4 v0 = (f32x4){__uint_as_float(b.x << 16), __uint_as_float(b.x & 0xffff0000u), __uint_as_float(b.y << 16), __uint_as_float(b.y & 0xffff0000u)} + g0 * acc[ai][bj][m][0];
;                     const f32x4 v1 = (f32x4){__uint_as_float(b.z << 16), __uint_as_float(b.z & 0xffff0000u), __uint_as_float(b.w << 16), __uint_as_float(b.w & 0xffff0000u)} + g1 * acc[ai][bj][m][1];
;                     u32x4 w; w.x = cvt_pk_bf16(v0.x, v0.y); w.y = cvt_pk_bf16(v0.z, v0.w); w.z = cvt_pk_bf16(v1.x, v1.y); w.w = cvt_pk_bf16(v1.z, v1.w);
;                     *(u32x4*)(xb + off) = w; }
	v_lshlrev_b32_e32 v106, 16, v114
	v_and_b32_e32 v107, 0xffff0000, v114
	v_lshlrev_b32_e32 v108, 16, v115
	v_and_b32_e32 v109, 0xffff0000, v115
	v_lshlrev_b32_e32 v114, 16, v117
	v_and_b32_e32 v115, 0xffff0000, v117
	v_lshlrev_b32_e32 v110, 16, v116
	v_and_b32_e32 v111, 0xffff0000, v116
	v_pk_fma_f32 v[100:101], v[100:101], v[128:129], v[106:107]
	v_pk_fma_f32 v[106:107], v[98:99], v[134:135], v[114:115]
	v_pk_fma_f32 v[102:103], v[102:103], v[130:131], v[108:109]
	v_pk_fma_f32 v[96:97], v[96:97], v[132:133], v[110:111]
	v_cvt_pk_bf16_f32 v98, v100, v101
	v_cvt_pk_bf16_f32 v99, v102, v103
	s_nop 0
	v_cvt_pk_bf16_f32 v100, v96, v97
	v_cvt_pk_bf16_f32 v101, v106, v107
	global_load_dwordx4 v[106:109], v[104:105], off
	v_add_co_u32_e32 v96, vcc, s47, v150
	global_store_dwordx4 v[112:113], v[98:101], off
	s_nop 0
	v_addc_co_u32_e32 v97, vcc, 0, v151, vcc
	s_waitcnt vmcnt(1)
	v_lshlrev_b32_e32 v98, 16, v106
	v_and_b32_e32 v99, 0xffff0000, v106
	v_lshlrev_b32_e32 v100, 16, v107
	v_and_b32_e32 v101, 0xffff0000, v107
	v_lshlrev_b32_e32 v106, 16, v109
	v_and_b32_e32 v107, 0xffff0000, v109
	v_lshlrev_b32_e32 v102, 16, v108
	v_and_b32_e32 v103, 0xffff0000, v108
	v_pk_fma_f32 v[92:93], v[92:93], v[128:129], v[98:99]
	v_pk_fma_f32 v[98:99], v[90:91], v[134:135], v[106:107]
	v_pk_fma_f32 v[94:95], v[94:95], v[130:131], v[100:101]
	v_pk_fma_f32 v[88:89], v[88:89], v[132:133], v[102:103]
	v_cvt_pk_bf16_f32 v90, v92, v93
	v_cvt_pk_bf16_f32 v91, v94, v95
	s_nop 0
	v_cvt_pk_bf16_f32 v92, v88, v89
	v_cvt_pk_bf16_f32 v93, v98, v99
	global_load_dwordx4 v[98:101], v[96:97], off
	v_add_co_u32_e32 v88, vcc, s48, v150
	global_store_dwordx4 v[104:105], v[90:93], off
	s_nop 0
	v_addc_co_u32_e32 v89, vcc, 0, v151, vcc
	s_waitcnt vmcnt(1)
	v_lshlrev_b32_e32 v90, 16, v98
	v_and_b32_e32 v91, 0xffff0000, v98
	v_lshlrev_b32_e32 v92, 16, v99
	v_and_b32_e32 v93, 0xffff0000, v99
	v_lshlrev_b32_e32 v98, 16, v101
	v_and_b32_e32 v99, 0xffff0000, v101
	v_lshlrev_b32_e32 v94, 16, v100
	v_and_b32_e32 v95, 0xffff0000, v100
	v_pk_fma_f32 v[84:85], v[84:85], v[128:129], v[90:91]
	v_pk_fma_f32 v[90:91], v[82:83], v[134:135], v[98:99]
	v_pk_fma_f32 v[86:87], v[86:87], v[130:131], v[92:93]
	v_pk_fma_f32 v[80:81], v[80:81], v[132:133], v[94:95]
	v_cvt_pk_bf16_f32 v82, v84, v85
	v_cvt_pk_bf16_f32 v83, v86, v87
	s_nop 0
	v_cvt_pk_bf16_f32 v84, v80, v81
	v_cvt_pk_bf16_f32 v85, v90, v91
	global_load_dwordx4 v[90:93], v[88:89], off
	v_add_co_u32_e32 v80, vcc, s49, v150
	global_store_dwordx4 v[96:97], v[82:85], off
	s_nop 0
	v_addc_co_u32_e32 v81, vcc, 0, v151, vcc
	s_waitcnt vmcnt(1)
	v_lshlrev_b32_e32 v82, 16, v90
	v_and_b32_e32 v83, 0xffff0000, v90
	v_lshlrev_b32_e32 v84, 16, v91
	v_and_b32_e32 v85, 0xffff0000, v91
	v_lshlrev_b32_e32 v86, 16, v92
	v_and_b32_e32 v87, 0xffff0000, v92
	v_lshlrev_b32_e32 v90, 16, v93
	v_and_b32_e32 v91, 0xffff0000, v93
	v_pk_fma_f32 v[78:79], v[78:79], v[130:131], v[84:85]
	v_pk_fma_f32 v[76:77], v[76:77], v[128:129], v[82:83]
	v_pk_fma_f32 v[82:83], v[74:75], v[134:135], v[90:91]
	v_pk_fma_f32 v[74:75], v[72:73], v[132:133], v[86:87]
	v_cvt_pk_bf16_f32 v72, v76, v77
	v_cvt_pk_bf16_f32 v73, v78, v79
	s_nop 0
	v_cvt_pk_bf16_f32 v74, v74, v75
	v_cvt_pk_bf16_f32 v75, v82, v83
	global_load_dwordx4 v[76:79], v[80:81], off
	v_add_u32_e32 v82, 0x200, v161
	global_store_dwordx4 v[88:89], v[72:75], off
	v_add_u32_e32 v83, 0x210, v161
	s_waitcnt vmcnt(1)
	v_lshlrev_b32_e32 v72, 16, v76
	v_and_b32_e32 v73, 0xffff0000, v76
	v_lshlrev_b32_e32 v74, 16, v77
	v_and_b32_e32 v75, 0xffff0000, v77
	v_lshlrev_b32_e32 v76, 16, v78
	v_and_b32_e32 v77, 0xffff0000, v78
	v_lshlrev_b32_e32 v78, 16, v79
	v_and_b32_e32 v79, 0xffff0000, v79
	v_pk_fma_f32 v[60:61], v[60:61], v[128:129], v[72:73]
	v_pk_fma_f32 v[72:73], v[58:59], v[134:135], v[78:79]
	v_pk_fma_f32 v[58:59], v[56:57], v[132:133], v[76:77]
	v_pk_fma_f32 v[62:63], v[62:63], v[130:131], v[74:75]
	v_cvt_pk_bf16_f32 v56, v60, v61
	s_nop 0
	v_cvt_pk_bf16_f32 v57, v62, v63
	v_cvt_pk_bf16_f32 v58, v58, v59
	v_cvt_pk_bf16_f32 v59, v72, v73
	global_store_dwordx4 v[80:81], v[56:59], off
	ds_read_b128 v[60:63], v82
	s_waitcnt lgkmcnt(0)
	s_nop 1
	ds_read_b128 v[56:59], v83
	s_waitcnt lgkmcnt(0)
	global_load_dwordx4 v[72:75], v[150:151], off offset:256
	s_waitcnt vmcnt(0)
	v_lshlrev_b32_e32 v76, 16, v72
	v_and_b32_e32 v77, 0xffff0000, v72
	v_lshlrev_b32_e32 v72, 16, v73
	v_and_b32_e32 v73, 0xffff0000, v73
	v_lshlrev_b32_e32 v78, 16, v74
	v_and_b32_e32 v79, 0xffff0000, v74
	v_lshlrev_b32_e32 v74, 16, v75
	v_and_b32_e32 v75, 0xffff0000, v75
	v_pk_fma_f32 v[70:71], v[70:71], v[62:63], v[72:73]
	v_pk_fma_f32 v[68:69], v[68:69], v[60:61], v[76:77]
	v_pk_fma_f32 v[72:73], v[66:67], v[58:59], v[74:75]
	v_pk_fma_f32 v[66:67], v[64:65], v[56:57], v[78:79]
	v_cvt_pk_bf16_f32 v64, v68, v69
	v_cvt_pk_bf16_f32 v65, v70, v71
	s_nop 0
	v_cvt_pk_bf16_f32 v66, v66, v67
	v_cvt_pk_bf16_f32 v67, v72, v73
	global_load_dwordx4 v[68:71], v[152:153], off offset:256
	s_nop 0
	global_store_dwordx4 v[150:151], v[64:67], off offset:256
	s_waitcnt vmcnt(1)
; __device__ __forceinline__ unsigned cvt_pk_bf16(float lo, float hi) { unsigned r; asm volatile("v_cvt_pk_bf16_f32 %0, %1, %2" : "=v"(r) : "v"(lo), "v"(hi)); return r; }
; __device__ __forceinline__ f32x4 lds_ld4(const PG8_LAS float* p) { f32x4 v; asm volatile("ds_read_b128 %0, %1\n\ts_waitcnt lgkmcnt(0)" : "=v"(v) : "v"((unsigned)(size_t)p) : "memory"); return v; }
; #define PG8_BAR __builtin_amdgcn_s_barrier()
;     __device__ __forceinline__ void operator()(const f32x4 (&acc)[2][2][4][2], const Unit& u, int wr, int wc, int fr, int fq) const {
;     ...
;             const f32x4 g0 = lds_ld4(gvt + ct0 + bj * HALF), g1 = lds_ld4(gvt + ct0 + bj * HALF + 4);
; #pragma unroll
;             for (int ai = 0; ai < 2; ++ai)
; #pragma unroll
;                 for (int m = 0; m < 4; ++m) { const size_t off = off0 + (size_t)(ai * HALF + m * 16) * 4096 + bj * HALF;
;                     const u32x4 b = *(const u32x4*)(xb + off);
;                     const f32x4 v0 = (f32x4){__uint_as_float(b.x << 16), __uint_as_float(b.x & 0xffff0000u), __uint_as_float(b.y << 16), __uint_as_float(b.y & 0xffff0000u)} + g0 * acc[ai][bj][m][0];
;                     const f32x4 v1 = (f32x4){__uint_as_float(b.z << 16), __uint_as_float(b.z & 0xffff0000u), __uint_as_float(b.w << 16), __uint_as_float(b.w & 0xffff0000u)} + g1 * acc[ai][bj][m][1];
;                     u32x4 w; w.x = cvt_pk_bf16(v0.x, v0.y); w.y = cvt_pk_bf16(v0.z, v0.w); w.z = cvt_pk_bf16(v1.x, v1.y); w.w = cvt_pk_bf16(v1.z, v1.w);
;                     *(u32x4*)(xb + off) = w; }
; template <class Epi, class Sched, bool ALIGN_EPI = false, bool SP2 = false>
; __device__ __forceinline__ void gemm_phase(PG8_LAS unsigned char* lds, const Gemm g, const Sched& S, const Epi& E) {
;     ...
;         if (!has_next) break;
; #pragma unroll
;         for (int a = 0; a < 2; ++a)
; #pragma unroll
;             for (int b = 0; b < 2; ++b)
; #pragma unroll
;                 for (int m = 0; m < 4; ++m)
; #pragma unroll
;                     for (int n = 0; n < 2; ++n) acc[a][b][m][n] = (f32x4){0.f, 0.f, 0.f, 0.f};
;         cur = nxt; cA = nA; cB = nB; ++ui;
;         if constexpr (ALIGN_EPI) { if (wr == 1) PG8_BAR; }
	s_nop 0
	v_lshlrev_b32_e32 v64, 16, v68
	v_and_b32_e32 v65, 0xffff0000, v68
	v_lshlrev_b32_e32 v66, 16, v69
	v_and_b32_e32 v67, 0xffff0000, v69
	v_lshlrev_b32_e32 v68, 16, v70
	v_and_b32_e32 v69, 0xffff0000, v70
	v_lshlrev_b32_e32 v70, 16, v71
	v_and_b32_e32 v71, 0xffff0000, v71
	v_pk_fma_f32 v[54:55], v[54:55], v[62:63], v[66:67]
	v_pk_fma_f32 v[52:53], v[52:53], v[60:61], v[64:65]
	v_pk_fma_f32 v[64:65], v[50:51], v[58:59], v[70:71]
	v_pk_fma_f32 v[50:51], v[48:49], v[56:57], v[68:69]
	v_cvt_pk_bf16_f32 v48, v52, v53
	v_cvt_pk_bf16_f32 v49, v54, v55
	s_nop 0
	v_cvt_pk_bf16_f32 v50, v50, v51
	v_cvt_pk_bf16_f32 v51, v64, v65
	global_load_dwordx4 v[52:55], v[120:121], off offset:256
	s_nop 0
	global_store_dwordx4 v[152:153], v[48:51], off offset:256
	s_waitcnt vmcnt(1)
	s_nop 0
	v_lshlrev_b32_e32 v48, 16, v52
	v_and_b32_e32 v49, 0xffff0000, v52
	v_lshlrev_b32_e32 v50, 16, v53
	v_and_b32_e32 v51, 0xffff0000, v53
	v_lshlrev_b32_e32 v52, 16, v54
	v_and_b32_e32 v53, 0xffff0000, v54
	v_lshlrev_b32_e32 v54, 16, v55
	v_and_b32_e32 v55, 0xffff0000, v55
	v_pk_fma_f32 v[46:47], v[46:47], v[62:63], v[50:51]
	v_pk_fma_f32 v[44:45], v[44:45], v[60:61], v[48:49]
	v_pk_fma_f32 v[48:49], v[42:43], v[58:59], v[54:55]
	v_pk_fma_f32 v[42:43], v[40:41], v[56:57], v[52:53]
	v_cvt_pk_bf16_f32 v40, v44, v45
	v_cvt_pk_bf16_f32 v41, v46, v47
	s_nop 0
	v_cvt_pk_bf16_f32 v42, v42, v43
	v_cvt_pk_bf16_f32 v43, v48, v49
	global_load_dwordx4 v[44:47], v[112:113], off offset:256
	s_nop 0
	global_store_dwordx4 v[120:121], v[40:43], off offset:256
	s_waitcnt vmcnt(1)
	s_nop 0
	v_lshlrev_b32_e32 v40, 16, v44
	v_and_b32_e32 v41, 0xffff0000, v44
	v_lshlrev_b32_e32 v42, 16, v45
	v_and_b32_e32 v43, 0xffff0000, v45
	v_lshlrev_b32_e32 v44, 16, v46
	v_and_b32_e32 v45, 0xffff0000, v46
	v_lshlrev_b32_e32 v46, 16, v47
	v_and_b32_e32 v47, 0xffff0000, v47
	v_pk_fma_f32 v[38:39], v[38:39], v[62:63], v[42:43]
	v_pk_fma_f32 v[36:37], v[36:37], v[60:61], v[40:41]
	v_pk_fma_f32 v[40:41], v[34:35], v[58:59], v[46:47]
	v_pk_fma_f32 v[34:35], v[32:33], v[56:57], v[44:45]
	v_cvt_pk_bf16_f32 v32, v36, v37
	v_cvt_pk_bf16_f32 v33, v38, v39
	s_nop 0
	v_cvt_pk_bf16_f32 v34, v34, v35
	v_cvt_pk_bf16_f32 v35, v40, v41
	global_load_dwordx4 v[36:39], v[104:105], off offset:256
	s_nop 0
	global_store_dwordx4 v[112:113], v[32:35], off offset:256
	s_waitcnt vmcnt(1)
	s_nop 0
	v_lshlrev_b32_e32 v32, 16, v36
	v_and_b32_e32 v33, 0xffff0000, v36
	v_lshlrev_b32_e32 v34, 16, v37
	v_and_b32_e32 v35, 0xffff0000, v37
	v_lshlrev_b32_e32 v36, 16, v38
	v_and_b32_e32 v37, 0xffff0000, v38
	v_lshlrev_b32_e32 v38, 16, v39
	v_and_b32_e32 v39, 0xffff0000, v39
	v_pk_fma_f32 v[30:31], v[30:31], v[62:63], v[34:35]
	v_pk_fma_f32 v[28:29], v[28:29], v[60:61], v[32:33]
	v_pk_fma_f32 v[32:33], v[26:27], v[58:59], v[38:39]
	v_pk_fma_f32 v[26:27], v[24:25], v[56:57], v[36:37]
	v_cvt_pk_bf16_f32 v24, v28, v29
	v_cvt_pk_bf16_f32 v25, v30, v31
	s_nop 0
	v_cvt_pk_bf16_f32 v26, v26, v27
	v_cvt_pk_bf16_f32 v27, v32, v33
	global_load_dwordx4 v[28:31], v[96:97], off offset:256
	s_nop 0
	global_store_dwordx4 v[104:105], v[24:27], off offset:256
	s_waitcnt vmcnt(1)
	s_nop 0
	v_lshlrev_b32_e32 v24, 16, v28
	v_and_b32_e32 v25, 0xffff0000, v28
	v_lshlrev_b32_e32 v26, 16, v29
	v_and_b32_e32 v27, 0xffff0000, v29
	v_lshlrev_b32_e32 v28, 16, v30
	v_and_b32_e32 v29, 0xffff0000, v30
	v_lshlrev_b32_e32 v30, 16, v31
	v_and_b32_e32 v31, 0xffff0000, v31
	v_pk_fma_f32 v[22:23], v[22:23], v[62:63], v[26:27]
	v_pk_fma_f32 v[20:21], v[20:21], v[60:61], v[24:25]
	v_pk_fma_f32 v[24:25], v[18:19], v[58:59], v[30:31]
	v_pk_fma_f32 v[18:19], v[16:17], v[56:57], v[28:29]
	v_cvt_pk_bf16_f32 v16, v20, v21
	v_cvt_pk_bf16_f32 v17, v22, v23
	s_nop 0
	v_cvt_pk_bf16_f32 v18, v18, v19
	v_cvt_pk_bf16_f32 v19, v24, v25
	global_load_dwordx4 v[20:23], v[88:89], off offset:256
	s_nop 0
	global_store_dwordx4 v[96:97], v[16:19], off offset:256
	s_waitcnt vmcnt(1)
	s_nop 0
	v_lshlrev_b32_e32 v16, 16, v20
	v_and_b32_e32 v17, 0xffff0000, v20
	v_lshlrev_b32_e32 v18, 16, v21
	v_and_b32_e32 v19, 0xffff0000, v21
	v_lshlrev_b32_e32 v20, 16, v22
	v_and_b32_e32 v21, 0xffff0000, v22
	v_lshlrev_b32_e32 v22, 16, v23
	v_and_b32_e32 v23, 0xffff0000, v23
	v_pk_fma_f32 v[14:15], v[14:15], v[62:63], v[18:19]
	v_pk_fma_f32 v[12:13], v[12:13], v[60:61], v[16:17]
	v_pk_fma_f32 v[16:17], v[10:11], v[58:59], v[22:23]
	v_pk_fma_f32 v[10:11], v[8:9], v[56:57], v[20:21]
	v_cvt_pk_bf16_f32 v8, v12, v13
	v_cvt_pk_bf16_f32 v9, v14, v15
	s_nop 0
	v_cvt_pk_bf16_f32 v10, v10, v11
	v_cvt_pk_bf16_f32 v11, v16, v17
	global_load_dwordx4 v[12:15], v[80:81], off offset:256
	s_nop 0
	global_store_dwordx4 v[88:89], v[8:11], off offset:256
	s_waitcnt vmcnt(1)
	s_nop 0
	v_lshlrev_b32_e32 v8, 16, v12
	v_and_b32_e32 v9, 0xffff0000, v12
	v_lshlrev_b32_e32 v10, 16, v13
	v_and_b32_e32 v11, 0xffff0000, v13
	v_lshlrev_b32_e32 v12, 16, v14
	v_and_b32_e32 v13, 0xffff0000, v14
	v_lshlrev_b32_e32 v14, 16, v15
	v_and_b32_e32 v15, 0xffff0000, v15
	v_pk_fma_f32 v[4:5], v[4:5], v[60:61], v[8:9]
	v_pk_fma_f32 v[8:9], v[2:3], v[58:59], v[14:15]
	v_pk_fma_f32 v[2:3], v[0:1], v[56:57], v[12:13]
	v_pk_fma_f32 v[6:7], v[6:7], v[62:63], v[10:11]
	v_cvt_pk_bf16_f32 v0, v4, v5
	s_nop 0
	v_cvt_pk_bf16_f32 v1, v6, v7
	v_cvt_pk_bf16_f32 v2, v2, v3
	v_cvt_pk_bf16_f32 v3, v8, v9
	global_store_dwordx4 v[80:81], v[0:3], off offset:256
	s_cbranch_scc1 .LBB0_1319
	s_andn2_b64 vcc, exec, s[10:11]
	s_cbranch_vccnz .LBB0_1318
	s_branch .LBB0_1318
